# GEMM K-loops: dropped the mid-block s_setprio 0/1 pair and the redundant post-barrier lgkmcnt(0) in all 16 K-loops
# baseline (speedup 1.0000x reference)
; #define PG8_STAGE(bufoff, gbase, voff) do { _Pragma("unroll") for (int _i = 0; _i < 2; ++_i) \
;         __builtin_amdgcn_global_load_lds((const unsigned*)((const char*)(gbase) + (voff)[_i]), (PG8_LAS unsigned*)(lds + (bufoff) + ldsw + _i * 8192), 16, 0, 0); } while (0)
; #define PG8_LDA(dst, b, h) do { _Pragma("unroll") for (int m = 0; m < 4; ++m) _Pragma("unroll") for (int k = 0; k < 2; ++k) dst[m][k] = *(const PG8_LAS bf16x8*)(lds + PG8_SA(b, h) + aoff + m * 2048 + k * 1024); } while (0)
; #define PG8_LDB(dst, b, h) do { _Pragma("unroll") for (int n = 0; n < 2; ++n) _Pragma("unroll") for (int k = 0; k < 2; ++k) dst[n][k] = *(const PG8_LAS bf16x8*)(lds + PG8_SB(b, h) + boff + n * 2048 + k * 1024); } while (0)
; #define PG8_MMA(ai, bj, At, Bt) do { __builtin_amdgcn_s_setprio(1); _Pragma("unroll") for (int m = 0; m < 4; ++m) _Pragma("unroll") for (int n = 0; n < 2; ++n) _Pragma("unroll") for (int k = 0; k < 2; ++k) \
;         acc[ai][bj][m][n] = __builtin_amdgcn_mfma_f32_16x16x32_bf16(Bt[n][k], At[m][k], acc[ai][bj][m][n], 0, 0, 0); __builtin_amdgcn_s_setprio(0); } while (0)
; #define PG8_WAIT_V(n) asm volatile("s_waitcnt vmcnt(" #n ")" ::: "memory")
; #define PG8_WAIT_L(n) asm volatile("s_waitcnt lgkmcnt(" #n ")" ::: "memory")
; #define PG8_BAR __builtin_amdgcn_s_barrier()
; #define PG8_SCHED __builtin_amdgcn_sched_barrier(0)
; template <class Epi, class Sched, bool ALIGN_EPI = false, bool SP2 = false>
; __device__ __forceinline__ void gemm_phase(PG8_LAS unsigned char* lds, const Gemm g, const Sched& S, const Epi& E) {
;     ...
;             if constexpr (SP2) {
;             PG8_LDB(B0, 0, 0); PG8_LDB(B1, 0, 1); PG8_SCHED; PG8_LDA(At, 0, 0); PG8_STAGE(PG8_SA(1, 1), a1 + hstepA, voffA);
;             PG8_WAIT_V(8); PG8_WAIT_L(0); PG8_BAR; PG8_MMA(0, 0, At, B0); PG8_MMA(0, 1, At, B1); PG8_BAR; PG8_SCHED;
;             PG8_LDA(At, 0, 1); PG8_STAGE(PG8_SB(0, 0), b2, voffB); PG8_STAGE(PG8_SB(0, 1), b2 + hstepB, voffB); PG8_STAGE(PG8_SA(0, 0), a2, voffA);
;             PG8_WAIT_V(8); PG8_WAIT_L(0); PG8_BAR; PG8_MMA(1, 0, At, B0); PG8_MMA(1, 1, At, B1); PG8_BAR; PG8_SCHED;
.LBB0_259:
	ds_read_b128 v[152:155], v149
	ds_read_b128 v[156:159], v149 offset:1024
	ds_read_b128 v[160:163], v149 offset:2048
	ds_read_b128 v[164:167], v149 offset:3072
	ds_read_b128 v[168:171], v150
	ds_read_b128 v[172:175], v150 offset:1024
	ds_read_b128 v[176:179], v150 offset:2048
	ds_read_b128 v[180:183], v150 offset:3072
	s_add_i32 s62, s28, 2
	s_add_u32 s29, s26, 0xfffc0080
	s_addc_u32 s30, s27, -1
	s_cmp_eq_u32 s52, s28
	s_cselect_b32 s28, s59, s60
	s_cselect_b32 s31, s17, s30
	s_cselect_b32 s30, s19, s29
	s_cselect_b32 s29, s58, s61
	v_lshl_add_u64 v[144:145], s[26:27], 0, v[136:137]
	s_add_i32 m0, s43, 0xc000
	ds_read_b128 v[184:187], v151
	ds_read_b128 v[188:191], v151 offset:1024
	ds_read_b128 v[192:195], v151 offset:2048
	ds_read_b128 v[196:199], v151 offset:3072
	ds_read_b128 v[200:203], v151 offset:4096
	ds_read_b128 v[204:207], v151 offset:5120
	ds_read_b128 v[208:211], v151 offset:6144
	ds_read_b128 v[212:215], v151 offset:7168
	global_load_lds_dwordx4 v[144:145], off
	v_lshl_add_u64 v[144:145], s[26:27], 0, v[138:139]
	s_add_i32 m0, s43, 0xe000
	s_nop 0
	global_load_lds_dwordx4 v[144:145], off
	s_waitcnt vmcnt(8)
	s_waitcnt lgkmcnt(0)
	s_barrier
	s_setprio 1
	v_mfma_f32_16x16x32_bf16 v[124:127], v[152:155], v[184:187], v[124:127]
	v_mfma_f32_16x16x32_bf16 v[116:119], v[160:163], v[184:187], v[116:119]
	v_mfma_f32_16x16x32_bf16 v[108:111], v[152:155], v[192:195], v[108:111]
	v_mfma_f32_16x16x32_bf16 v[100:103], v[160:163], v[192:195], v[100:103]
	v_mfma_f32_16x16x32_bf16 v[92:95], v[152:155], v[200:203], v[92:95]
	v_mfma_f32_16x16x32_bf16 v[84:87], v[160:163], v[200:203], v[84:87]
	v_mfma_f32_16x16x32_bf16 v[76:79], v[152:155], v[208:211], v[76:79]
	v_mfma_f32_16x16x32_bf16 v[68:71], v[160:163], v[208:211], v[68:71]
	v_mfma_f32_16x16x32_bf16 v[124:127], v[156:159], v[188:191], v[124:127]
	v_mfma_f32_16x16x32_bf16 v[116:119], v[164:167], v[188:191], v[116:119]
	v_mfma_f32_16x16x32_bf16 v[108:111], v[156:159], v[196:199], v[108:111]
	v_mfma_f32_16x16x32_bf16 v[100:103], v[164:167], v[196:199], v[100:103]
	v_mfma_f32_16x16x32_bf16 v[92:95], v[156:159], v[204:207], v[92:95]
	v_mfma_f32_16x16x32_bf16 v[84:87], v[164:167], v[204:207], v[84:87]
	v_mfma_f32_16x16x32_bf16 v[76:79], v[156:159], v[212:215], v[76:79]
	v_mfma_f32_16x16x32_bf16 v[68:71], v[164:167], v[212:215], v[68:71]
	v_mfma_f32_16x16x32_bf16 v[120:123], v[168:171], v[184:187], v[120:123]
	v_mfma_f32_16x16x32_bf16 v[112:115], v[176:179], v[184:187], v[112:115]
	v_mfma_f32_16x16x32_bf16 v[104:107], v[168:171], v[192:195], v[104:107]
	v_mfma_f32_16x16x32_bf16 v[96:99], v[176:179], v[192:195], v[96:99]
	v_mfma_f32_16x16x32_bf16 v[88:91], v[168:171], v[200:203], v[88:91]
	v_mfma_f32_16x16x32_bf16 v[80:83], v[176:179], v[200:203], v[80:83]
	v_mfma_f32_16x16x32_bf16 v[72:75], v[168:171], v[208:211], v[72:75]
	v_mfma_f32_16x16x32_bf16 v[64:67], v[176:179], v[208:211], v[64:67]
	v_mfma_f32_16x16x32_bf16 v[120:123], v[172:175], v[188:191], v[120:123]
	v_mfma_f32_16x16x32_bf16 v[112:115], v[180:183], v[188:191], v[112:115]
	v_mfma_f32_16x16x32_bf16 v[104:107], v[172:175], v[196:199], v[104:107]
	v_mfma_f32_16x16x32_bf16 v[96:99], v[180:183], v[196:199], v[96:99]
	v_mfma_f32_16x16x32_bf16 v[88:91], v[172:175], v[204:207], v[88:91]
	v_mfma_f32_16x16x32_bf16 v[80:83], v[180:183], v[204:207], v[80:83]
	v_mfma_f32_16x16x32_bf16 v[72:75], v[172:175], v[212:215], v[72:75]
	v_mfma_f32_16x16x32_bf16 v[64:67], v[180:183], v[212:215], v[64:67]
	s_setprio 0
	s_barrier
	s_add_i32 s63, s56, s38
	v_lshl_add_u64 v[144:145], s[28:29], 0, v[132:133]
	s_mov_b32 m0, s63
	ds_read_b128 v[184:187], v151 offset:16384
	ds_read_b128 v[188:191], v151 offset:17408
	ds_read_b128 v[192:195], v151 offset:18432
	ds_read_b128 v[196:199], v151 offset:19456
	ds_read_b128 v[200:203], v151 offset:20480
	ds_read_b128 v[204:207], v151 offset:21504
	ds_read_b128 v[208:211], v151 offset:22528
	ds_read_b128 v[212:215], v151 offset:23552
	global_load_lds_dwordx4 v[144:145], off
	s_add_i32 m0, s63, 0x2000
	s_add_u32 s64, s28, 0x40000
	v_lshl_add_u64 v[216:217], s[28:29], 0, v[128:129]
	s_addc_u32 s65, s29, 0
	s_add_i32 s63, s57, s38
	global_load_lds_dwordx4 v[216:217], off
	v_lshl_add_u64 v[218:219], s[64:65], 0, v[132:133]
	s_mov_b32 m0, s63
	v_lshl_add_u64 v[220:221], s[30:31], 0, v[130:131]
	global_load_lds_dwordx4 v[218:219], off
	v_lshl_add_u64 v[218:219], s[64:65], 0, v[128:129]
	s_add_i32 m0, s63, 0x2000
	s_nop 0
	global_load_lds_dwordx4 v[218:219], off
	v_lshl_add_u64 v[218:219], s[30:31], 0, v[134:135]
	s_mov_b32 m0, s43
	s_nop 0
	global_load_lds_dwordx4 v[218:219], off
	s_mov_b32 m0, s44
	s_nop 0
	global_load_lds_dwordx4 v[220:221], off
	s_waitcnt vmcnt(8)
	s_waitcnt lgkmcnt(0)
	s_barrier
; #define PG8_STAGE(bufoff, gbase, voff) do { _Pragma("unroll") for (int _i = 0; _i < 2; ++_i) \
;         __builtin_amdgcn_global_load_lds((const unsigned*)((const char*)(gbase) + (voff)[_i]), (PG8_LAS unsigned*)(lds + (bufoff) + ldsw + _i * 8192), 16, 0, 0); } while (0)
; #define PG8_LDA(dst, b, h) do { _Pragma("unroll") for (int m = 0; m < 4; ++m) _Pragma("unroll") for (int k = 0; k < 2; ++k) dst[m][k] = *(const PG8_LAS bf16x8*)(lds + PG8_SA(b, h) + aoff + m * 2048 + k * 1024); } while (0)
; #define PG8_LDB(dst, b, h) do { _Pragma("unroll") for (int n = 0; n < 2; ++n) _Pragma("unroll") for (int k = 0; k < 2; ++k) dst[n][k] = *(const PG8_LAS bf16x8*)(lds + PG8_SB(b, h) + boff + n * 2048 + k * 1024); } while (0)
; #define PG8_MMA(ai, bj, At, Bt) do { __builtin_amdgcn_s_setprio(1); _Pragma("unroll") for (int m = 0; m < 4; ++m) _Pragma("unroll") for (int n = 0; n < 2; ++n) _Pragma("unroll") for (int k = 0; k < 2; ++k) \
;         acc[ai][bj][m][n] = __builtin_amdgcn_mfma_f32_16x16x32_bf16(Bt[n][k], At[m][k], acc[ai][bj][m][n], 0, 0, 0); __builtin_amdgcn_s_setprio(0); } while (0)
; #define PG8_WAIT_V(n) asm volatile("s_waitcnt vmcnt(" #n ")" ::: "memory")
; #define PG8_WAIT_L(n) asm volatile("s_waitcnt lgkmcnt(" #n ")" ::: "memory")
; #define PG8_BAR __builtin_amdgcn_s_barrier()
; #define PG8_SCHED __builtin_amdgcn_sched_barrier(0)
; template <class Epi, class Sched, bool ALIGN_EPI = false, bool SP2 = false>
; __device__ __forceinline__ void gemm_phase(PG8_LAS unsigned char* lds, const Gemm g, const Sched& S, const Epi& E) {
;     ...
;             PG8_WAIT_V(8); PG8_WAIT_L(0); PG8_BAR; PG8_MMA(1, 0, At, B0); PG8_MMA(1, 1, At, B1); PG8_BAR; PG8_SCHED;
;             PG8_LDB(B0, 1, 0); PG8_LDB(B1, 1, 1); PG8_SCHED; PG8_LDA(At, 1, 0); PG8_STAGE(PG8_SA(0, 1), a2 + hstepA, voffA);
;             PG8_WAIT_V(8); PG8_WAIT_L(0); PG8_BAR; PG8_MMA(0, 0, At, B0); PG8_MMA(0, 1, At, B1); PG8_BAR; PG8_SCHED;
	s_setprio 1
	v_mfma_f32_16x16x32_bf16 v[60:63], v[152:155], v[184:187], v[60:63]
	v_mfma_f32_16x16x32_bf16 v[52:55], v[160:163], v[184:187], v[52:55]
	v_mfma_f32_16x16x32_bf16 v[44:47], v[152:155], v[192:195], v[44:47]
	v_mfma_f32_16x16x32_bf16 v[36:39], v[160:163], v[192:195], v[36:39]
	v_mfma_f32_16x16x32_bf16 v[28:31], v[152:155], v[200:203], v[28:31]
	v_mfma_f32_16x16x32_bf16 v[20:23], v[160:163], v[200:203], v[20:23]
	v_mfma_f32_16x16x32_bf16 v[12:15], v[152:155], v[208:211], v[12:15]
	v_mfma_f32_16x16x32_bf16 v[4:7], v[160:163], v[208:211], v[4:7]
	v_mfma_f32_16x16x32_bf16 v[60:63], v[156:159], v[188:191], v[60:63]
	v_mfma_f32_16x16x32_bf16 v[52:55], v[164:167], v[188:191], v[52:55]
	v_mfma_f32_16x16x32_bf16 v[44:47], v[156:159], v[196:199], v[44:47]
	v_mfma_f32_16x16x32_bf16 v[36:39], v[164:167], v[196:199], v[36:39]
	v_mfma_f32_16x16x32_bf16 v[28:31], v[156:159], v[204:207], v[28:31]
	v_mfma_f32_16x16x32_bf16 v[20:23], v[164:167], v[204:207], v[20:23]
	v_mfma_f32_16x16x32_bf16 v[12:15], v[156:159], v[212:215], v[12:15]
	v_mfma_f32_16x16x32_bf16 v[4:7], v[164:167], v[212:215], v[4:7]
	v_mfma_f32_16x16x32_bf16 v[56:59], v[168:171], v[184:187], v[56:59]
	v_mfma_f32_16x16x32_bf16 v[48:51], v[176:179], v[184:187], v[48:51]
	v_mfma_f32_16x16x32_bf16 v[40:43], v[168:171], v[192:195], v[40:43]
	v_mfma_f32_16x16x32_bf16 v[32:35], v[176:179], v[192:195], v[32:35]
	v_mfma_f32_16x16x32_bf16 v[24:27], v[168:171], v[200:203], v[24:27]
	v_mfma_f32_16x16x32_bf16 v[16:19], v[176:179], v[200:203], v[16:19]
	v_mfma_f32_16x16x32_bf16 v[8:11], v[168:171], v[208:211], v[8:11]
	v_mfma_f32_16x16x32_bf16 v[0:3], v[176:179], v[208:211], v[0:3]
	v_mfma_f32_16x16x32_bf16 v[56:59], v[172:175], v[188:191], v[56:59]
	v_mfma_f32_16x16x32_bf16 v[48:51], v[180:183], v[188:191], v[48:51]
	v_mfma_f32_16x16x32_bf16 v[40:43], v[172:175], v[196:199], v[40:43]
	v_mfma_f32_16x16x32_bf16 v[32:35], v[180:183], v[196:199], v[32:35]
	v_mfma_f32_16x16x32_bf16 v[24:27], v[172:175], v[204:207], v[24:27]
	v_mfma_f32_16x16x32_bf16 v[16:19], v[180:183], v[204:207], v[16:19]
	v_mfma_f32_16x16x32_bf16 v[8:11], v[172:175], v[212:215], v[8:11]
	v_mfma_f32_16x16x32_bf16 v[0:3], v[180:183], v[212:215], v[0:3]
	s_setprio 0
	s_barrier
	s_add_i32 s63, 0, 0x18000
	s_add_i32 s64, 0, 0x1c000
	v_add_u32_e32 v164, s63, v148
	v_add_u32_e32 v180, s64, v148
	ds_read_b128 v[152:155], v164
	ds_read_b128 v[156:159], v164 offset:1024
	ds_read_b128 v[160:163], v164 offset:2048
	ds_read_b128 v[164:167], v164 offset:3072
	ds_read_b128 v[168:171], v180
	ds_read_b128 v[172:175], v180 offset:1024
	ds_read_b128 v[176:179], v180 offset:2048
	ds_read_b128 v[180:183], v180 offset:3072
	s_add_u32 s30, s30, 0x40000
	s_addc_u32 s31, s31, 0
	s_mov_b32 m0, s45
	v_lshl_add_u64 v[222:223], s[30:31], 0, v[134:135]
	ds_read_b128 v[184:187], v151 offset:32768
	ds_read_b128 v[188:191], v151 offset:33792
	ds_read_b128 v[192:195], v151 offset:34816
	ds_read_b128 v[196:199], v151 offset:35840
	ds_read_b128 v[200:203], v151 offset:36864
	ds_read_b128 v[204:207], v151 offset:37888
	ds_read_b128 v[208:211], v151 offset:38912
	ds_read_b128 v[212:215], v151 offset:39936
	global_load_lds_dwordx4 v[222:223], off
	v_lshl_add_u64 v[222:223], s[30:31], 0, v[130:131]
	s_mov_b32 m0, s46
	s_nop 0
	global_load_lds_dwordx4 v[222:223], off
	s_waitcnt vmcnt(8)
	s_waitcnt lgkmcnt(0)
	s_barrier
	s_setprio 1
	v_mfma_f32_16x16x32_bf16 v[124:127], v[152:155], v[184:187], v[124:127]
	v_mfma_f32_16x16x32_bf16 v[116:119], v[160:163], v[184:187], v[116:119]
	v_mfma_f32_16x16x32_bf16 v[108:111], v[152:155], v[192:195], v[108:111]
	v_mfma_f32_16x16x32_bf16 v[100:103], v[160:163], v[192:195], v[100:103]
	v_mfma_f32_16x16x32_bf16 v[92:95], v[152:155], v[200:203], v[92:95]
	v_mfma_f32_16x16x32_bf16 v[84:87], v[160:163], v[200:203], v[84:87]
	v_mfma_f32_16x16x32_bf16 v[76:79], v[152:155], v[208:211], v[76:79]
	v_mfma_f32_16x16x32_bf16 v[68:71], v[160:163], v[208:211], v[68:71]
	v_mfma_f32_16x16x32_bf16 v[124:127], v[156:159], v[188:191], v[124:127]
	v_mfma_f32_16x16x32_bf16 v[116:119], v[164:167], v[188:191], v[116:119]
	v_mfma_f32_16x16x32_bf16 v[108:111], v[156:159], v[196:199], v[108:111]
	v_mfma_f32_16x16x32_bf16 v[100:103], v[164:167], v[196:199], v[100:103]
	v_mfma_f32_16x16x32_bf16 v[92:95], v[156:159], v[204:207], v[92:95]
	v_mfma_f32_16x16x32_bf16 v[84:87], v[164:167], v[204:207], v[84:87]
	v_mfma_f32_16x16x32_bf16 v[76:79], v[156:159], v[212:215], v[76:79]
	v_mfma_f32_16x16x32_bf16 v[68:71], v[164:167], v[212:215], v[68:71]
	v_mfma_f32_16x16x32_bf16 v[120:123], v[168:171], v[184:187], v[120:123]
	v_mfma_f32_16x16x32_bf16 v[112:115], v[176:179], v[184:187], v[112:115]
	v_mfma_f32_16x16x32_bf16 v[104:107], v[168:171], v[192:195], v[104:107]
	v_mfma_f32_16x16x32_bf16 v[96:99], v[176:179], v[192:195], v[96:99]
	v_mfma_f32_16x16x32_bf16 v[88:91], v[168:171], v[200:203], v[88:91]
	v_mfma_f32_16x16x32_bf16 v[80:83], v[176:179], v[200:203], v[80:83]
	v_mfma_f32_16x16x32_bf16 v[72:75], v[168:171], v[208:211], v[72:75]
	v_mfma_f32_16x16x32_bf16 v[64:67], v[176:179], v[208:211], v[64:67]
	v_mfma_f32_16x16x32_bf16 v[120:123], v[172:175], v[188:191], v[120:123]
	v_mfma_f32_16x16x32_bf16 v[112:115], v[180:183], v[188:191], v[112:115]
	v_mfma_f32_16x16x32_bf16 v[104:107], v[172:175], v[196:199], v[104:107]
	v_mfma_f32_16x16x32_bf16 v[96:99], v[180:183], v[196:199], v[96:99]
	v_mfma_f32_16x16x32_bf16 v[88:91], v[172:175], v[204:207], v[88:91]
	v_mfma_f32_16x16x32_bf16 v[80:83], v[180:183], v[204:207], v[80:83]
	v_mfma_f32_16x16x32_bf16 v[72:75], v[172:175], v[212:215], v[72:75]
	v_mfma_f32_16x16x32_bf16 v[64:67], v[180:183], v[212:215], v[64:67]
	s_setprio 0
	s_barrier
; #define PG8_STAGE(bufoff, gbase, voff) do { _Pragma("unroll") for (int _i = 0; _i < 2; ++_i) \
;         __builtin_amdgcn_global_load_lds((const unsigned*)((const char*)(gbase) + (voff)[_i]), (PG8_LAS unsigned*)(lds + (bufoff) + ldsw + _i * 8192), 16, 0, 0); } while (0)
; #define PG8_LDA(dst, b, h) do { _Pragma("unroll") for (int m = 0; m < 4; ++m) _Pragma("unroll") for (int k = 0; k < 2; ++k) dst[m][k] = *(const PG8_LAS bf16x8*)(lds + PG8_SA(b, h) + aoff + m * 2048 + k * 1024); } while (0)
; #define PG8_MMA(ai, bj, At, Bt) do { __builtin_amdgcn_s_setprio(1); _Pragma("unroll") for (int m = 0; m < 4; ++m) _Pragma("unroll") for (int n = 0; n < 2; ++n) _Pragma("unroll") for (int k = 0; k < 2; ++k) \
;         acc[ai][bj][m][n] = __builtin_amdgcn_mfma_f32_16x16x32_bf16(Bt[n][k], At[m][k], acc[ai][bj][m][n], 0, 0, 0); __builtin_amdgcn_s_setprio(0); } while (0)
; #define PG8_WAIT_V(n) asm volatile("s_waitcnt vmcnt(" #n ")" ::: "memory")
; #define PG8_WAIT_L(n) asm volatile("s_waitcnt lgkmcnt(" #n ")" ::: "memory")
; #define PG8_BAR __builtin_amdgcn_s_barrier()
; #define PG8_SCHED __builtin_amdgcn_sched_barrier(0)
; template <class Epi, class Sched, bool ALIGN_EPI = false, bool SP2 = false>
; __device__ __forceinline__ void gemm_phase(PG8_LAS unsigned char* lds, const Gemm g, const Sched& S, const Epi& E) {
;     ...
;         for (int t = 0; t < nt; t += 2) {
;             const bool last = (t == nt - 2);
;             const char* a1 = cA + (long)(t + 1) * kstepA;
;             const char* a2 = last ? nA : cA + (long)(t + 2) * kstepA; const char* b2 = last ? nB : cB + (long)(t + 2) * kstep;
;     ...
;             PG8_LDA(At, 1, 1); PG8_STAGE(PG8_SB(1, 0), b3, voffB); PG8_STAGE(PG8_SB(1, 1), b3 + hstepB, voffB); PG8_STAGE(PG8_SA(1, 0), a3, voffA);
;             PG8_WAIT_V(8); PG8_WAIT_L(0); PG8_BAR; PG8_MMA(1, 0, At, B0); PG8_MMA(1, 1, At, B1); PG8_BAR; PG8_SCHED;
	s_add_i32 s30, s63, s38
	v_lshl_add_u64 v[144:145], v[144:145], 0, s[12:13]
	s_mov_b32 m0, s30
	ds_read_b128 v[184:187], v151 offset:49152
	ds_read_b128 v[188:191], v151 offset:50176
	ds_read_b128 v[192:195], v151 offset:51200
	ds_read_b128 v[196:199], v151 offset:52224
	ds_read_b128 v[200:203], v151 offset:53248
	ds_read_b128 v[204:207], v151 offset:54272
	ds_read_b128 v[208:211], v151 offset:55296
	ds_read_b128 v[212:215], v151 offset:56320
	global_load_lds_dwordx4 v[144:145], off
	s_add_i32 m0, s30, 0x2000
	s_add_u32 s28, s28, 0x40080
	v_lshl_add_u64 v[144:145], v[216:217], 0, s[12:13]
	s_addc_u32 s29, s29, 0
	s_add_i32 s30, s64, s38
	global_load_lds_dwordx4 v[144:145], off
	v_lshl_add_u64 v[144:145], s[28:29], 0, v[132:133]
	s_mov_b32 m0, s30
	s_nop 0
	global_load_lds_dwordx4 v[144:145], off
	v_lshl_add_u64 v[144:145], s[28:29], 0, v[128:129]
	s_add_i32 m0, s30, 0x2000
	s_nop 0
	global_load_lds_dwordx4 v[144:145], off
	v_lshl_add_u64 v[144:145], v[218:219], 0, s[12:13]
	s_mov_b32 m0, s50
	s_nop 0
	global_load_lds_dwordx4 v[144:145], off
	v_lshl_add_u64 v[144:145], v[220:221], 0, s[12:13]
	s_mov_b32 m0, s51
	s_nop 0
	global_load_lds_dwordx4 v[144:145], off
	s_waitcnt vmcnt(8)
	s_waitcnt lgkmcnt(0)
	s_barrier
	s_setprio 1
	v_mfma_f32_16x16x32_bf16 v[60:63], v[152:155], v[184:187], v[60:63]
	v_mfma_f32_16x16x32_bf16 v[52:55], v[160:163], v[184:187], v[52:55]
	v_mfma_f32_16x16x32_bf16 v[44:47], v[152:155], v[192:195], v[44:47]
	v_mfma_f32_16x16x32_bf16 v[36:39], v[160:163], v[192:195], v[36:39]
	v_mfma_f32_16x16x32_bf16 v[28:31], v[152:155], v[200:203], v[28:31]
	v_mfma_f32_16x16x32_bf16 v[20:23], v[160:163], v[200:203], v[20:23]
	v_mfma_f32_16x16x32_bf16 v[12:15], v[152:155], v[208:211], v[12:15]
	v_mfma_f32_16x16x32_bf16 v[4:7], v[160:163], v[208:211], v[4:7]
	v_mfma_f32_16x16x32_bf16 v[60:63], v[156:159], v[188:191], v[60:63]
	v_mfma_f32_16x16x32_bf16 v[52:55], v[164:167], v[188:191], v[52:55]
	v_mfma_f32_16x16x32_bf16 v[44:47], v[156:159], v[196:199], v[44:47]
	v_mfma_f32_16x16x32_bf16 v[36:39], v[164:167], v[196:199], v[36:39]
	v_mfma_f32_16x16x32_bf16 v[28:31], v[156:159], v[204:207], v[28:31]
	v_mfma_f32_16x16x32_bf16 v[20:23], v[164:167], v[204:207], v[20:23]
	v_mfma_f32_16x16x32_bf16 v[12:15], v[156:159], v[212:215], v[12:15]
	v_mfma_f32_16x16x32_bf16 v[4:7], v[164:167], v[212:215], v[4:7]
	v_mfma_f32_16x16x32_bf16 v[56:59], v[168:171], v[184:187], v[56:59]
	v_mfma_f32_16x16x32_bf16 v[48:51], v[176:179], v[184:187], v[48:51]
	v_mfma_f32_16x16x32_bf16 v[40:43], v[168:171], v[192:195], v[40:43]
	v_mfma_f32_16x16x32_bf16 v[32:35], v[176:179], v[192:195], v[32:35]
	v_mfma_f32_16x16x32_bf16 v[24:27], v[168:171], v[200:203], v[24:27]
	v_mfma_f32_16x16x32_bf16 v[16:19], v[176:179], v[200:203], v[16:19]
	v_mfma_f32_16x16x32_bf16 v[8:11], v[168:171], v[208:211], v[8:11]
	v_mfma_f32_16x16x32_bf16 v[0:3], v[176:179], v[208:211], v[0:3]
	v_mfma_f32_16x16x32_bf16 v[56:59], v[172:175], v[188:191], v[56:59]
	v_mfma_f32_16x16x32_bf16 v[48:51], v[180:183], v[188:191], v[48:51]
	v_mfma_f32_16x16x32_bf16 v[40:43], v[172:175], v[196:199], v[40:43]
	v_mfma_f32_16x16x32_bf16 v[32:35], v[180:183], v[196:199], v[32:35]
	v_mfma_f32_16x16x32_bf16 v[24:27], v[172:175], v[204:207], v[24:27]
	v_mfma_f32_16x16x32_bf16 v[16:19], v[180:183], v[204:207], v[16:19]
	v_mfma_f32_16x16x32_bf16 v[8:11], v[172:175], v[212:215], v[8:11]
	v_mfma_f32_16x16x32_bf16 v[0:3], v[180:183], v[212:215], v[0:3]
	s_setprio 0
	s_barrier
	s_add_u32 s26, s26, 0x100
	s_addc_u32 s27, s27, 0
	s_add_u32 s60, s60, 0x100
	s_addc_u32 s61, s61, 0
	s_cmp_ge_i32 s62, s48
	s_mov_b32 s28, s62
	s_cbranch_scc0 .LBB0_259

; #define PG8_STAGE(bufoff, gbase, voff) do { _Pragma("unroll") for (int _i = 0; _i < 2; ++_i) \
;         __builtin_amdgcn_global_load_lds((const unsigned*)((const char*)(gbase) + (voff)[_i]), (PG8_LAS unsigned*)(lds + (bufoff) + ldsw + _i * 8192), 16, 0, 0); } while (0)
; #define PG8_LDA(dst, b, h) do { _Pragma("unroll") for (int m = 0; m < 4; ++m) _Pragma("unroll") for (int k = 0; k < 2; ++k) dst[m][k] = *(const PG8_LAS bf16x8*)(lds + PG8_SA(b, h) + aoff + m * 2048 + k * 1024); } while (0)
; #define PG8_LDB(dst, b, h) do { _Pragma("unroll") for (int n = 0; n < 2; ++n) _Pragma("unroll") for (int k = 0; k < 2; ++k) dst[n][k] = *(const PG8_LAS bf16x8*)(lds + PG8_SB(b, h) + boff + n * 2048 + k * 1024); } while (0)
; #define PG8_MMA(ai, bj, At, Bt) do { __builtin_amdgcn_s_setprio(1); _Pragma("unroll") for (int m = 0; m < 4; ++m) _Pragma("unroll") for (int n = 0; n < 2; ++n) _Pragma("unroll") for (int k = 0; k < 2; ++k) \
;         acc[ai][bj][m][n] = __builtin_amdgcn_mfma_f32_16x16x32_bf16(Bt[n][k], At[m][k], acc[ai][bj][m][n], 0, 0, 0); __builtin_amdgcn_s_setprio(0); } while (0)
; #define PG8_WAIT_V(n) asm volatile("s_waitcnt vmcnt(" #n ")" ::: "memory")
; #define PG8_WAIT_L(n) asm volatile("s_waitcnt lgkmcnt(" #n ")" ::: "memory")
; #define PG8_BAR __builtin_amdgcn_s_barrier()
; #define PG8_SCHED __builtin_amdgcn_sched_barrier(0)
; template <class Epi, class Sched, bool ALIGN_EPI = false, bool SP2 = false>
; __device__ __forceinline__ void gemm_phase(PG8_LAS unsigned char* lds, const Gemm g, const Sched& S, const Epi& E) {
;     ...
;             if constexpr (SP2) {
;             PG8_LDB(B0, 0, 0); PG8_LDB(B1, 0, 1); PG8_SCHED; PG8_LDA(At, 0, 0); PG8_STAGE(PG8_SA(1, 1), a1 + hstepA, voffA);
;             PG8_WAIT_V(8); PG8_WAIT_L(0); PG8_BAR; PG8_MMA(0, 0, At, B0); PG8_MMA(0, 1, At, B1); PG8_BAR; PG8_SCHED;
;             PG8_LDA(At, 0, 1); PG8_STAGE(PG8_SB(0, 0), b2, voffB); PG8_STAGE(PG8_SB(0, 1), b2 + hstepB, voffB); PG8_STAGE(PG8_SA(0, 0), a2, voffA);
;             PG8_WAIT_V(8); PG8_WAIT_L(0); PG8_BAR; PG8_MMA(1, 0, At, B0); PG8_MMA(1, 1, At, B1); PG8_BAR; PG8_SCHED;
.LBB0_338:
	ds_read_b128 v[150:153], v169
	ds_read_b128 v[154:157], v169 offset:1024
	ds_read_b128 v[158:161], v169 offset:2048
	ds_read_b128 v[162:165], v169 offset:3072
	ds_read_b128 v[174:177], v170
	ds_read_b128 v[178:181], v170 offset:1024
	ds_read_b128 v[182:185], v170 offset:2048
	ds_read_b128 v[186:189], v170 offset:3072
	s_add_i32 s64, s44, 2
	s_add_u32 s45, s42, 0x3fc000
	s_addc_u32 s46, s43, 0
	s_cmp_eq_u32 s57, s44
	s_cselect_b32 s48, s8, s45
	s_cselect_b32 s49, s7, s46
	s_cselect_b32 s46, s29, s31
	s_cselect_b32 s47, s9, s41
	s_add_u32 s44, s48, 0x400000
	s_addc_u32 s45, s49, 0
	v_lshl_add_u64 v[166:167], s[42:43], 0, v[138:139]
	s_add_i32 m0, s20, 0xc000
	ds_read_b128 v[190:193], v171
	ds_read_b128 v[194:197], v171 offset:1024
	ds_read_b128 v[198:201], v171 offset:2048
	ds_read_b128 v[202:205], v171 offset:3072
	ds_read_b128 v[206:209], v171 offset:4096
	ds_read_b128 v[210:213], v171 offset:5120
	ds_read_b128 v[214:217], v171 offset:6144
	ds_read_b128 v[218:221], v171 offset:7168
	global_load_lds_dwordx4 v[166:167], off
	v_lshl_add_u64 v[166:167], s[42:43], 0, v[140:141]
	s_add_i32 m0, s20, 0xe000
	s_nop 0
	global_load_lds_dwordx4 v[166:167], off
	s_waitcnt vmcnt(8)
	s_waitcnt lgkmcnt(0)
	s_barrier
	s_setprio 1
	v_mfma_f32_16x16x32_bf16 v[124:127], v[150:153], v[190:193], v[124:127]
	v_mfma_f32_16x16x32_bf16 v[120:123], v[158:161], v[190:193], v[120:123]
	v_mfma_f32_16x16x32_bf16 v[116:119], v[150:153], v[198:201], v[116:119]
	v_mfma_f32_16x16x32_bf16 v[112:115], v[158:161], v[198:201], v[112:115]
	v_mfma_f32_16x16x32_bf16 v[108:111], v[150:153], v[206:209], v[108:111]
	v_mfma_f32_16x16x32_bf16 v[104:107], v[158:161], v[206:209], v[104:107]
	v_mfma_f32_16x16x32_bf16 v[100:103], v[150:153], v[214:217], v[100:103]
	v_mfma_f32_16x16x32_bf16 v[96:99], v[158:161], v[214:217], v[96:99]
	v_mfma_f32_16x16x32_bf16 v[124:127], v[154:157], v[194:197], v[124:127]
	v_mfma_f32_16x16x32_bf16 v[120:123], v[162:165], v[194:197], v[120:123]
	v_mfma_f32_16x16x32_bf16 v[116:119], v[154:157], v[202:205], v[116:119]
	v_mfma_f32_16x16x32_bf16 v[112:115], v[162:165], v[202:205], v[112:115]
	v_mfma_f32_16x16x32_bf16 v[108:111], v[154:157], v[210:213], v[108:111]
	v_mfma_f32_16x16x32_bf16 v[104:107], v[162:165], v[210:213], v[104:107]
	v_mfma_f32_16x16x32_bf16 v[100:103], v[154:157], v[218:221], v[100:103]
	v_mfma_f32_16x16x32_bf16 v[96:99], v[162:165], v[218:221], v[96:99]
	v_mfma_f32_16x16x32_bf16 v[60:63], v[174:177], v[190:193], v[60:63]
	v_mfma_f32_16x16x32_bf16 v[56:59], v[182:185], v[190:193], v[56:59]
	v_mfma_f32_16x16x32_bf16 v[52:55], v[174:177], v[198:201], v[52:55]
	v_mfma_f32_16x16x32_bf16 v[48:51], v[182:185], v[198:201], v[48:51]
	v_mfma_f32_16x16x32_bf16 v[44:47], v[174:177], v[206:209], v[44:47]
	v_mfma_f32_16x16x32_bf16 v[40:43], v[182:185], v[206:209], v[40:43]
	v_mfma_f32_16x16x32_bf16 v[36:39], v[174:177], v[214:217], v[36:39]
	v_mfma_f32_16x16x32_bf16 v[32:35], v[182:185], v[214:217], v[32:35]
	v_mfma_f32_16x16x32_bf16 v[60:63], v[178:181], v[194:197], v[60:63]
	v_mfma_f32_16x16x32_bf16 v[56:59], v[186:189], v[194:197], v[56:59]
	v_mfma_f32_16x16x32_bf16 v[52:55], v[178:181], v[202:205], v[52:55]
	v_mfma_f32_16x16x32_bf16 v[48:51], v[186:189], v[202:205], v[48:51]
	v_mfma_f32_16x16x32_bf16 v[44:47], v[178:181], v[210:213], v[44:47]
	v_mfma_f32_16x16x32_bf16 v[40:43], v[186:189], v[210:213], v[40:43]
	v_mfma_f32_16x16x32_bf16 v[36:39], v[178:181], v[218:221], v[36:39]
	v_mfma_f32_16x16x32_bf16 v[32:35], v[186:189], v[218:221], v[32:35]
	s_setprio 0
	s_barrier
	s_add_i32 s65, s62, s19
	v_lshl_add_u64 v[166:167], s[46:47], 0, v[130:131]
	s_mov_b32 m0, s65
	ds_read_b128 v[190:193], v171 offset:16384
	ds_read_b128 v[194:197], v171 offset:17408
	ds_read_b128 v[198:201], v171 offset:18432
	ds_read_b128 v[202:205], v171 offset:19456
	ds_read_b128 v[206:209], v171 offset:20480
	ds_read_b128 v[210:213], v171 offset:21504
	ds_read_b128 v[214:217], v171 offset:22528
	ds_read_b128 v[218:221], v171 offset:23552
	global_load_lds_dwordx4 v[166:167], off
	s_add_i32 m0, s65, 0x2000
	s_add_u32 s66, s46, 0x4000
	v_lshl_add_u64 v[166:167], s[46:47], 0, v[134:135]
	s_addc_u32 s67, s47, 0
	s_add_i32 s65, s63, s19
	global_load_lds_dwordx4 v[166:167], off
	v_lshl_add_u64 v[166:167], s[66:67], 0, v[130:131]
	s_mov_b32 m0, s65
	s_nop 0
	global_load_lds_dwordx4 v[166:167], off
	v_lshl_add_u64 v[166:167], s[66:67], 0, v[134:135]
	s_add_i32 m0, s65, 0x2000
	s_nop 0
	global_load_lds_dwordx4 v[166:167], off
	v_lshl_add_u64 v[166:167], s[48:49], 0, v[128:129]
	s_mov_b32 m0, s20
	s_nop 0
	global_load_lds_dwordx4 v[166:167], off
	v_lshl_add_u64 v[166:167], s[48:49], 0, v[132:133]
	s_mov_b32 m0, s21
	s_nop 0
	global_load_lds_dwordx4 v[166:167], off
	s_waitcnt vmcnt(8)
	s_waitcnt lgkmcnt(0)
	s_barrier
; #define PG8_STAGE(bufoff, gbase, voff) do { _Pragma("unroll") for (int _i = 0; _i < 2; ++_i) \
;         __builtin_amdgcn_global_load_lds((const unsigned*)((const char*)(gbase) + (voff)[_i]), (PG8_LAS unsigned*)(lds + (bufoff) + ldsw + _i * 8192), 16, 0, 0); } while (0)
; #define PG8_LDA(dst, b, h) do { _Pragma("unroll") for (int m = 0; m < 4; ++m) _Pragma("unroll") for (int k = 0; k < 2; ++k) dst[m][k] = *(const PG8_LAS bf16x8*)(lds + PG8_SA(b, h) + aoff + m * 2048 + k * 1024); } while (0)
; #define PG8_LDB(dst, b, h) do { _Pragma("unroll") for (int n = 0; n < 2; ++n) _Pragma("unroll") for (int k = 0; k < 2; ++k) dst[n][k] = *(const PG8_LAS bf16x8*)(lds + PG8_SB(b, h) + boff + n * 2048 + k * 1024); } while (0)
; #define PG8_MMA(ai, bj, At, Bt) do { __builtin_amdgcn_s_setprio(1); _Pragma("unroll") for (int m = 0; m < 4; ++m) _Pragma("unroll") for (int n = 0; n < 2; ++n) _Pragma("unroll") for (int k = 0; k < 2; ++k) \
;         acc[ai][bj][m][n] = __builtin_amdgcn_mfma_f32_16x16x32_bf16(Bt[n][k], At[m][k], acc[ai][bj][m][n], 0, 0, 0); __builtin_amdgcn_s_setprio(0); } while (0)
; #define PG8_WAIT_V(n) asm volatile("s_waitcnt vmcnt(" #n ")" ::: "memory")
; #define PG8_WAIT_L(n) asm volatile("s_waitcnt lgkmcnt(" #n ")" ::: "memory")
; #define PG8_BAR __builtin_amdgcn_s_barrier()
; #define PG8_SCHED __builtin_amdgcn_sched_barrier(0)
; template <class Epi, class Sched, bool ALIGN_EPI = false, bool SP2 = false>
; __device__ __forceinline__ void gemm_phase(PG8_LAS unsigned char* lds, const Gemm g, const Sched& S, const Epi& E) {
;     ...
;             PG8_WAIT_V(8); PG8_WAIT_L(0); PG8_BAR; PG8_MMA(1, 0, At, B0); PG8_MMA(1, 1, At, B1); PG8_BAR; PG8_SCHED;
;             PG8_LDB(B0, 1, 0); PG8_LDB(B1, 1, 1); PG8_SCHED; PG8_LDA(At, 1, 0); PG8_STAGE(PG8_SA(0, 1), a2 + hstepA, voffA);
;             PG8_WAIT_V(8); PG8_WAIT_L(0); PG8_BAR; PG8_MMA(0, 0, At, B0); PG8_MMA(0, 1, At, B1); PG8_BAR; PG8_SCHED;
	s_setprio 1
	v_mfma_f32_16x16x32_bf16 v[92:95], v[150:153], v[190:193], v[92:95]
	v_mfma_f32_16x16x32_bf16 v[88:91], v[158:161], v[190:193], v[88:91]
	v_mfma_f32_16x16x32_bf16 v[84:87], v[150:153], v[198:201], v[84:87]
	v_mfma_f32_16x16x32_bf16 v[80:83], v[158:161], v[198:201], v[80:83]
	v_mfma_f32_16x16x32_bf16 v[76:79], v[150:153], v[206:209], v[76:79]
	v_mfma_f32_16x16x32_bf16 v[72:75], v[158:161], v[206:209], v[72:75]
	v_mfma_f32_16x16x32_bf16 v[68:71], v[150:153], v[214:217], v[68:71]
	v_mfma_f32_16x16x32_bf16 v[64:67], v[158:161], v[214:217], v[64:67]
	v_mfma_f32_16x16x32_bf16 v[92:95], v[154:157], v[194:197], v[92:95]
	v_mfma_f32_16x16x32_bf16 v[88:91], v[162:165], v[194:197], v[88:91]
	v_mfma_f32_16x16x32_bf16 v[84:87], v[154:157], v[202:205], v[84:87]
	v_mfma_f32_16x16x32_bf16 v[80:83], v[162:165], v[202:205], v[80:83]
	v_mfma_f32_16x16x32_bf16 v[76:79], v[154:157], v[210:213], v[76:79]
	v_mfma_f32_16x16x32_bf16 v[72:75], v[162:165], v[210:213], v[72:75]
	v_mfma_f32_16x16x32_bf16 v[68:71], v[154:157], v[218:221], v[68:71]
	v_mfma_f32_16x16x32_bf16 v[64:67], v[162:165], v[218:221], v[64:67]
	v_mfma_f32_16x16x32_bf16 v[28:31], v[174:177], v[190:193], v[28:31]
	v_mfma_f32_16x16x32_bf16 v[24:27], v[182:185], v[190:193], v[24:27]
	v_mfma_f32_16x16x32_bf16 v[20:23], v[174:177], v[198:201], v[20:23]
	v_mfma_f32_16x16x32_bf16 v[16:19], v[182:185], v[198:201], v[16:19]
	v_mfma_f32_16x16x32_bf16 v[12:15], v[174:177], v[206:209], v[12:15]
	v_mfma_f32_16x16x32_bf16 v[8:11], v[182:185], v[206:209], v[8:11]
	v_mfma_f32_16x16x32_bf16 v[4:7], v[174:177], v[214:217], v[4:7]
	v_mfma_f32_16x16x32_bf16 v[0:3], v[182:185], v[214:217], v[0:3]
	v_mfma_f32_16x16x32_bf16 v[28:31], v[178:181], v[194:197], v[28:31]
	v_mfma_f32_16x16x32_bf16 v[24:27], v[186:189], v[194:197], v[24:27]
	v_mfma_f32_16x16x32_bf16 v[20:23], v[178:181], v[202:205], v[20:23]
	v_mfma_f32_16x16x32_bf16 v[16:19], v[186:189], v[202:205], v[16:19]
	v_mfma_f32_16x16x32_bf16 v[12:15], v[178:181], v[210:213], v[12:15]
	v_mfma_f32_16x16x32_bf16 v[8:11], v[186:189], v[210:213], v[8:11]
	v_mfma_f32_16x16x32_bf16 v[4:7], v[178:181], v[218:221], v[4:7]
	v_mfma_f32_16x16x32_bf16 v[0:3], v[186:189], v[218:221], v[0:3]
	s_setprio 0
	s_barrier
	s_add_i32 s65, 0, 0x18000
	v_add_u32_e32 v137, s65, v168
	s_add_i32 s66, 0, 0x1c000
	ds_read_b128 v[150:153], v137
	ds_read_b128 v[154:157], v137 offset:1024
	ds_read_b128 v[158:161], v137 offset:2048
	ds_read_b128 v[162:165], v137 offset:3072
	v_add_u32_e32 v137, s66, v168
	ds_read_b128 v[174:177], v137
	ds_read_b128 v[178:181], v137 offset:1024
	ds_read_b128 v[182:185], v137 offset:2048
	ds_read_b128 v[186:189], v137 offset:3072
	s_add_u32 s48, s48, 0x4000
	s_addc_u32 s49, s49, 0
	s_mov_b32 m0, s33
	v_lshl_add_u64 v[166:167], s[48:49], 0, v[128:129]
	ds_read_b128 v[190:193], v171 offset:32768
	ds_read_b128 v[194:197], v171 offset:33792
	ds_read_b128 v[198:201], v171 offset:34816
	ds_read_b128 v[202:205], v171 offset:35840
	ds_read_b128 v[206:209], v171 offset:36864
	ds_read_b128 v[210:213], v171 offset:37888
	ds_read_b128 v[214:217], v171 offset:38912
	ds_read_b128 v[218:221], v171 offset:39936
	global_load_lds_dwordx4 v[166:167], off
	v_lshl_add_u64 v[166:167], s[48:49], 0, v[132:133]
	s_mov_b32 m0, s50
	s_nop 0
	global_load_lds_dwordx4 v[166:167], off
	s_waitcnt vmcnt(8)
	s_waitcnt lgkmcnt(0)
	s_barrier
	s_setprio 1
	v_mfma_f32_16x16x32_bf16 v[124:127], v[150:153], v[190:193], v[124:127]
	v_mfma_f32_16x16x32_bf16 v[120:123], v[158:161], v[190:193], v[120:123]
	v_mfma_f32_16x16x32_bf16 v[116:119], v[150:153], v[198:201], v[116:119]
	v_mfma_f32_16x16x32_bf16 v[112:115], v[158:161], v[198:201], v[112:115]
	v_mfma_f32_16x16x32_bf16 v[108:111], v[150:153], v[206:209], v[108:111]
	v_mfma_f32_16x16x32_bf16 v[104:107], v[158:161], v[206:209], v[104:107]
	v_mfma_f32_16x16x32_bf16 v[100:103], v[150:153], v[214:217], v[100:103]
	v_mfma_f32_16x16x32_bf16 v[96:99], v[158:161], v[214:217], v[96:99]
	v_mfma_f32_16x16x32_bf16 v[124:127], v[154:157], v[194:197], v[124:127]
	v_mfma_f32_16x16x32_bf16 v[120:123], v[162:165], v[194:197], v[120:123]
	v_mfma_f32_16x16x32_bf16 v[116:119], v[154:157], v[202:205], v[116:119]
	v_mfma_f32_16x16x32_bf16 v[112:115], v[162:165], v[202:205], v[112:115]
	v_mfma_f32_16x16x32_bf16 v[108:111], v[154:157], v[210:213], v[108:111]
	v_mfma_f32_16x16x32_bf16 v[104:107], v[162:165], v[210:213], v[104:107]
	v_mfma_f32_16x16x32_bf16 v[100:103], v[154:157], v[218:221], v[100:103]
	v_mfma_f32_16x16x32_bf16 v[96:99], v[162:165], v[218:221], v[96:99]
	v_mfma_f32_16x16x32_bf16 v[60:63], v[174:177], v[190:193], v[60:63]
	v_mfma_f32_16x16x32_bf16 v[56:59], v[182:185], v[190:193], v[56:59]
	v_mfma_f32_16x16x32_bf16 v[52:55], v[174:177], v[198:201], v[52:55]
	v_mfma_f32_16x16x32_bf16 v[48:51], v[182:185], v[198:201], v[48:51]
	v_mfma_f32_16x16x32_bf16 v[44:47], v[174:177], v[206:209], v[44:47]
	v_mfma_f32_16x16x32_bf16 v[40:43], v[182:185], v[206:209], v[40:43]
	v_mfma_f32_16x16x32_bf16 v[36:39], v[174:177], v[214:217], v[36:39]
	v_mfma_f32_16x16x32_bf16 v[32:35], v[182:185], v[214:217], v[32:35]
	v_mfma_f32_16x16x32_bf16 v[60:63], v[178:181], v[194:197], v[60:63]
	v_mfma_f32_16x16x32_bf16 v[56:59], v[186:189], v[194:197], v[56:59]
	v_mfma_f32_16x16x32_bf16 v[52:55], v[178:181], v[202:205], v[52:55]
	v_mfma_f32_16x16x32_bf16 v[48:51], v[186:189], v[202:205], v[48:51]
	v_mfma_f32_16x16x32_bf16 v[44:47], v[178:181], v[210:213], v[44:47]
	v_mfma_f32_16x16x32_bf16 v[40:43], v[186:189], v[210:213], v[40:43]
	v_mfma_f32_16x16x32_bf16 v[36:39], v[178:181], v[218:221], v[36:39]
	v_mfma_f32_16x16x32_bf16 v[32:35], v[186:189], v[218:221], v[32:35]
	s_setprio 0
	s_barrier
; #define PG8_STAGE(bufoff, gbase, voff) do { _Pragma("unroll") for (int _i = 0; _i < 2; ++_i) \
;         __builtin_amdgcn_global_load_lds((const unsigned*)((const char*)(gbase) + (voff)[_i]), (PG8_LAS unsigned*)(lds + (bufoff) + ldsw + _i * 8192), 16, 0, 0); } while (0)
; #define PG8_LDA(dst, b, h) do { _Pragma("unroll") for (int m = 0; m < 4; ++m) _Pragma("unroll") for (int k = 0; k < 2; ++k) dst[m][k] = *(const PG8_LAS bf16x8*)(lds + PG8_SA(b, h) + aoff + m * 2048 + k * 1024); } while (0)
; #define PG8_MMA(ai, bj, At, Bt) do { __builtin_amdgcn_s_setprio(1); _Pragma("unroll") for (int m = 0; m < 4; ++m) _Pragma("unroll") for (int n = 0; n < 2; ++n) _Pragma("unroll") for (int k = 0; k < 2; ++k) \
;         acc[ai][bj][m][n] = __builtin_amdgcn_mfma_f32_16x16x32_bf16(Bt[n][k], At[m][k], acc[ai][bj][m][n], 0, 0, 0); __builtin_amdgcn_s_setprio(0); } while (0)
; #define PG8_WAIT_V(n) asm volatile("s_waitcnt vmcnt(" #n ")" ::: "memory")
; #define PG8_WAIT_L(n) asm volatile("s_waitcnt lgkmcnt(" #n ")" ::: "memory")
; #define PG8_BAR __builtin_amdgcn_s_barrier()
; #define PG8_SCHED __builtin_amdgcn_sched_barrier(0)
; template <class Epi, class Sched, bool ALIGN_EPI = false, bool SP2 = false>
; __device__ __forceinline__ void gemm_phase(PG8_LAS unsigned char* lds, const Gemm g, const Sched& S, const Epi& E) {
;     ...
;         for (int t = 0; t < nt; t += 2) {
;             const bool last = (t == nt - 2);
;             const char* a1 = cA + (long)(t + 1) * kstepA;
;             const char* a2 = last ? nA : cA + (long)(t + 2) * kstepA; const char* b2 = last ? nB : cB + (long)(t + 2) * kstep;
;     ...
;             PG8_LDA(At, 1, 1); PG8_STAGE(PG8_SB(1, 0), b3, voffB); PG8_STAGE(PG8_SB(1, 1), b3 + hstepB, voffB); PG8_STAGE(PG8_SA(1, 0), a3, voffA);
;             PG8_WAIT_V(8); PG8_WAIT_L(0); PG8_BAR; PG8_MMA(1, 0, At, B0); PG8_MMA(1, 1, At, B1); PG8_BAR; PG8_SCHED;
	s_add_u32 s48, s46, 0x20000
	s_addc_u32 s49, s47, 0
	s_add_i32 s65, s65, s19
	v_lshl_add_u64 v[166:167], s[48:49], 0, v[130:131]
	s_mov_b32 m0, s65
	ds_read_b128 v[190:193], v171 offset:49152
	ds_read_b128 v[194:197], v171 offset:50176
	ds_read_b128 v[198:201], v171 offset:51200
	ds_read_b128 v[202:205], v171 offset:52224
	ds_read_b128 v[206:209], v171 offset:53248
	ds_read_b128 v[210:213], v171 offset:54272
	ds_read_b128 v[214:217], v171 offset:55296
	ds_read_b128 v[218:221], v171 offset:56320
	global_load_lds_dwordx4 v[166:167], off
	s_add_i32 m0, s65, 0x2000
	s_add_u32 s46, s46, 0x24000
	v_lshl_add_u64 v[166:167], s[48:49], 0, v[134:135]
	s_addc_u32 s47, s47, 0
	s_add_i32 s48, s66, s19
	global_load_lds_dwordx4 v[166:167], off
	v_lshl_add_u64 v[166:167], s[46:47], 0, v[130:131]
	s_mov_b32 m0, s48
	s_nop 0
	global_load_lds_dwordx4 v[166:167], off
	v_lshl_add_u64 v[166:167], s[46:47], 0, v[134:135]
	s_add_i32 m0, s48, 0x2000
	s_nop 0
	global_load_lds_dwordx4 v[166:167], off
	v_lshl_add_u64 v[166:167], s[44:45], 0, v[128:129]
	s_mov_b32 m0, s55
	s_nop 0
	global_load_lds_dwordx4 v[166:167], off
	v_lshl_add_u64 v[166:167], s[44:45], 0, v[132:133]
	s_mov_b32 m0, s56
	s_nop 0
	global_load_lds_dwordx4 v[166:167], off
	s_waitcnt vmcnt(8)
	s_waitcnt lgkmcnt(0)
	s_barrier
	s_setprio 1
	v_mfma_f32_16x16x32_bf16 v[92:95], v[150:153], v[190:193], v[92:95]
	v_mfma_f32_16x16x32_bf16 v[88:91], v[158:161], v[190:193], v[88:91]
	v_mfma_f32_16x16x32_bf16 v[84:87], v[150:153], v[198:201], v[84:87]
	v_mfma_f32_16x16x32_bf16 v[80:83], v[158:161], v[198:201], v[80:83]
	v_mfma_f32_16x16x32_bf16 v[76:79], v[150:153], v[206:209], v[76:79]
	v_mfma_f32_16x16x32_bf16 v[72:75], v[158:161], v[206:209], v[72:75]
	v_mfma_f32_16x16x32_bf16 v[68:71], v[150:153], v[214:217], v[68:71]
	v_mfma_f32_16x16x32_bf16 v[64:67], v[158:161], v[214:217], v[64:67]
	v_mfma_f32_16x16x32_bf16 v[92:95], v[154:157], v[194:197], v[92:95]
	v_mfma_f32_16x16x32_bf16 v[88:91], v[162:165], v[194:197], v[88:91]
	v_mfma_f32_16x16x32_bf16 v[84:87], v[154:157], v[202:205], v[84:87]
	v_mfma_f32_16x16x32_bf16 v[80:83], v[162:165], v[202:205], v[80:83]
	v_mfma_f32_16x16x32_bf16 v[76:79], v[154:157], v[210:213], v[76:79]
	v_mfma_f32_16x16x32_bf16 v[72:75], v[162:165], v[210:213], v[72:75]
	v_mfma_f32_16x16x32_bf16 v[68:71], v[154:157], v[218:221], v[68:71]
	v_mfma_f32_16x16x32_bf16 v[64:67], v[162:165], v[218:221], v[64:67]
	v_mfma_f32_16x16x32_bf16 v[28:31], v[174:177], v[190:193], v[28:31]
	v_mfma_f32_16x16x32_bf16 v[24:27], v[182:185], v[190:193], v[24:27]
	v_mfma_f32_16x16x32_bf16 v[20:23], v[174:177], v[198:201], v[20:23]
	v_mfma_f32_16x16x32_bf16 v[16:19], v[182:185], v[198:201], v[16:19]
	v_mfma_f32_16x16x32_bf16 v[12:15], v[174:177], v[206:209], v[12:15]
	v_mfma_f32_16x16x32_bf16 v[8:11], v[182:185], v[206:209], v[8:11]
	v_mfma_f32_16x16x32_bf16 v[4:7], v[174:177], v[214:217], v[4:7]
	v_mfma_f32_16x16x32_bf16 v[0:3], v[182:185], v[214:217], v[0:3]
	v_mfma_f32_16x16x32_bf16 v[28:31], v[178:181], v[194:197], v[28:31]
	v_mfma_f32_16x16x32_bf16 v[24:27], v[186:189], v[194:197], v[24:27]
	v_mfma_f32_16x16x32_bf16 v[20:23], v[178:181], v[202:205], v[20:23]
	v_mfma_f32_16x16x32_bf16 v[16:19], v[186:189], v[202:205], v[16:19]
	v_mfma_f32_16x16x32_bf16 v[12:15], v[178:181], v[210:213], v[12:15]
	v_mfma_f32_16x16x32_bf16 v[8:11], v[186:189], v[210:213], v[8:11]
	v_mfma_f32_16x16x32_bf16 v[4:7], v[178:181], v[218:221], v[4:7]
	v_mfma_f32_16x16x32_bf16 v[0:3], v[186:189], v[218:221], v[0:3]
	s_setprio 0
	s_barrier
	s_add_u32 s31, s31, 0x40000
	s_addc_u32 s41, s41, 0
	s_add_u32 s42, s42, 0x800000
	s_addc_u32 s43, s43, 0
	s_cmp_ge_i32 s64, s52
	s_mov_b32 s44, s64
	s_cbranch_scc0 .LBB0_338

; #define PG8_STAGE(bufoff, gbase, voff) do { _Pragma("unroll") for (int _i = 0; _i < 2; ++_i) \
;         __builtin_amdgcn_global_load_lds((const unsigned*)((const char*)(gbase) + (voff)[_i]), (PG8_LAS unsigned*)(lds + (bufoff) + ldsw + _i * 8192), 16, 0, 0); } while (0)
; #define PG8_LDA(dst, b, h) do { _Pragma("unroll") for (int m = 0; m < 4; ++m) _Pragma("unroll") for (int k = 0; k < 2; ++k) dst[m][k] = *(const PG8_LAS bf16x8*)(lds + PG8_SA(b, h) + aoff + m * 2048 + k * 1024); } while (0)
; #define PG8_LDB(dst, b, h) do { _Pragma("unroll") for (int n = 0; n < 2; ++n) _Pragma("unroll") for (int k = 0; k < 2; ++k) dst[n][k] = *(const PG8_LAS bf16x8*)(lds + PG8_SB(b, h) + boff + n * 2048 + k * 1024); } while (0)
; #define PG8_MMA(ai, bj, At, Bt) do { __builtin_amdgcn_s_setprio(1); _Pragma("unroll") for (int m = 0; m < 4; ++m) _Pragma("unroll") for (int n = 0; n < 2; ++n) _Pragma("unroll") for (int k = 0; k < 2; ++k) \
;         acc[ai][bj][m][n] = __builtin_amdgcn_mfma_f32_16x16x32_bf16(Bt[n][k], At[m][k], acc[ai][bj][m][n], 0, 0, 0); __builtin_amdgcn_s_setprio(0); } while (0)
; #define PG8_WAIT_V(n) asm volatile("s_waitcnt vmcnt(" #n ")" ::: "memory")
; #define PG8_WAIT_L(n) asm volatile("s_waitcnt lgkmcnt(" #n ")" ::: "memory")
; template <class Epi, class Sched, bool ALIGN_EPI = false, bool SP2 = false>
; __device__ __forceinline__ void gemm_phase(PG8_LAS unsigned char* lds, const Gemm g, const Sched& S, const Epi& E) {
;     ...
;             const bool last = (t == nt - 2);
;             const char* a1 = cA + (long)(t + 1) * kstepA;
;             const char* a2 = last ? nA : cA + (long)(t + 2) * kstepA; const char* b2 = last ? nB : cB + (long)(t + 2) * kstep;
;             const char* a3 = a2 + kstepA; const char* b3 = b2 + kstep;
;             if (last && has_next) S.a_ready(nxt);
;             if constexpr (SP2) {
;             PG8_LDB(B0, 0, 0); PG8_LDB(B1, 0, 1); PG8_SCHED; PG8_LDA(At, 0, 0); PG8_STAGE(PG8_SA(1, 1), a1 + hstepA, voffA);
;             PG8_WAIT_V(8); PG8_WAIT_L(0); PG8_BAR; PG8_MMA(0, 0, At, B0); PG8_MMA(0, 1, At, B1); PG8_BAR; PG8_SCHED;
;             PG8_LDA(At, 0, 1); PG8_STAGE(PG8_SB(0, 0), b2, voffB); PG8_STAGE(PG8_SB(0, 1), b2 + hstepB, voffB); PG8_STAGE(PG8_SA(0, 0), a2, voffA);
;             PG8_WAIT_V(8); PG8_WAIT_L(0); PG8_BAR; PG8_MMA(1, 0, At, B0); PG8_MMA(1, 1, At, B1); PG8_BAR; PG8_SCHED;
.LBB0_433:
	ds_read_b128 v[128:131], v199
	ds_read_b128 v[132:135], v199 offset:1024
	ds_read_b128 v[136:139], v199 offset:2048
	ds_read_b128 v[140:143], v199 offset:3072
	ds_read_b128 v[144:147], v205
	ds_read_b128 v[148:151], v205 offset:1024
	ds_read_b128 v[152:155], v205 offset:2048
	ds_read_b128 v[156:159], v205 offset:3072
	s_add_i32 s68, s52, 2
	s_add_u32 s53, s50, 0xfffc0080
	s_addc_u32 s54, s51, -1
	s_cmp_eq_u32 s61, s52
	s_cselect_b32 s52, s41, s47
	s_cselect_b32 s55, s8, s54
	s_cselect_b32 s54, s9, s53
	s_cselect_b32 s53, s37, s67
	v_lshl_add_u64 v[196:197], s[50:51], 0, v[170:171]
	s_add_i32 m0, s18, 0xc000
	ds_read_b128 v[178:181], v213
	ds_read_b128 v[184:187], v213 offset:1024
	ds_read_b128 v[190:193], v213 offset:2048
	ds_read_b128 v[200:203], v213 offset:3072
	ds_read_b128 v[206:209], v213 offset:4096
	ds_read_b128 v[214:217], v213 offset:5120
	ds_read_b128 v[220:223], v213 offset:6144
	ds_read_b128 v[226:229], v213 offset:7168
	global_load_lds_dwordx4 v[196:197], off
	v_lshl_add_u64 v[196:197], s[50:51], 0, v[172:173]
	s_add_i32 m0, s18, 0xe000
	s_nop 0
	global_load_lds_dwordx4 v[196:197], off
	s_waitcnt vmcnt(8)
	s_waitcnt lgkmcnt(0)
	s_barrier
	s_setprio 1
	v_mfma_f32_16x16x32_bf16 v[124:127], v[128:131], v[178:181], v[124:127]
	v_mfma_f32_16x16x32_bf16 v[120:123], v[136:139], v[178:181], v[120:123]
	v_mfma_f32_16x16x32_bf16 v[108:111], v[128:131], v[190:193], v[108:111]
	v_mfma_f32_16x16x32_bf16 v[104:107], v[136:139], v[190:193], v[104:107]
	v_mfma_f32_16x16x32_bf16 v[92:95], v[128:131], v[206:209], v[92:95]
	v_mfma_f32_16x16x32_bf16 v[88:91], v[136:139], v[206:209], v[88:91]
	v_mfma_f32_16x16x32_bf16 v[76:79], v[128:131], v[220:223], v[76:79]
	v_mfma_f32_16x16x32_bf16 v[72:75], v[136:139], v[220:223], v[72:75]
	v_mfma_f32_16x16x32_bf16 v[124:127], v[132:135], v[184:187], v[124:127]
	v_mfma_f32_16x16x32_bf16 v[120:123], v[140:143], v[184:187], v[120:123]
	v_mfma_f32_16x16x32_bf16 v[108:111], v[132:135], v[200:203], v[108:111]
	v_mfma_f32_16x16x32_bf16 v[104:107], v[140:143], v[200:203], v[104:107]
	v_mfma_f32_16x16x32_bf16 v[92:95], v[132:135], v[214:217], v[92:95]
	v_mfma_f32_16x16x32_bf16 v[88:91], v[140:143], v[214:217], v[88:91]
	v_mfma_f32_16x16x32_bf16 v[76:79], v[132:135], v[226:229], v[76:79]
	v_mfma_f32_16x16x32_bf16 v[72:75], v[140:143], v[226:229], v[72:75]
	v_mfma_f32_16x16x32_bf16 v[116:119], v[144:147], v[178:181], v[116:119]
	v_mfma_f32_16x16x32_bf16 v[112:115], v[152:155], v[178:181], v[112:115]
	v_mfma_f32_16x16x32_bf16 v[100:103], v[144:147], v[190:193], v[100:103]
	v_mfma_f32_16x16x32_bf16 v[96:99], v[152:155], v[190:193], v[96:99]
	v_mfma_f32_16x16x32_bf16 v[84:87], v[144:147], v[206:209], v[84:87]
	v_mfma_f32_16x16x32_bf16 v[80:83], v[152:155], v[206:209], v[80:83]
	v_mfma_f32_16x16x32_bf16 v[68:71], v[144:147], v[220:223], v[68:71]
	v_mfma_f32_16x16x32_bf16 v[64:67], v[152:155], v[220:223], v[64:67]
	v_mfma_f32_16x16x32_bf16 v[116:119], v[148:151], v[184:187], v[116:119]
	v_mfma_f32_16x16x32_bf16 v[112:115], v[156:159], v[184:187], v[112:115]
	v_mfma_f32_16x16x32_bf16 v[100:103], v[148:151], v[200:203], v[100:103]
	v_mfma_f32_16x16x32_bf16 v[96:99], v[156:159], v[200:203], v[96:99]
	v_mfma_f32_16x16x32_bf16 v[84:87], v[148:151], v[214:217], v[84:87]
	v_mfma_f32_16x16x32_bf16 v[80:83], v[156:159], v[214:217], v[80:83]
	v_mfma_f32_16x16x32_bf16 v[68:71], v[148:151], v[226:229], v[68:71]
	v_mfma_f32_16x16x32_bf16 v[64:67], v[156:159], v[226:229], v[64:67]
	s_setprio 0
	s_barrier
	s_add_i32 s69, s65, s17
	v_lshl_add_u64 v[196:197], s[52:53], 0, v[162:163]
	s_mov_b32 m0, s69
	ds_read_b128 v[178:181], v213 offset:16384
	ds_read_b128 v[184:187], v213 offset:17408
	ds_read_b128 v[190:193], v213 offset:18432
	ds_read_b128 v[200:203], v213 offset:19456
	ds_read_b128 v[206:209], v213 offset:20480
	ds_read_b128 v[214:217], v213 offset:21504
	ds_read_b128 v[220:223], v213 offset:22528
	ds_read_b128 v[226:229], v213 offset:23552
	global_load_lds_dwordx4 v[196:197], off
	s_add_i32 m0, s69, 0x2000
	s_add_u32 s70, s52, 0x40000
	v_lshl_add_u64 v[210:211], s[52:53], 0, v[166:167]
	s_addc_u32 s71, s53, 0
	s_add_i32 s69, s66, s17
	global_load_lds_dwordx4 v[210:211], off
	v_lshl_add_u64 v[230:231], s[70:71], 0, v[162:163]
	s_mov_b32 m0, s69
	v_lshl_add_u64 v[232:233], s[54:55], 0, v[164:165]
	global_load_lds_dwordx4 v[230:231], off
	v_lshl_add_u64 v[230:231], s[70:71], 0, v[166:167]
	s_add_i32 m0, s69, 0x2000
	s_nop 0
	global_load_lds_dwordx4 v[230:231], off
	v_lshl_add_u64 v[230:231], s[54:55], 0, v[160:161]
	s_mov_b32 m0, s18
	s_nop 0
	global_load_lds_dwordx4 v[230:231], off
	s_mov_b32 m0, s19
	s_nop 0
	global_load_lds_dwordx4 v[232:233], off
	s_waitcnt vmcnt(8)
	s_waitcnt lgkmcnt(0)
	s_barrier
; #define PG8_STAGE(bufoff, gbase, voff) do { _Pragma("unroll") for (int _i = 0; _i < 2; ++_i) \
;         __builtin_amdgcn_global_load_lds((const unsigned*)((const char*)(gbase) + (voff)[_i]), (PG8_LAS unsigned*)(lds + (bufoff) + ldsw + _i * 8192), 16, 0, 0); } while (0)
; #define PG8_LDA(dst, b, h) do { _Pragma("unroll") for (int m = 0; m < 4; ++m) _Pragma("unroll") for (int k = 0; k < 2; ++k) dst[m][k] = *(const PG8_LAS bf16x8*)(lds + PG8_SA(b, h) + aoff + m * 2048 + k * 1024); } while (0)
; #define PG8_LDB(dst, b, h) do { _Pragma("unroll") for (int n = 0; n < 2; ++n) _Pragma("unroll") for (int k = 0; k < 2; ++k) dst[n][k] = *(const PG8_LAS bf16x8*)(lds + PG8_SB(b, h) + boff + n * 2048 + k * 1024); } while (0)
; #define PG8_MMA(ai, bj, At, Bt) do { __builtin_amdgcn_s_setprio(1); _Pragma("unroll") for (int m = 0; m < 4; ++m) _Pragma("unroll") for (int n = 0; n < 2; ++n) _Pragma("unroll") for (int k = 0; k < 2; ++k) \
;         acc[ai][bj][m][n] = __builtin_amdgcn_mfma_f32_16x16x32_bf16(Bt[n][k], At[m][k], acc[ai][bj][m][n], 0, 0, 0); __builtin_amdgcn_s_setprio(0); } while (0)
; #define PG8_WAIT_V(n) asm volatile("s_waitcnt vmcnt(" #n ")" ::: "memory")
; #define PG8_WAIT_L(n) asm volatile("s_waitcnt lgkmcnt(" #n ")" ::: "memory")
; #define PG8_BAR __builtin_amdgcn_s_barrier()
; #define PG8_SCHED __builtin_amdgcn_sched_barrier(0)
; template <class Epi, class Sched, bool ALIGN_EPI = false, bool SP2 = false>
; __device__ __forceinline__ void gemm_phase(PG8_LAS unsigned char* lds, const Gemm g, const Sched& S, const Epi& E) {
;     ...
;             PG8_WAIT_V(8); PG8_WAIT_L(0); PG8_BAR; PG8_MMA(1, 0, At, B0); PG8_MMA(1, 1, At, B1); PG8_BAR; PG8_SCHED;
;             PG8_LDB(B0, 1, 0); PG8_LDB(B1, 1, 1); PG8_SCHED; PG8_LDA(At, 1, 0); PG8_STAGE(PG8_SA(0, 1), a2 + hstepA, voffA);
;             PG8_WAIT_V(8); PG8_WAIT_L(0); PG8_BAR; PG8_MMA(0, 0, At, B0); PG8_MMA(0, 1, At, B1); PG8_BAR; PG8_SCHED;
	s_setprio 1
	v_mfma_f32_16x16x32_bf16 v[60:63], v[128:131], v[178:181], v[60:63]
	v_mfma_f32_16x16x32_bf16 v[56:59], v[136:139], v[178:181], v[56:59]
	v_mfma_f32_16x16x32_bf16 v[44:47], v[128:131], v[190:193], v[44:47]
	v_mfma_f32_16x16x32_bf16 v[40:43], v[136:139], v[190:193], v[40:43]
	v_mfma_f32_16x16x32_bf16 v[28:31], v[128:131], v[206:209], v[28:31]
	v_mfma_f32_16x16x32_bf16 v[24:27], v[136:139], v[206:209], v[24:27]
	v_mfma_f32_16x16x32_bf16 v[12:15], v[128:131], v[220:223], v[12:15]
	v_mfma_f32_16x16x32_bf16 v[8:11], v[136:139], v[220:223], v[8:11]
	v_mfma_f32_16x16x32_bf16 v[60:63], v[132:135], v[184:187], v[60:63]
	v_mfma_f32_16x16x32_bf16 v[56:59], v[140:143], v[184:187], v[56:59]
	v_mfma_f32_16x16x32_bf16 v[44:47], v[132:135], v[200:203], v[44:47]
	v_mfma_f32_16x16x32_bf16 v[40:43], v[140:143], v[200:203], v[40:43]
	v_mfma_f32_16x16x32_bf16 v[28:31], v[132:135], v[214:217], v[28:31]
	v_mfma_f32_16x16x32_bf16 v[24:27], v[140:143], v[214:217], v[24:27]
	v_mfma_f32_16x16x32_bf16 v[12:15], v[132:135], v[226:229], v[12:15]
	v_mfma_f32_16x16x32_bf16 v[8:11], v[140:143], v[226:229], v[8:11]
	v_mfma_f32_16x16x32_bf16 v[52:55], v[144:147], v[178:181], v[52:55]
	v_mfma_f32_16x16x32_bf16 v[48:51], v[152:155], v[178:181], v[48:51]
	v_mfma_f32_16x16x32_bf16 v[36:39], v[144:147], v[190:193], v[36:39]
	v_mfma_f32_16x16x32_bf16 v[32:35], v[152:155], v[190:193], v[32:35]
	v_mfma_f32_16x16x32_bf16 v[20:23], v[144:147], v[206:209], v[20:23]
	v_mfma_f32_16x16x32_bf16 v[16:19], v[152:155], v[206:209], v[16:19]
	v_mfma_f32_16x16x32_bf16 v[4:7], v[144:147], v[220:223], v[4:7]
	v_mfma_f32_16x16x32_bf16 v[0:3], v[152:155], v[220:223], v[0:3]
	v_mfma_f32_16x16x32_bf16 v[52:55], v[148:151], v[184:187], v[52:55]
	v_mfma_f32_16x16x32_bf16 v[48:51], v[156:159], v[184:187], v[48:51]
	v_mfma_f32_16x16x32_bf16 v[36:39], v[148:151], v[200:203], v[36:39]
	v_mfma_f32_16x16x32_bf16 v[32:35], v[156:159], v[200:203], v[32:35]
	v_mfma_f32_16x16x32_bf16 v[20:23], v[148:151], v[214:217], v[20:23]
	v_mfma_f32_16x16x32_bf16 v[16:19], v[156:159], v[214:217], v[16:19]
	v_mfma_f32_16x16x32_bf16 v[4:7], v[148:151], v[226:229], v[4:7]
	v_mfma_f32_16x16x32_bf16 v[0:3], v[156:159], v[226:229], v[0:3]
	s_setprio 0
	s_barrier
	s_add_i32 s69, 0, 0x18000
	s_add_i32 s70, 0, 0x1c000
	v_add_u32_e32 v140, s69, v195
	v_add_u32_e32 v156, s70, v195
	ds_read_b128 v[128:131], v140
	ds_read_b128 v[132:135], v140 offset:1024
	ds_read_b128 v[136:139], v140 offset:2048
	ds_read_b128 v[140:143], v140 offset:3072
	ds_read_b128 v[144:147], v156
	ds_read_b128 v[148:151], v156 offset:1024
	ds_read_b128 v[152:155], v156 offset:2048
	ds_read_b128 v[156:159], v156 offset:3072
	s_add_u32 s54, s54, 0x40000
	s_addc_u32 s55, s55, 0
	s_mov_b32 m0, s20
	v_lshl_add_u64 v[234:235], s[54:55], 0, v[160:161]
	ds_read_b128 v[178:181], v213 offset:32768
	ds_read_b128 v[184:187], v213 offset:33792
	ds_read_b128 v[190:193], v213 offset:34816
	ds_read_b128 v[200:203], v213 offset:35840
	ds_read_b128 v[206:209], v213 offset:36864
	ds_read_b128 v[214:217], v213 offset:37888
	ds_read_b128 v[220:223], v213 offset:38912
	ds_read_b128 v[226:229], v213 offset:39936
	global_load_lds_dwordx4 v[234:235], off
	v_lshl_add_u64 v[234:235], s[54:55], 0, v[164:165]
	s_mov_b32 m0, s21
	s_nop 0
	global_load_lds_dwordx4 v[234:235], off
	s_waitcnt vmcnt(8)
	s_waitcnt lgkmcnt(0)
	s_barrier
	s_setprio 1
	v_mfma_f32_16x16x32_bf16 v[124:127], v[128:131], v[178:181], v[124:127]
	v_mfma_f32_16x16x32_bf16 v[120:123], v[136:139], v[178:181], v[120:123]
	v_mfma_f32_16x16x32_bf16 v[108:111], v[128:131], v[190:193], v[108:111]
	v_mfma_f32_16x16x32_bf16 v[104:107], v[136:139], v[190:193], v[104:107]
	v_mfma_f32_16x16x32_bf16 v[92:95], v[128:131], v[206:209], v[92:95]
	v_mfma_f32_16x16x32_bf16 v[88:91], v[136:139], v[206:209], v[88:91]
	v_mfma_f32_16x16x32_bf16 v[76:79], v[128:131], v[220:223], v[76:79]
	v_mfma_f32_16x16x32_bf16 v[72:75], v[136:139], v[220:223], v[72:75]
	v_mfma_f32_16x16x32_bf16 v[124:127], v[132:135], v[184:187], v[124:127]
	v_mfma_f32_16x16x32_bf16 v[120:123], v[140:143], v[184:187], v[120:123]
	v_mfma_f32_16x16x32_bf16 v[108:111], v[132:135], v[200:203], v[108:111]
	v_mfma_f32_16x16x32_bf16 v[104:107], v[140:143], v[200:203], v[104:107]
	v_mfma_f32_16x16x32_bf16 v[92:95], v[132:135], v[214:217], v[92:95]
	v_mfma_f32_16x16x32_bf16 v[88:91], v[140:143], v[214:217], v[88:91]
	v_mfma_f32_16x16x32_bf16 v[76:79], v[132:135], v[226:229], v[76:79]
	v_mfma_f32_16x16x32_bf16 v[72:75], v[140:143], v[226:229], v[72:75]
	v_mfma_f32_16x16x32_bf16 v[116:119], v[144:147], v[178:181], v[116:119]
	v_mfma_f32_16x16x32_bf16 v[112:115], v[152:155], v[178:181], v[112:115]
	v_mfma_f32_16x16x32_bf16 v[100:103], v[144:147], v[190:193], v[100:103]
	v_mfma_f32_16x16x32_bf16 v[96:99], v[152:155], v[190:193], v[96:99]
	v_mfma_f32_16x16x32_bf16 v[84:87], v[144:147], v[206:209], v[84:87]
	v_mfma_f32_16x16x32_bf16 v[80:83], v[152:155], v[206:209], v[80:83]
	v_mfma_f32_16x16x32_bf16 v[68:71], v[144:147], v[220:223], v[68:71]
	v_mfma_f32_16x16x32_bf16 v[64:67], v[152:155], v[220:223], v[64:67]
	v_mfma_f32_16x16x32_bf16 v[116:119], v[148:151], v[184:187], v[116:119]
	v_mfma_f32_16x16x32_bf16 v[112:115], v[156:159], v[184:187], v[112:115]
	v_mfma_f32_16x16x32_bf16 v[100:103], v[148:151], v[200:203], v[100:103]
	v_mfma_f32_16x16x32_bf16 v[96:99], v[156:159], v[200:203], v[96:99]
	v_mfma_f32_16x16x32_bf16 v[84:87], v[148:151], v[214:217], v[84:87]
	v_mfma_f32_16x16x32_bf16 v[80:83], v[156:159], v[214:217], v[80:83]
	v_mfma_f32_16x16x32_bf16 v[68:71], v[148:151], v[226:229], v[68:71]
	v_mfma_f32_16x16x32_bf16 v[64:67], v[156:159], v[226:229], v[64:67]
	s_setprio 0
	s_barrier
; #define PG8_STAGE(bufoff, gbase, voff) do { _Pragma("unroll") for (int _i = 0; _i < 2; ++_i) \
;         __builtin_amdgcn_global_load_lds((const unsigned*)((const char*)(gbase) + (voff)[_i]), (PG8_LAS unsigned*)(lds + (bufoff) + ldsw + _i * 8192), 16, 0, 0); } while (0)
; #define PG8_LDA(dst, b, h) do { _Pragma("unroll") for (int m = 0; m < 4; ++m) _Pragma("unroll") for (int k = 0; k < 2; ++k) dst[m][k] = *(const PG8_LAS bf16x8*)(lds + PG8_SA(b, h) + aoff + m * 2048 + k * 1024); } while (0)
; #define PG8_MMA(ai, bj, At, Bt) do { __builtin_amdgcn_s_setprio(1); _Pragma("unroll") for (int m = 0; m < 4; ++m) _Pragma("unroll") for (int n = 0; n < 2; ++n) _Pragma("unroll") for (int k = 0; k < 2; ++k) \
;         acc[ai][bj][m][n] = __builtin_amdgcn_mfma_f32_16x16x32_bf16(Bt[n][k], At[m][k], acc[ai][bj][m][n], 0, 0, 0); __builtin_amdgcn_s_setprio(0); } while (0)
; #define PG8_WAIT_V(n) asm volatile("s_waitcnt vmcnt(" #n ")" ::: "memory")
; #define PG8_WAIT_L(n) asm volatile("s_waitcnt lgkmcnt(" #n ")" ::: "memory")
; #define PG8_BAR __builtin_amdgcn_s_barrier()
; #define PG8_SCHED __builtin_amdgcn_sched_barrier(0)
; template <class Epi, class Sched, bool ALIGN_EPI = false, bool SP2 = false>
; __device__ __forceinline__ void gemm_phase(PG8_LAS unsigned char* lds, const Gemm g, const Sched& S, const Epi& E) {
;     ...
;             PG8_LDA(At, 1, 1); PG8_STAGE(PG8_SB(1, 0), b3, voffB); PG8_STAGE(PG8_SB(1, 1), b3 + hstepB, voffB); PG8_STAGE(PG8_SA(1, 0), a3, voffA);
;             PG8_WAIT_V(8); PG8_WAIT_L(0); PG8_BAR; PG8_MMA(1, 0, At, B0); PG8_MMA(1, 1, At, B1); PG8_BAR; PG8_SCHED;
	s_add_i32 s54, s69, s17
	v_lshl_add_u64 v[196:197], v[196:197], 0, s[26:27]
	s_mov_b32 m0, s54
	ds_read_b128 v[178:181], v213 offset:49152
	ds_read_b128 v[184:187], v213 offset:50176
	ds_read_b128 v[190:193], v213 offset:51200
	ds_read_b128 v[200:203], v213 offset:52224
	ds_read_b128 v[206:209], v213 offset:53248
	ds_read_b128 v[214:217], v213 offset:54272
	ds_read_b128 v[220:223], v213 offset:55296
	ds_read_b128 v[226:229], v213 offset:56320
	global_load_lds_dwordx4 v[196:197], off
	s_add_i32 m0, s54, 0x2000
	s_add_u32 s52, s52, 0x40080
	v_lshl_add_u64 v[196:197], v[210:211], 0, s[26:27]
	s_addc_u32 s53, s53, 0
	s_add_i32 s54, s70, s17
	global_load_lds_dwordx4 v[196:197], off
	v_lshl_add_u64 v[196:197], s[52:53], 0, v[162:163]
	s_mov_b32 m0, s54
	s_nop 0
	global_load_lds_dwordx4 v[196:197], off
	v_lshl_add_u64 v[196:197], s[52:53], 0, v[166:167]
	s_add_i32 m0, s54, 0x2000
	s_nop 0
	global_load_lds_dwordx4 v[196:197], off
	v_lshl_add_u64 v[196:197], v[230:231], 0, s[26:27]
	s_mov_b32 m0, s59
	s_nop 0
	global_load_lds_dwordx4 v[196:197], off
	v_lshl_add_u64 v[196:197], v[232:233], 0, s[26:27]
	s_mov_b32 m0, s60
	s_nop 0
	global_load_lds_dwordx4 v[196:197], off
	s_waitcnt vmcnt(8)
	s_waitcnt lgkmcnt(0)
	s_barrier
	s_setprio 1
	v_mfma_f32_16x16x32_bf16 v[60:63], v[128:131], v[178:181], v[60:63]
	v_mfma_f32_16x16x32_bf16 v[56:59], v[136:139], v[178:181], v[56:59]
	v_mfma_f32_16x16x32_bf16 v[44:47], v[128:131], v[190:193], v[44:47]
	v_mfma_f32_16x16x32_bf16 v[40:43], v[136:139], v[190:193], v[40:43]
	v_mfma_f32_16x16x32_bf16 v[28:31], v[128:131], v[206:209], v[28:31]
	v_mfma_f32_16x16x32_bf16 v[24:27], v[136:139], v[206:209], v[24:27]
	v_mfma_f32_16x16x32_bf16 v[12:15], v[128:131], v[220:223], v[12:15]
	v_mfma_f32_16x16x32_bf16 v[8:11], v[136:139], v[220:223], v[8:11]
	v_mfma_f32_16x16x32_bf16 v[60:63], v[132:135], v[184:187], v[60:63]
	v_mfma_f32_16x16x32_bf16 v[56:59], v[140:143], v[184:187], v[56:59]
	v_mfma_f32_16x16x32_bf16 v[44:47], v[132:135], v[200:203], v[44:47]
	v_mfma_f32_16x16x32_bf16 v[40:43], v[140:143], v[200:203], v[40:43]
	v_mfma_f32_16x16x32_bf16 v[28:31], v[132:135], v[214:217], v[28:31]
	v_mfma_f32_16x16x32_bf16 v[24:27], v[140:143], v[214:217], v[24:27]
	v_mfma_f32_16x16x32_bf16 v[12:15], v[132:135], v[226:229], v[12:15]
	v_mfma_f32_16x16x32_bf16 v[8:11], v[140:143], v[226:229], v[8:11]
	v_mfma_f32_16x16x32_bf16 v[52:55], v[144:147], v[178:181], v[52:55]
	v_mfma_f32_16x16x32_bf16 v[48:51], v[152:155], v[178:181], v[48:51]
	v_mfma_f32_16x16x32_bf16 v[36:39], v[144:147], v[190:193], v[36:39]
	v_mfma_f32_16x16x32_bf16 v[32:35], v[152:155], v[190:193], v[32:35]
	v_mfma_f32_16x16x32_bf16 v[20:23], v[144:147], v[206:209], v[20:23]
	v_mfma_f32_16x16x32_bf16 v[16:19], v[152:155], v[206:209], v[16:19]
	v_mfma_f32_16x16x32_bf16 v[4:7], v[144:147], v[220:223], v[4:7]
	v_mfma_f32_16x16x32_bf16 v[0:3], v[152:155], v[220:223], v[0:3]
	v_mfma_f32_16x16x32_bf16 v[52:55], v[148:151], v[184:187], v[52:55]
	v_mfma_f32_16x16x32_bf16 v[48:51], v[156:159], v[184:187], v[48:51]
	v_mfma_f32_16x16x32_bf16 v[36:39], v[148:151], v[200:203], v[36:39]
	v_mfma_f32_16x16x32_bf16 v[32:35], v[156:159], v[200:203], v[32:35]
	v_mfma_f32_16x16x32_bf16 v[20:23], v[148:151], v[214:217], v[20:23]
	v_mfma_f32_16x16x32_bf16 v[16:19], v[156:159], v[214:217], v[16:19]
	v_mfma_f32_16x16x32_bf16 v[4:7], v[148:151], v[226:229], v[4:7]
	v_mfma_f32_16x16x32_bf16 v[0:3], v[156:159], v[226:229], v[0:3]
	s_setprio 0
	s_barrier
	s_add_u32 s50, s50, 0x100
	s_addc_u32 s51, s51, 0
	s_add_u32 s47, s47, 0x100
	s_addc_u32 s67, s67, 0
	s_cmp_ge_i32 s68, s35
	s_mov_b32 s52, s68
	s_cbranch_scc0 .LBB0_433

; #define PG8_STAGE(bufoff, gbase, voff) do { _Pragma("unroll") for (int _i = 0; _i < 2; ++_i) \
;         __builtin_amdgcn_global_load_lds((const unsigned*)((const char*)(gbase) + (voff)[_i]), (PG8_LAS unsigned*)(lds + (bufoff) + ldsw + _i * 8192), 16, 0, 0); } while (0)
; #define PG8_LDA(dst, b, h) do { _Pragma("unroll") for (int m = 0; m < 4; ++m) _Pragma("unroll") for (int k = 0; k < 2; ++k) dst[m][k] = *(const PG8_LAS bf16x8*)(lds + PG8_SA(b, h) + aoff + m * 2048 + k * 1024); } while (0)
; #define PG8_LDB(dst, b, h) do { _Pragma("unroll") for (int n = 0; n < 2; ++n) _Pragma("unroll") for (int k = 0; k < 2; ++k) dst[n][k] = *(const PG8_LAS bf16x8*)(lds + PG8_SB(b, h) + boff + n * 2048 + k * 1024); } while (0)
; #define PG8_MMA(ai, bj, At, Bt) do { __builtin_amdgcn_s_setprio(1); _Pragma("unroll") for (int m = 0; m < 4; ++m) _Pragma("unroll") for (int n = 0; n < 2; ++n) _Pragma("unroll") for (int k = 0; k < 2; ++k) \
;         acc[ai][bj][m][n] = __builtin_amdgcn_mfma_f32_16x16x32_bf16(Bt[n][k], At[m][k], acc[ai][bj][m][n], 0, 0, 0); __builtin_amdgcn_s_setprio(0); } while (0)
; #define PG8_WAIT_V(n) asm volatile("s_waitcnt vmcnt(" #n ")" ::: "memory")
; #define PG8_WAIT_L(n) asm volatile("s_waitcnt lgkmcnt(" #n ")" ::: "memory")
; template <class Epi, class Sched, bool ALIGN_EPI = false, bool SP2 = false>
; __device__ __forceinline__ void gemm_phase(PG8_LAS unsigned char* lds, const Gemm g, const Sched& S, const Epi& E) {
;     ...
;             const bool last = (t == nt - 2);
;             const char* a1 = cA + (long)(t + 1) * kstepA;
;             const char* a2 = last ? nA : cA + (long)(t + 2) * kstepA; const char* b2 = last ? nB : cB + (long)(t + 2) * kstep;
;             const char* a3 = a2 + kstepA; const char* b3 = b2 + kstep;
;             if (last && has_next) S.a_ready(nxt);
;             if constexpr (SP2) {
;             PG8_LDB(B0, 0, 0); PG8_LDB(B1, 0, 1); PG8_SCHED; PG8_LDA(At, 0, 0); PG8_STAGE(PG8_SA(1, 1), a1 + hstepA, voffA);
;             PG8_WAIT_V(8); PG8_WAIT_L(0); PG8_BAR; PG8_MMA(0, 0, At, B0); PG8_MMA(0, 1, At, B1); PG8_BAR; PG8_SCHED;
;             PG8_LDA(At, 0, 1); PG8_STAGE(PG8_SB(0, 0), b2, voffB); PG8_STAGE(PG8_SB(0, 1), b2 + hstepB, voffB); PG8_STAGE(PG8_SA(0, 0), a2, voffA);
;             PG8_WAIT_V(8); PG8_WAIT_L(0); PG8_BAR; PG8_MMA(1, 0, At, B0); PG8_MMA(1, 1, At, B1); PG8_BAR; PG8_SCHED;
.LBB0_1172:
	ds_read_b128 v[128:131], v183
	ds_read_b128 v[132:135], v183 offset:1024
	ds_read_b128 v[136:139], v183 offset:2048
	ds_read_b128 v[140:143], v183 offset:3072
	ds_read_b128 v[144:147], v187
	ds_read_b128 v[148:151], v187 offset:1024
	ds_read_b128 v[152:155], v187 offset:2048
	ds_read_b128 v[196:199], v187 offset:3072
	s_add_i32 s69, s52, 2
	s_add_u32 s53, s50, 0xfffc0080
	s_addc_u32 s54, s51, -1
	s_cmp_eq_u32 s20, s52
	s_cselect_b32 s52, s43, s45
	s_cselect_b32 s55, s8, s54
	s_cselect_b32 s54, s9, s53
	s_cselect_b32 s53, s11, s49
	v_lshl_add_u64 v[180:181], s[50:51], 0, v[166:167]
	s_add_i32 m0, s33, 0xc000
	ds_read_b128 v[200:203], v191
	ds_read_b128 v[204:207], v191 offset:1024
	ds_read_b128 v[208:211], v191 offset:2048
	ds_read_b128 v[212:215], v191 offset:3072
	ds_read_b128 v[216:219], v191 offset:4096
	ds_read_b128 v[220:223], v191 offset:5120
	ds_read_b128 v[224:227], v191 offset:6144
	ds_read_b128 v[228:231], v191 offset:7168
	global_load_lds_dwordx4 v[180:181], off
	v_lshl_add_u64 v[180:181], s[50:51], 0, v[168:169]
	s_add_i32 m0, s33, 0xe000
	s_nop 0
	global_load_lds_dwordx4 v[180:181], off
	s_waitcnt vmcnt(8)
	s_waitcnt lgkmcnt(0)
	s_barrier
	s_setprio 1
	v_mfma_f32_16x16x32_bf16 v[124:127], v[128:131], v[200:203], v[124:127]
	v_mfma_f32_16x16x32_bf16 v[120:123], v[136:139], v[200:203], v[120:123]
	v_mfma_f32_16x16x32_bf16 v[116:119], v[128:131], v[208:211], v[116:119]
	v_mfma_f32_16x16x32_bf16 v[112:115], v[136:139], v[208:211], v[112:115]
	v_mfma_f32_16x16x32_bf16 v[108:111], v[128:131], v[216:219], v[108:111]
	v_mfma_f32_16x16x32_bf16 v[104:107], v[136:139], v[216:219], v[104:107]
	v_mfma_f32_16x16x32_bf16 v[100:103], v[128:131], v[224:227], v[100:103]
	v_mfma_f32_16x16x32_bf16 v[96:99], v[136:139], v[224:227], v[96:99]
	v_mfma_f32_16x16x32_bf16 v[124:127], v[132:135], v[204:207], v[124:127]
	v_mfma_f32_16x16x32_bf16 v[120:123], v[140:143], v[204:207], v[120:123]
	v_mfma_f32_16x16x32_bf16 v[116:119], v[132:135], v[212:215], v[116:119]
	v_mfma_f32_16x16x32_bf16 v[112:115], v[140:143], v[212:215], v[112:115]
	v_mfma_f32_16x16x32_bf16 v[108:111], v[132:135], v[220:223], v[108:111]
	v_mfma_f32_16x16x32_bf16 v[104:107], v[140:143], v[220:223], v[104:107]
	v_mfma_f32_16x16x32_bf16 v[100:103], v[132:135], v[228:231], v[100:103]
	v_mfma_f32_16x16x32_bf16 v[96:99], v[140:143], v[228:231], v[96:99]
	v_mfma_f32_16x16x32_bf16 v[60:63], v[144:147], v[200:203], v[60:63]
	v_mfma_f32_16x16x32_bf16 v[56:59], v[152:155], v[200:203], v[56:59]
	v_mfma_f32_16x16x32_bf16 v[52:55], v[144:147], v[208:211], v[52:55]
	v_mfma_f32_16x16x32_bf16 v[48:51], v[152:155], v[208:211], v[48:51]
	v_mfma_f32_16x16x32_bf16 v[44:47], v[144:147], v[216:219], v[44:47]
	v_mfma_f32_16x16x32_bf16 v[40:43], v[152:155], v[216:219], v[40:43]
	v_mfma_f32_16x16x32_bf16 v[36:39], v[144:147], v[224:227], v[36:39]
	v_mfma_f32_16x16x32_bf16 v[32:35], v[152:155], v[224:227], v[32:35]
	v_mfma_f32_16x16x32_bf16 v[60:63], v[148:151], v[204:207], v[60:63]
	v_mfma_f32_16x16x32_bf16 v[56:59], v[196:199], v[204:207], v[56:59]
	v_mfma_f32_16x16x32_bf16 v[52:55], v[148:151], v[212:215], v[52:55]
	v_mfma_f32_16x16x32_bf16 v[48:51], v[196:199], v[212:215], v[48:51]
	v_mfma_f32_16x16x32_bf16 v[44:47], v[148:151], v[220:223], v[44:47]
	v_mfma_f32_16x16x32_bf16 v[40:43], v[196:199], v[220:223], v[40:43]
	v_mfma_f32_16x16x32_bf16 v[36:39], v[148:151], v[228:231], v[36:39]
	v_mfma_f32_16x16x32_bf16 v[32:35], v[196:199], v[228:231], v[32:35]
	s_setprio 0
	s_barrier
	s_add_i32 s70, s67, s19
	v_lshl_add_u64 v[180:181], s[52:53], 0, v[158:159]
	s_mov_b32 m0, s70
	ds_read_b128 v[200:203], v191 offset:16384
	ds_read_b128 v[204:207], v191 offset:17408
	ds_read_b128 v[208:211], v191 offset:18432
	ds_read_b128 v[212:215], v191 offset:19456
	ds_read_b128 v[216:219], v191 offset:20480
	ds_read_b128 v[220:223], v191 offset:21504
	ds_read_b128 v[224:227], v191 offset:22528
	ds_read_b128 v[228:231], v191 offset:23552
	global_load_lds_dwordx4 v[180:181], off
	s_add_i32 m0, s70, 0x2000
	s_add_u32 s70, s52, 0x40000
	v_lshl_add_u64 v[184:185], s[52:53], 0, v[162:163]
	s_addc_u32 s71, s53, 0
	s_add_i32 s72, s68, s19
	global_load_lds_dwordx4 v[184:185], off
	v_lshl_add_u64 v[188:189], s[70:71], 0, v[158:159]
	s_mov_b32 m0, s72
	v_lshl_add_u64 v[192:193], s[54:55], 0, v[160:161]
	global_load_lds_dwordx4 v[188:189], off
	v_lshl_add_u64 v[188:189], s[70:71], 0, v[162:163]
	s_add_i32 m0, s72, 0x2000
	s_nop 0
	global_load_lds_dwordx4 v[188:189], off
	v_lshl_add_u64 v[188:189], s[54:55], 0, v[156:157]
	s_mov_b32 m0, s33
	s_nop 0
	global_load_lds_dwordx4 v[188:189], off
	s_mov_b32 m0, s41
	s_nop 0
	global_load_lds_dwordx4 v[192:193], off
	s_waitcnt vmcnt(8)
	s_waitcnt lgkmcnt(0)
	s_barrier
; #define PG8_STAGE(bufoff, gbase, voff) do { _Pragma("unroll") for (int _i = 0; _i < 2; ++_i) \
;         __builtin_amdgcn_global_load_lds((const unsigned*)((const char*)(gbase) + (voff)[_i]), (PG8_LAS unsigned*)(lds + (bufoff) + ldsw + _i * 8192), 16, 0, 0); } while (0)
; #define PG8_LDA(dst, b, h) do { _Pragma("unroll") for (int m = 0; m < 4; ++m) _Pragma("unroll") for (int k = 0; k < 2; ++k) dst[m][k] = *(const PG8_LAS bf16x8*)(lds + PG8_SA(b, h) + aoff + m * 2048 + k * 1024); } while (0)
; #define PG8_LDB(dst, b, h) do { _Pragma("unroll") for (int n = 0; n < 2; ++n) _Pragma("unroll") for (int k = 0; k < 2; ++k) dst[n][k] = *(const PG8_LAS bf16x8*)(lds + PG8_SB(b, h) + boff + n * 2048 + k * 1024); } while (0)
; #define PG8_MMA(ai, bj, At, Bt) do { __builtin_amdgcn_s_setprio(1); _Pragma("unroll") for (int m = 0; m < 4; ++m) _Pragma("unroll") for (int n = 0; n < 2; ++n) _Pragma("unroll") for (int k = 0; k < 2; ++k) \
;         acc[ai][bj][m][n] = __builtin_amdgcn_mfma_f32_16x16x32_bf16(Bt[n][k], At[m][k], acc[ai][bj][m][n], 0, 0, 0); __builtin_amdgcn_s_setprio(0); } while (0)
; #define PG8_WAIT_V(n) asm volatile("s_waitcnt vmcnt(" #n ")" ::: "memory")
; #define PG8_WAIT_L(n) asm volatile("s_waitcnt lgkmcnt(" #n ")" ::: "memory")
; #define PG8_BAR __builtin_amdgcn_s_barrier()
; #define PG8_SCHED __builtin_amdgcn_sched_barrier(0)
; template <class Epi, class Sched, bool ALIGN_EPI = false, bool SP2 = false>
; __device__ __forceinline__ void gemm_phase(PG8_LAS unsigned char* lds, const Gemm g, const Sched& S, const Epi& E) {
;     ...
;             PG8_WAIT_V(8); PG8_WAIT_L(0); PG8_BAR; PG8_MMA(1, 0, At, B0); PG8_MMA(1, 1, At, B1); PG8_BAR; PG8_SCHED;
;             PG8_LDB(B0, 1, 0); PG8_LDB(B1, 1, 1); PG8_SCHED; PG8_LDA(At, 1, 0); PG8_STAGE(PG8_SA(0, 1), a2 + hstepA, voffA);
;             PG8_WAIT_V(8); PG8_WAIT_L(0); PG8_BAR; PG8_MMA(0, 0, At, B0); PG8_MMA(0, 1, At, B1); PG8_BAR; PG8_SCHED;
	s_setprio 1
	v_mfma_f32_16x16x32_bf16 v[92:95], v[128:131], v[200:203], v[92:95]
	v_mfma_f32_16x16x32_bf16 v[88:91], v[136:139], v[200:203], v[88:91]
	v_mfma_f32_16x16x32_bf16 v[84:87], v[128:131], v[208:211], v[84:87]
	v_mfma_f32_16x16x32_bf16 v[80:83], v[136:139], v[208:211], v[80:83]
	v_mfma_f32_16x16x32_bf16 v[76:79], v[128:131], v[216:219], v[76:79]
	v_mfma_f32_16x16x32_bf16 v[72:75], v[136:139], v[216:219], v[72:75]
	v_mfma_f32_16x16x32_bf16 v[68:71], v[128:131], v[224:227], v[68:71]
	v_mfma_f32_16x16x32_bf16 v[64:67], v[136:139], v[224:227], v[64:67]
	v_mfma_f32_16x16x32_bf16 v[92:95], v[132:135], v[204:207], v[92:95]
	v_mfma_f32_16x16x32_bf16 v[88:91], v[140:143], v[204:207], v[88:91]
	v_mfma_f32_16x16x32_bf16 v[84:87], v[132:135], v[212:215], v[84:87]
	v_mfma_f32_16x16x32_bf16 v[80:83], v[140:143], v[212:215], v[80:83]
	v_mfma_f32_16x16x32_bf16 v[76:79], v[132:135], v[220:223], v[76:79]
	v_mfma_f32_16x16x32_bf16 v[72:75], v[140:143], v[220:223], v[72:75]
	v_mfma_f32_16x16x32_bf16 v[68:71], v[132:135], v[228:231], v[68:71]
	v_mfma_f32_16x16x32_bf16 v[64:67], v[140:143], v[228:231], v[64:67]
	v_mfma_f32_16x16x32_bf16 v[28:31], v[144:147], v[200:203], v[28:31]
	v_mfma_f32_16x16x32_bf16 v[24:27], v[152:155], v[200:203], v[24:27]
	v_mfma_f32_16x16x32_bf16 v[20:23], v[144:147], v[208:211], v[20:23]
	v_mfma_f32_16x16x32_bf16 v[16:19], v[152:155], v[208:211], v[16:19]
	v_mfma_f32_16x16x32_bf16 v[12:15], v[144:147], v[216:219], v[12:15]
	v_mfma_f32_16x16x32_bf16 v[8:11], v[152:155], v[216:219], v[8:11]
	v_mfma_f32_16x16x32_bf16 v[4:7], v[144:147], v[224:227], v[4:7]
	v_mfma_f32_16x16x32_bf16 v[0:3], v[152:155], v[224:227], v[0:3]
	v_mfma_f32_16x16x32_bf16 v[28:31], v[148:151], v[204:207], v[28:31]
	v_mfma_f32_16x16x32_bf16 v[24:27], v[196:199], v[204:207], v[24:27]
	v_mfma_f32_16x16x32_bf16 v[20:23], v[148:151], v[212:215], v[20:23]
	v_mfma_f32_16x16x32_bf16 v[16:19], v[196:199], v[212:215], v[16:19]
	v_mfma_f32_16x16x32_bf16 v[12:15], v[148:151], v[220:223], v[12:15]
	v_mfma_f32_16x16x32_bf16 v[8:11], v[196:199], v[220:223], v[8:11]
	v_mfma_f32_16x16x32_bf16 v[4:7], v[148:151], v[228:231], v[4:7]
	v_mfma_f32_16x16x32_bf16 v[0:3], v[196:199], v[228:231], v[0:3]
	s_setprio 0
	s_barrier
	s_add_i32 s70, 0, 0x18000
	s_add_i32 s71, 0, 0x1c000
	v_add_u32_e32 v140, s70, v179
	v_add_u32_e32 v165, s71, v179
	ds_read_b128 v[128:131], v140
	ds_read_b128 v[132:135], v140 offset:1024
	ds_read_b128 v[136:139], v140 offset:2048
	ds_read_b128 v[140:143], v140 offset:3072
	ds_read_b128 v[144:147], v165
	ds_read_b128 v[148:151], v165 offset:1024
	ds_read_b128 v[152:155], v165 offset:2048
	ds_read_b128 v[196:199], v165 offset:3072
	s_add_u32 s54, s54, 0x40000
	s_addc_u32 s55, s55, 0
	s_mov_b32 m0, s56
	v_lshl_add_u64 v[232:233], s[54:55], 0, v[156:157]
	ds_read_b128 v[200:203], v191 offset:32768
	ds_read_b128 v[204:207], v191 offset:33792
	ds_read_b128 v[208:211], v191 offset:34816
	ds_read_b128 v[212:215], v191 offset:35840
	ds_read_b128 v[216:219], v191 offset:36864
	ds_read_b128 v[220:223], v191 offset:37888
	ds_read_b128 v[224:227], v191 offset:38912
	ds_read_b128 v[228:231], v191 offset:39936
	global_load_lds_dwordx4 v[232:233], off
	v_lshl_add_u64 v[232:233], s[54:55], 0, v[160:161]
	s_mov_b32 m0, s57
	s_nop 0
	global_load_lds_dwordx4 v[232:233], off
	s_waitcnt vmcnt(8)
	s_waitcnt lgkmcnt(0)
	s_barrier
	s_setprio 1
	v_mfma_f32_16x16x32_bf16 v[124:127], v[128:131], v[200:203], v[124:127]
	v_mfma_f32_16x16x32_bf16 v[120:123], v[136:139], v[200:203], v[120:123]
	v_mfma_f32_16x16x32_bf16 v[116:119], v[128:131], v[208:211], v[116:119]
	v_mfma_f32_16x16x32_bf16 v[112:115], v[136:139], v[208:211], v[112:115]
	v_mfma_f32_16x16x32_bf16 v[108:111], v[128:131], v[216:219], v[108:111]
	v_mfma_f32_16x16x32_bf16 v[104:107], v[136:139], v[216:219], v[104:107]
	v_mfma_f32_16x16x32_bf16 v[100:103], v[128:131], v[224:227], v[100:103]
	v_mfma_f32_16x16x32_bf16 v[96:99], v[136:139], v[224:227], v[96:99]
	v_mfma_f32_16x16x32_bf16 v[124:127], v[132:135], v[204:207], v[124:127]
	v_mfma_f32_16x16x32_bf16 v[120:123], v[140:143], v[204:207], v[120:123]
	v_mfma_f32_16x16x32_bf16 v[116:119], v[132:135], v[212:215], v[116:119]
	v_mfma_f32_16x16x32_bf16 v[112:115], v[140:143], v[212:215], v[112:115]
	v_mfma_f32_16x16x32_bf16 v[108:111], v[132:135], v[220:223], v[108:111]
	v_mfma_f32_16x16x32_bf16 v[104:107], v[140:143], v[220:223], v[104:107]
	v_mfma_f32_16x16x32_bf16 v[100:103], v[132:135], v[228:231], v[100:103]
	v_mfma_f32_16x16x32_bf16 v[96:99], v[140:143], v[228:231], v[96:99]
	v_mfma_f32_16x16x32_bf16 v[60:63], v[144:147], v[200:203], v[60:63]
	v_mfma_f32_16x16x32_bf16 v[56:59], v[152:155], v[200:203], v[56:59]
	v_mfma_f32_16x16x32_bf16 v[52:55], v[144:147], v[208:211], v[52:55]
	v_mfma_f32_16x16x32_bf16 v[48:51], v[152:155], v[208:211], v[48:51]
	v_mfma_f32_16x16x32_bf16 v[44:47], v[144:147], v[216:219], v[44:47]
	v_mfma_f32_16x16x32_bf16 v[40:43], v[152:155], v[216:219], v[40:43]
	v_mfma_f32_16x16x32_bf16 v[36:39], v[144:147], v[224:227], v[36:39]
	v_mfma_f32_16x16x32_bf16 v[32:35], v[152:155], v[224:227], v[32:35]
	v_mfma_f32_16x16x32_bf16 v[60:63], v[148:151], v[204:207], v[60:63]
	v_mfma_f32_16x16x32_bf16 v[56:59], v[196:199], v[204:207], v[56:59]
	v_mfma_f32_16x16x32_bf16 v[52:55], v[148:151], v[212:215], v[52:55]
	v_mfma_f32_16x16x32_bf16 v[48:51], v[196:199], v[212:215], v[48:51]
	v_mfma_f32_16x16x32_bf16 v[44:47], v[148:151], v[220:223], v[44:47]
	v_mfma_f32_16x16x32_bf16 v[40:43], v[196:199], v[220:223], v[40:43]
	v_mfma_f32_16x16x32_bf16 v[36:39], v[148:151], v[228:231], v[36:39]
	v_mfma_f32_16x16x32_bf16 v[32:35], v[196:199], v[228:231], v[32:35]
	s_setprio 0
	s_barrier
; #define PG8_STAGE(bufoff, gbase, voff) do { _Pragma("unroll") for (int _i = 0; _i < 2; ++_i) \
;         __builtin_amdgcn_global_load_lds((const unsigned*)((const char*)(gbase) + (voff)[_i]), (PG8_LAS unsigned*)(lds + (bufoff) + ldsw + _i * 8192), 16, 0, 0); } while (0)
; #define PG8_LDA(dst, b, h) do { _Pragma("unroll") for (int m = 0; m < 4; ++m) _Pragma("unroll") for (int k = 0; k < 2; ++k) dst[m][k] = *(const PG8_LAS bf16x8*)(lds + PG8_SA(b, h) + aoff + m * 2048 + k * 1024); } while (0)
; #define PG8_MMA(ai, bj, At, Bt) do { __builtin_amdgcn_s_setprio(1); _Pragma("unroll") for (int m = 0; m < 4; ++m) _Pragma("unroll") for (int n = 0; n < 2; ++n) _Pragma("unroll") for (int k = 0; k < 2; ++k) \
;         acc[ai][bj][m][n] = __builtin_amdgcn_mfma_f32_16x16x32_bf16(Bt[n][k], At[m][k], acc[ai][bj][m][n], 0, 0, 0); __builtin_amdgcn_s_setprio(0); } while (0)
; #define PG8_WAIT_V(n) asm volatile("s_waitcnt vmcnt(" #n ")" ::: "memory")
; #define PG8_WAIT_L(n) asm volatile("s_waitcnt lgkmcnt(" #n ")" ::: "memory")
; #define PG8_BAR __builtin_amdgcn_s_barrier()
; #define PG8_SCHED __builtin_amdgcn_sched_barrier(0)
; template <class Epi, class Sched, bool ALIGN_EPI = false, bool SP2 = false>
; __device__ __forceinline__ void gemm_phase(PG8_LAS unsigned char* lds, const Gemm g, const Sched& S, const Epi& E) {
;     ...
;             PG8_LDA(At, 1, 1); PG8_STAGE(PG8_SB(1, 0), b3, voffB); PG8_STAGE(PG8_SB(1, 1), b3 + hstepB, voffB); PG8_STAGE(PG8_SA(1, 0), a3, voffA);
;             PG8_WAIT_V(8); PG8_WAIT_L(0); PG8_BAR; PG8_MMA(1, 0, At, B0); PG8_MMA(1, 1, At, B1); PG8_BAR; PG8_SCHED;
	s_add_i32 s54, s70, s19
	v_lshl_add_u64 v[180:181], v[180:181], 0, s[28:29]
	s_mov_b32 m0, s54
	ds_read_b128 v[200:203], v191 offset:49152
	ds_read_b128 v[204:207], v191 offset:50176
	ds_read_b128 v[208:211], v191 offset:51200
	ds_read_b128 v[212:215], v191 offset:52224
	ds_read_b128 v[216:219], v191 offset:53248
	ds_read_b128 v[220:223], v191 offset:54272
	ds_read_b128 v[224:227], v191 offset:55296
	ds_read_b128 v[228:231], v191 offset:56320
	global_load_lds_dwordx4 v[180:181], off
	s_add_i32 m0, s54, 0x2000
	s_add_u32 s52, s52, 0x40080
	v_lshl_add_u64 v[180:181], v[184:185], 0, s[28:29]
	s_addc_u32 s53, s53, 0
	s_add_i32 s54, s71, s19
	global_load_lds_dwordx4 v[180:181], off
	v_lshl_add_u64 v[180:181], s[52:53], 0, v[158:159]
	s_mov_b32 m0, s54
	s_nop 0
	global_load_lds_dwordx4 v[180:181], off
	v_lshl_add_u64 v[180:181], s[52:53], 0, v[162:163]
	s_add_i32 m0, s54, 0x2000
	s_nop 0
	global_load_lds_dwordx4 v[180:181], off
	v_lshl_add_u64 v[180:181], v[188:189], 0, s[28:29]
	s_mov_b32 m0, s62
	s_nop 0
	global_load_lds_dwordx4 v[180:181], off
	v_lshl_add_u64 v[180:181], v[192:193], 0, s[28:29]
	s_mov_b32 m0, s63
	s_nop 0
	global_load_lds_dwordx4 v[180:181], off
	s_waitcnt vmcnt(8)
	s_waitcnt lgkmcnt(0)
	s_barrier
	s_setprio 1
	v_mfma_f32_16x16x32_bf16 v[92:95], v[128:131], v[200:203], v[92:95]
	v_mfma_f32_16x16x32_bf16 v[88:91], v[136:139], v[200:203], v[88:91]
	v_mfma_f32_16x16x32_bf16 v[84:87], v[128:131], v[208:211], v[84:87]
	v_mfma_f32_16x16x32_bf16 v[80:83], v[136:139], v[208:211], v[80:83]
	v_mfma_f32_16x16x32_bf16 v[76:79], v[128:131], v[216:219], v[76:79]
	v_mfma_f32_16x16x32_bf16 v[72:75], v[136:139], v[216:219], v[72:75]
	v_mfma_f32_16x16x32_bf16 v[68:71], v[128:131], v[224:227], v[68:71]
	v_mfma_f32_16x16x32_bf16 v[64:67], v[136:139], v[224:227], v[64:67]
	v_mfma_f32_16x16x32_bf16 v[92:95], v[132:135], v[204:207], v[92:95]
	v_mfma_f32_16x16x32_bf16 v[88:91], v[140:143], v[204:207], v[88:91]
	v_mfma_f32_16x16x32_bf16 v[84:87], v[132:135], v[212:215], v[84:87]
	v_mfma_f32_16x16x32_bf16 v[80:83], v[140:143], v[212:215], v[80:83]
	v_mfma_f32_16x16x32_bf16 v[76:79], v[132:135], v[220:223], v[76:79]
	v_mfma_f32_16x16x32_bf16 v[72:75], v[140:143], v[220:223], v[72:75]
	v_mfma_f32_16x16x32_bf16 v[68:71], v[132:135], v[228:231], v[68:71]
	v_mfma_f32_16x16x32_bf16 v[64:67], v[140:143], v[228:231], v[64:67]
	v_mfma_f32_16x16x32_bf16 v[28:31], v[144:147], v[200:203], v[28:31]
	v_mfma_f32_16x16x32_bf16 v[24:27], v[152:155], v[200:203], v[24:27]
	v_mfma_f32_16x16x32_bf16 v[20:23], v[144:147], v[208:211], v[20:23]
	v_mfma_f32_16x16x32_bf16 v[16:19], v[152:155], v[208:211], v[16:19]
	v_mfma_f32_16x16x32_bf16 v[12:15], v[144:147], v[216:219], v[12:15]
	v_mfma_f32_16x16x32_bf16 v[8:11], v[152:155], v[216:219], v[8:11]
	v_mfma_f32_16x16x32_bf16 v[4:7], v[144:147], v[224:227], v[4:7]
	v_mfma_f32_16x16x32_bf16 v[0:3], v[152:155], v[224:227], v[0:3]
	v_mfma_f32_16x16x32_bf16 v[28:31], v[148:151], v[204:207], v[28:31]
	v_mfma_f32_16x16x32_bf16 v[24:27], v[196:199], v[204:207], v[24:27]
	v_mfma_f32_16x16x32_bf16 v[20:23], v[148:151], v[212:215], v[20:23]
	v_mfma_f32_16x16x32_bf16 v[16:19], v[196:199], v[212:215], v[16:19]
	v_mfma_f32_16x16x32_bf16 v[12:15], v[148:151], v[220:223], v[12:15]
	v_mfma_f32_16x16x32_bf16 v[8:11], v[196:199], v[220:223], v[8:11]
	v_mfma_f32_16x16x32_bf16 v[4:7], v[148:151], v[228:231], v[4:7]
	v_mfma_f32_16x16x32_bf16 v[0:3], v[196:199], v[228:231], v[0:3]
	s_setprio 0
	s_barrier
	s_add_u32 s45, s45, 0x100
	s_addc_u32 s49, s49, 0
	s_add_u32 s50, s50, 0x100
	s_addc_u32 s51, s51, 0
	s_cmp_ge_i32 s69, s59
	s_mov_b32 s52, s69
	s_cbranch_scc0 .LBB0_1172

; #define PG8_STAGE(bufoff, gbase, voff) do { _Pragma("unroll") for (int _i = 0; _i < 2; ++_i) \
;         __builtin_amdgcn_global_load_lds((const unsigned*)((const char*)(gbase) + (voff)[_i]), (PG8_LAS unsigned*)(lds + (bufoff) + ldsw + _i * 8192), 16, 0, 0); } while (0)
; #define PG8_LDA(dst, b, h) do { _Pragma("unroll") for (int m = 0; m < 4; ++m) _Pragma("unroll") for (int k = 0; k < 2; ++k) dst[m][k] = *(const PG8_LAS bf16x8*)(lds + PG8_SA(b, h) + aoff + m * 2048 + k * 1024); } while (0)
; #define PG8_LDB(dst, b, h) do { _Pragma("unroll") for (int n = 0; n < 2; ++n) _Pragma("unroll") for (int k = 0; k < 2; ++k) dst[n][k] = *(const PG8_LAS bf16x8*)(lds + PG8_SB(b, h) + boff + n * 2048 + k * 1024); } while (0)
; #define PG8_MMA(ai, bj, At, Bt) do { __builtin_amdgcn_s_setprio(1); _Pragma("unroll") for (int m = 0; m < 4; ++m) _Pragma("unroll") for (int n = 0; n < 2; ++n) _Pragma("unroll") for (int k = 0; k < 2; ++k) \
;         acc[ai][bj][m][n] = __builtin_amdgcn_mfma_f32_16x16x32_bf16(Bt[n][k], At[m][k], acc[ai][bj][m][n], 0, 0, 0); __builtin_amdgcn_s_setprio(0); } while (0)
; #define PG8_WAIT_V(n) asm volatile("s_waitcnt vmcnt(" #n ")" ::: "memory")
; #define PG8_WAIT_L(n) asm volatile("s_waitcnt lgkmcnt(" #n ")" ::: "memory")
; template <class Epi, class Sched, bool ALIGN_EPI = false, bool SP2 = false>
; __device__ __forceinline__ void gemm_phase(PG8_LAS unsigned char* lds, const Gemm g, const Sched& S, const Epi& E) {
;     ...
;             const bool last = (t == nt - 2);
;             const char* a1 = cA + (long)(t + 1) * kstepA;
;             const char* a2 = last ? nA : cA + (long)(t + 2) * kstepA; const char* b2 = last ? nB : cB + (long)(t + 2) * kstep;
;             const char* a3 = a2 + kstepA; const char* b3 = b2 + kstep;
;             if (last && has_next) S.a_ready(nxt);
;             if constexpr (SP2) {
;             PG8_LDB(B0, 0, 0); PG8_LDB(B1, 0, 1); PG8_SCHED; PG8_LDA(At, 0, 0); PG8_STAGE(PG8_SA(1, 1), a1 + hstepA, voffA);
;             PG8_WAIT_V(8); PG8_WAIT_L(0); PG8_BAR; PG8_MMA(0, 0, At, B0); PG8_MMA(0, 1, At, B1); PG8_BAR; PG8_SCHED;
;             PG8_LDA(At, 0, 1); PG8_STAGE(PG8_SB(0, 0), b2, voffB); PG8_STAGE(PG8_SB(0, 1), b2 + hstepB, voffB); PG8_STAGE(PG8_SA(0, 0), a2, voffA);
;             PG8_WAIT_V(8); PG8_WAIT_L(0); PG8_BAR; PG8_MMA(1, 0, At, B0); PG8_MMA(1, 1, At, B1); PG8_BAR; PG8_SCHED;
.LBB0_1257:
	ds_read_b128 v[112:115], v199
	ds_read_b128 v[116:119], v199 offset:1024
	ds_read_b128 v[128:131], v199 offset:2048
	ds_read_b128 v[132:135], v199 offset:3072
	ds_read_b128 v[136:139], v203
	ds_read_b128 v[148:151], v203 offset:1024
	ds_read_b128 v[152:155], v203 offset:2048
	ds_read_b128 v[156:159], v203 offset:3072
	s_add_i32 s68, s48, 2
	s_add_u32 s49, s46, 0xfffc0080
	s_addc_u32 s50, s47, -1
	s_cmp_eq_u32 s58, s48
	s_cselect_b32 s48, s65, s66
	s_cselect_b32 s51, s35, s50
	s_cselect_b32 s50, s37, s49
	s_cselect_b32 s49, s64, s67
	v_lshl_add_u64 v[176:177], s[46:47], 0, v[168:169]
	s_add_i32 m0, s20, 0xc000
	ds_read_b128 v[180:183], v217
	ds_read_b128 v[186:189], v217 offset:1024
	ds_read_b128 v[192:195], v217 offset:2048
	ds_read_b128 v[204:207], v217 offset:3072
	ds_read_b128 v[208:211], v217 offset:4096
	ds_read_b128 v[212:215], v217 offset:5120
	ds_read_b128 v[218:221], v217 offset:6144
	ds_read_b128 v[222:225], v217 offset:7168
	global_load_lds_dwordx4 v[176:177], off
	v_lshl_add_u64 v[176:177], s[46:47], 0, v[170:171]
	s_add_i32 m0, s20, 0xe000
	s_nop 0
	global_load_lds_dwordx4 v[176:177], off
	s_waitcnt vmcnt(8)
	s_waitcnt lgkmcnt(0)
	s_barrier
	s_setprio 1
	v_mfma_f32_16x16x32_bf16 v[140:143], v[112:115], v[180:183], v[140:143]
	v_mfma_f32_16x16x32_bf16 v[120:123], v[128:131], v[180:183], v[120:123]
	v_mfma_f32_16x16x32_bf16 v[104:107], v[112:115], v[192:195], v[104:107]
	v_mfma_f32_16x16x32_bf16 v[96:99], v[128:131], v[192:195], v[96:99]
	v_mfma_f32_16x16x32_bf16 v[88:91], v[112:115], v[208:211], v[88:91]
	v_mfma_f32_16x16x32_bf16 v[80:83], v[128:131], v[208:211], v[80:83]
	v_mfma_f32_16x16x32_bf16 v[72:75], v[112:115], v[218:221], v[72:75]
	v_mfma_f32_16x16x32_bf16 v[64:67], v[128:131], v[218:221], v[64:67]
	v_mfma_f32_16x16x32_bf16 v[140:143], v[116:119], v[186:189], v[140:143]
	v_mfma_f32_16x16x32_bf16 v[120:123], v[132:135], v[186:189], v[120:123]
	v_mfma_f32_16x16x32_bf16 v[104:107], v[116:119], v[204:207], v[104:107]
	v_mfma_f32_16x16x32_bf16 v[96:99], v[132:135], v[204:207], v[96:99]
	v_mfma_f32_16x16x32_bf16 v[88:91], v[116:119], v[212:215], v[88:91]
	v_mfma_f32_16x16x32_bf16 v[80:83], v[132:135], v[212:215], v[80:83]
	v_mfma_f32_16x16x32_bf16 v[72:75], v[116:119], v[222:225], v[72:75]
	v_mfma_f32_16x16x32_bf16 v[64:67], v[132:135], v[222:225], v[64:67]
	v_mfma_f32_16x16x32_bf16 v[144:147], v[136:139], v[180:183], v[144:147]
	v_mfma_f32_16x16x32_bf16 v[124:127], v[152:155], v[180:183], v[124:127]
	v_mfma_f32_16x16x32_bf16 v[108:111], v[136:139], v[192:195], v[108:111]
	v_mfma_f32_16x16x32_bf16 v[100:103], v[152:155], v[192:195], v[100:103]
	v_mfma_f32_16x16x32_bf16 v[92:95], v[136:139], v[208:211], v[92:95]
	v_mfma_f32_16x16x32_bf16 v[84:87], v[152:155], v[208:211], v[84:87]
	v_mfma_f32_16x16x32_bf16 v[76:79], v[136:139], v[218:221], v[76:79]
	v_mfma_f32_16x16x32_bf16 v[68:71], v[152:155], v[218:221], v[68:71]
	v_mfma_f32_16x16x32_bf16 v[144:147], v[148:151], v[186:189], v[144:147]
	v_mfma_f32_16x16x32_bf16 v[124:127], v[156:159], v[186:189], v[124:127]
	v_mfma_f32_16x16x32_bf16 v[108:111], v[148:151], v[204:207], v[108:111]
	v_mfma_f32_16x16x32_bf16 v[100:103], v[156:159], v[204:207], v[100:103]
	v_mfma_f32_16x16x32_bf16 v[92:95], v[148:151], v[212:215], v[92:95]
	v_mfma_f32_16x16x32_bf16 v[84:87], v[156:159], v[212:215], v[84:87]
	v_mfma_f32_16x16x32_bf16 v[76:79], v[148:151], v[222:225], v[76:79]
	v_mfma_f32_16x16x32_bf16 v[68:71], v[156:159], v[222:225], v[68:71]
	s_setprio 0
	s_barrier
	s_add_i32 s69, s62, s17
	v_lshl_add_u64 v[176:177], s[48:49], 0, v[164:165]
	s_mov_b32 m0, s69
	ds_read_b128 v[180:183], v217 offset:16384
	ds_read_b128 v[186:189], v217 offset:17408
	ds_read_b128 v[192:195], v217 offset:18432
	ds_read_b128 v[204:207], v217 offset:19456
	ds_read_b128 v[208:211], v217 offset:20480
	ds_read_b128 v[212:215], v217 offset:21504
	ds_read_b128 v[218:221], v217 offset:22528
	ds_read_b128 v[222:225], v217 offset:23552
	global_load_lds_dwordx4 v[176:177], off
	s_add_i32 m0, s69, 0x2000
	s_add_u32 s70, s48, 0x40000
	v_lshl_add_u64 v[196:197], s[48:49], 0, v[160:161]
	s_addc_u32 s71, s49, 0
	s_add_i32 s69, s63, s17
	global_load_lds_dwordx4 v[196:197], off
	v_lshl_add_u64 v[200:201], s[70:71], 0, v[164:165]
	s_mov_b32 m0, s69
	v_lshl_add_u64 v[226:227], s[50:51], 0, v[162:163]
	global_load_lds_dwordx4 v[200:201], off
	v_lshl_add_u64 v[200:201], s[70:71], 0, v[160:161]
	s_add_i32 m0, s69, 0x2000
	s_nop 0
	global_load_lds_dwordx4 v[200:201], off
	v_lshl_add_u64 v[200:201], s[50:51], 0, v[166:167]
	s_mov_b32 m0, s20
	s_nop 0
	global_load_lds_dwordx4 v[200:201], off
	s_mov_b32 m0, s21
	s_nop 0
	global_load_lds_dwordx4 v[226:227], off
	s_waitcnt vmcnt(8)
	s_waitcnt lgkmcnt(0)
	s_barrier
; #define PG8_STAGE(bufoff, gbase, voff) do { _Pragma("unroll") for (int _i = 0; _i < 2; ++_i) \
;         __builtin_amdgcn_global_load_lds((const unsigned*)((const char*)(gbase) + (voff)[_i]), (PG8_LAS unsigned*)(lds + (bufoff) + ldsw + _i * 8192), 16, 0, 0); } while (0)
; #define PG8_LDA(dst, b, h) do { _Pragma("unroll") for (int m = 0; m < 4; ++m) _Pragma("unroll") for (int k = 0; k < 2; ++k) dst[m][k] = *(const PG8_LAS bf16x8*)(lds + PG8_SA(b, h) + aoff + m * 2048 + k * 1024); } while (0)
; #define PG8_LDB(dst, b, h) do { _Pragma("unroll") for (int n = 0; n < 2; ++n) _Pragma("unroll") for (int k = 0; k < 2; ++k) dst[n][k] = *(const PG8_LAS bf16x8*)(lds + PG8_SB(b, h) + boff + n * 2048 + k * 1024); } while (0)
; #define PG8_MMA(ai, bj, At, Bt) do { __builtin_amdgcn_s_setprio(1); _Pragma("unroll") for (int m = 0; m < 4; ++m) _Pragma("unroll") for (int n = 0; n < 2; ++n) _Pragma("unroll") for (int k = 0; k < 2; ++k) \
;         acc[ai][bj][m][n] = __builtin_amdgcn_mfma_f32_16x16x32_bf16(Bt[n][k], At[m][k], acc[ai][bj][m][n], 0, 0, 0); __builtin_amdgcn_s_setprio(0); } while (0)
; #define PG8_WAIT_V(n) asm volatile("s_waitcnt vmcnt(" #n ")" ::: "memory")
; #define PG8_WAIT_L(n) asm volatile("s_waitcnt lgkmcnt(" #n ")" ::: "memory")
; #define PG8_BAR __builtin_amdgcn_s_barrier()
; #define PG8_SCHED __builtin_amdgcn_sched_barrier(0)
; template <class Epi, class Sched, bool ALIGN_EPI = false, bool SP2 = false>
; __device__ __forceinline__ void gemm_phase(PG8_LAS unsigned char* lds, const Gemm g, const Sched& S, const Epi& E) {
;     ...
;             PG8_WAIT_V(8); PG8_WAIT_L(0); PG8_BAR; PG8_MMA(1, 0, At, B0); PG8_MMA(1, 1, At, B1); PG8_BAR; PG8_SCHED;
;             PG8_LDB(B0, 1, 0); PG8_LDB(B1, 1, 1); PG8_SCHED; PG8_LDA(At, 1, 0); PG8_STAGE(PG8_SA(0, 1), a2 + hstepA, voffA);
;             PG8_WAIT_V(8); PG8_WAIT_L(0); PG8_BAR; PG8_MMA(0, 0, At, B0); PG8_MMA(0, 1, At, B1); PG8_BAR; PG8_SCHED;
	s_setprio 1
	v_mfma_f32_16x16x32_bf16 v[56:59], v[112:115], v[180:183], v[56:59]
	v_mfma_f32_16x16x32_bf16 v[48:51], v[128:131], v[180:183], v[48:51]
	v_mfma_f32_16x16x32_bf16 v[40:43], v[112:115], v[192:195], v[40:43]
	v_mfma_f32_16x16x32_bf16 v[32:35], v[128:131], v[192:195], v[32:35]
	v_mfma_f32_16x16x32_bf16 v[24:27], v[112:115], v[208:211], v[24:27]
	v_mfma_f32_16x16x32_bf16 v[16:19], v[128:131], v[208:211], v[16:19]
	v_mfma_f32_16x16x32_bf16 v[8:11], v[112:115], v[218:221], v[8:11]
	v_mfma_f32_16x16x32_bf16 v[4:7], v[128:131], v[218:221], v[4:7]
	v_mfma_f32_16x16x32_bf16 v[56:59], v[116:119], v[186:189], v[56:59]
	v_mfma_f32_16x16x32_bf16 v[48:51], v[132:135], v[186:189], v[48:51]
	v_mfma_f32_16x16x32_bf16 v[40:43], v[116:119], v[204:207], v[40:43]
	v_mfma_f32_16x16x32_bf16 v[32:35], v[132:135], v[204:207], v[32:35]
	v_mfma_f32_16x16x32_bf16 v[24:27], v[116:119], v[212:215], v[24:27]
	v_mfma_f32_16x16x32_bf16 v[16:19], v[132:135], v[212:215], v[16:19]
	v_mfma_f32_16x16x32_bf16 v[8:11], v[116:119], v[222:225], v[8:11]
	v_mfma_f32_16x16x32_bf16 v[4:7], v[132:135], v[222:225], v[4:7]
	v_mfma_f32_16x16x32_bf16 v[60:63], v[136:139], v[180:183], v[60:63]
	v_mfma_f32_16x16x32_bf16 v[52:55], v[152:155], v[180:183], v[52:55]
	v_mfma_f32_16x16x32_bf16 v[44:47], v[136:139], v[192:195], v[44:47]
	v_mfma_f32_16x16x32_bf16 v[36:39], v[152:155], v[192:195], v[36:39]
	v_mfma_f32_16x16x32_bf16 v[28:31], v[136:139], v[208:211], v[28:31]
	v_mfma_f32_16x16x32_bf16 v[20:23], v[152:155], v[208:211], v[20:23]
	v_mfma_f32_16x16x32_bf16 v[12:15], v[136:139], v[218:221], v[12:15]
	v_mfma_f32_16x16x32_bf16 v[0:3], v[152:155], v[218:221], v[0:3]
	v_mfma_f32_16x16x32_bf16 v[60:63], v[148:151], v[186:189], v[60:63]
	v_mfma_f32_16x16x32_bf16 v[52:55], v[156:159], v[186:189], v[52:55]
	v_mfma_f32_16x16x32_bf16 v[44:47], v[148:151], v[204:207], v[44:47]
	v_mfma_f32_16x16x32_bf16 v[36:39], v[156:159], v[204:207], v[36:39]
	v_mfma_f32_16x16x32_bf16 v[28:31], v[148:151], v[212:215], v[28:31]
	v_mfma_f32_16x16x32_bf16 v[20:23], v[156:159], v[212:215], v[20:23]
	v_mfma_f32_16x16x32_bf16 v[12:15], v[148:151], v[222:225], v[12:15]
	v_mfma_f32_16x16x32_bf16 v[0:3], v[156:159], v[222:225], v[0:3]
	s_setprio 0
	s_barrier
	s_add_i32 s69, 0, 0x18000
	s_add_i32 s70, 0, 0x1c000
	v_add_u32_e32 v132, s69, v191
	v_add_u32_e32 v156, s70, v191
	ds_read_b128 v[112:115], v132
	ds_read_b128 v[116:119], v132 offset:1024
	ds_read_b128 v[128:131], v132 offset:2048
	ds_read_b128 v[132:135], v132 offset:3072
	ds_read_b128 v[136:139], v156
	ds_read_b128 v[148:151], v156 offset:1024
	ds_read_b128 v[152:155], v156 offset:2048
	ds_read_b128 v[156:159], v156 offset:3072
	s_add_u32 s50, s50, 0x40000
	s_addc_u32 s51, s51, 0
	s_mov_b32 m0, s31
	v_lshl_add_u64 v[228:229], s[50:51], 0, v[166:167]
	ds_read_b128 v[180:183], v217 offset:32768
	ds_read_b128 v[186:189], v217 offset:33792
	ds_read_b128 v[192:195], v217 offset:34816
	ds_read_b128 v[204:207], v217 offset:35840
	ds_read_b128 v[208:211], v217 offset:36864
	ds_read_b128 v[212:215], v217 offset:37888
	ds_read_b128 v[218:221], v217 offset:38912
	ds_read_b128 v[222:225], v217 offset:39936
	global_load_lds_dwordx4 v[228:229], off
	v_lshl_add_u64 v[228:229], s[50:51], 0, v[162:163]
	s_mov_b32 m0, s33
	s_nop 0
	global_load_lds_dwordx4 v[228:229], off
	s_waitcnt vmcnt(8)
	s_waitcnt lgkmcnt(0)
	s_barrier
	s_setprio 1
	v_mfma_f32_16x16x32_bf16 v[140:143], v[112:115], v[180:183], v[140:143]
	v_mfma_f32_16x16x32_bf16 v[120:123], v[128:131], v[180:183], v[120:123]
	v_mfma_f32_16x16x32_bf16 v[104:107], v[112:115], v[192:195], v[104:107]
	v_mfma_f32_16x16x32_bf16 v[96:99], v[128:131], v[192:195], v[96:99]
	v_mfma_f32_16x16x32_bf16 v[88:91], v[112:115], v[208:211], v[88:91]
	v_mfma_f32_16x16x32_bf16 v[80:83], v[128:131], v[208:211], v[80:83]
	v_mfma_f32_16x16x32_bf16 v[72:75], v[112:115], v[218:221], v[72:75]
	v_mfma_f32_16x16x32_bf16 v[64:67], v[128:131], v[218:221], v[64:67]
	v_mfma_f32_16x16x32_bf16 v[140:143], v[116:119], v[186:189], v[140:143]
	v_mfma_f32_16x16x32_bf16 v[120:123], v[132:135], v[186:189], v[120:123]
	v_mfma_f32_16x16x32_bf16 v[104:107], v[116:119], v[204:207], v[104:107]
	v_mfma_f32_16x16x32_bf16 v[96:99], v[132:135], v[204:207], v[96:99]
	v_mfma_f32_16x16x32_bf16 v[88:91], v[116:119], v[212:215], v[88:91]
	v_mfma_f32_16x16x32_bf16 v[80:83], v[132:135], v[212:215], v[80:83]
	v_mfma_f32_16x16x32_bf16 v[72:75], v[116:119], v[222:225], v[72:75]
	v_mfma_f32_16x16x32_bf16 v[64:67], v[132:135], v[222:225], v[64:67]
	v_mfma_f32_16x16x32_bf16 v[144:147], v[136:139], v[180:183], v[144:147]
	v_mfma_f32_16x16x32_bf16 v[124:127], v[152:155], v[180:183], v[124:127]
	v_mfma_f32_16x16x32_bf16 v[108:111], v[136:139], v[192:195], v[108:111]
	v_mfma_f32_16x16x32_bf16 v[100:103], v[152:155], v[192:195], v[100:103]
	v_mfma_f32_16x16x32_bf16 v[92:95], v[136:139], v[208:211], v[92:95]
	v_mfma_f32_16x16x32_bf16 v[84:87], v[152:155], v[208:211], v[84:87]
	v_mfma_f32_16x16x32_bf16 v[76:79], v[136:139], v[218:221], v[76:79]
	v_mfma_f32_16x16x32_bf16 v[68:71], v[152:155], v[218:221], v[68:71]
	v_mfma_f32_16x16x32_bf16 v[144:147], v[148:151], v[186:189], v[144:147]
	v_mfma_f32_16x16x32_bf16 v[124:127], v[156:159], v[186:189], v[124:127]
	v_mfma_f32_16x16x32_bf16 v[108:111], v[148:151], v[204:207], v[108:111]
	v_mfma_f32_16x16x32_bf16 v[100:103], v[156:159], v[204:207], v[100:103]
	v_mfma_f32_16x16x32_bf16 v[92:95], v[148:151], v[212:215], v[92:95]
	v_mfma_f32_16x16x32_bf16 v[84:87], v[156:159], v[212:215], v[84:87]
	v_mfma_f32_16x16x32_bf16 v[76:79], v[148:151], v[222:225], v[76:79]
	v_mfma_f32_16x16x32_bf16 v[68:71], v[156:159], v[222:225], v[68:71]
	s_setprio 0
	s_barrier
; #define PG8_STAGE(bufoff, gbase, voff) do { _Pragma("unroll") for (int _i = 0; _i < 2; ++_i) \
;         __builtin_amdgcn_global_load_lds((const unsigned*)((const char*)(gbase) + (voff)[_i]), (PG8_LAS unsigned*)(lds + (bufoff) + ldsw + _i * 8192), 16, 0, 0); } while (0)
; #define PG8_LDA(dst, b, h) do { _Pragma("unroll") for (int m = 0; m < 4; ++m) _Pragma("unroll") for (int k = 0; k < 2; ++k) dst[m][k] = *(const PG8_LAS bf16x8*)(lds + PG8_SA(b, h) + aoff + m * 2048 + k * 1024); } while (0)
; #define PG8_MMA(ai, bj, At, Bt) do { __builtin_amdgcn_s_setprio(1); _Pragma("unroll") for (int m = 0; m < 4; ++m) _Pragma("unroll") for (int n = 0; n < 2; ++n) _Pragma("unroll") for (int k = 0; k < 2; ++k) \
;         acc[ai][bj][m][n] = __builtin_amdgcn_mfma_f32_16x16x32_bf16(Bt[n][k], At[m][k], acc[ai][bj][m][n], 0, 0, 0); __builtin_amdgcn_s_setprio(0); } while (0)
; #define PG8_WAIT_V(n) asm volatile("s_waitcnt vmcnt(" #n ")" ::: "memory")
; #define PG8_WAIT_L(n) asm volatile("s_waitcnt lgkmcnt(" #n ")" ::: "memory")
; #define PG8_BAR __builtin_amdgcn_s_barrier()
; #define PG8_SCHED __builtin_amdgcn_sched_barrier(0)
; template <class Epi, class Sched, bool ALIGN_EPI = false, bool SP2 = false>
; __device__ __forceinline__ void gemm_phase(PG8_LAS unsigned char* lds, const Gemm g, const Sched& S, const Epi& E) {
;     ...
;             PG8_LDA(At, 1, 1); PG8_STAGE(PG8_SB(1, 0), b3, voffB); PG8_STAGE(PG8_SB(1, 1), b3 + hstepB, voffB); PG8_STAGE(PG8_SA(1, 0), a3, voffA);
;             PG8_WAIT_V(8); PG8_WAIT_L(0); PG8_BAR; PG8_MMA(1, 0, At, B0); PG8_MMA(1, 1, At, B1); PG8_BAR; PG8_SCHED;
	s_add_i32 s50, s69, s17
	v_lshl_add_u64 v[176:177], v[176:177], 0, s[24:25]
	s_mov_b32 m0, s50
	ds_read_b128 v[180:183], v217 offset:49152
	ds_read_b128 v[186:189], v217 offset:50176
	ds_read_b128 v[192:195], v217 offset:51200
	ds_read_b128 v[204:207], v217 offset:52224
	ds_read_b128 v[208:211], v217 offset:53248
	ds_read_b128 v[212:215], v217 offset:54272
	ds_read_b128 v[218:221], v217 offset:55296
	ds_read_b128 v[222:225], v217 offset:56320
	global_load_lds_dwordx4 v[176:177], off
	s_add_i32 m0, s50, 0x2000
	s_add_u32 s48, s48, 0x40080
	v_lshl_add_u64 v[176:177], v[196:197], 0, s[24:25]
	s_addc_u32 s49, s49, 0
	s_add_i32 s50, s70, s17
	global_load_lds_dwordx4 v[176:177], off
	v_lshl_add_u64 v[176:177], s[48:49], 0, v[164:165]
	s_mov_b32 m0, s50
	s_nop 0
	global_load_lds_dwordx4 v[176:177], off
	v_lshl_add_u64 v[176:177], s[48:49], 0, v[160:161]
	s_add_i32 m0, s50, 0x2000
	s_nop 0
	global_load_lds_dwordx4 v[176:177], off
	v_lshl_add_u64 v[176:177], v[200:201], 0, s[24:25]
	s_mov_b32 m0, s56
	s_nop 0
	global_load_lds_dwordx4 v[176:177], off
	v_lshl_add_u64 v[176:177], v[226:227], 0, s[24:25]
	s_mov_b32 m0, s57
	s_nop 0
	global_load_lds_dwordx4 v[176:177], off
	s_waitcnt vmcnt(8)
	s_waitcnt lgkmcnt(0)
	s_barrier
	s_setprio 1
	v_mfma_f32_16x16x32_bf16 v[56:59], v[112:115], v[180:183], v[56:59]
	v_mfma_f32_16x16x32_bf16 v[48:51], v[128:131], v[180:183], v[48:51]
	v_mfma_f32_16x16x32_bf16 v[40:43], v[112:115], v[192:195], v[40:43]
	v_mfma_f32_16x16x32_bf16 v[32:35], v[128:131], v[192:195], v[32:35]
	v_mfma_f32_16x16x32_bf16 v[24:27], v[112:115], v[208:211], v[24:27]
	v_mfma_f32_16x16x32_bf16 v[16:19], v[128:131], v[208:211], v[16:19]
	v_mfma_f32_16x16x32_bf16 v[8:11], v[112:115], v[218:221], v[8:11]
	v_mfma_f32_16x16x32_bf16 v[4:7], v[128:131], v[218:221], v[4:7]
	v_mfma_f32_16x16x32_bf16 v[56:59], v[116:119], v[186:189], v[56:59]
	v_mfma_f32_16x16x32_bf16 v[48:51], v[132:135], v[186:189], v[48:51]
	v_mfma_f32_16x16x32_bf16 v[40:43], v[116:119], v[204:207], v[40:43]
	v_mfma_f32_16x16x32_bf16 v[32:35], v[132:135], v[204:207], v[32:35]
	v_mfma_f32_16x16x32_bf16 v[24:27], v[116:119], v[212:215], v[24:27]
	v_mfma_f32_16x16x32_bf16 v[16:19], v[132:135], v[212:215], v[16:19]
	v_mfma_f32_16x16x32_bf16 v[8:11], v[116:119], v[222:225], v[8:11]
	v_mfma_f32_16x16x32_bf16 v[4:7], v[132:135], v[222:225], v[4:7]
	v_mfma_f32_16x16x32_bf16 v[60:63], v[136:139], v[180:183], v[60:63]
	v_mfma_f32_16x16x32_bf16 v[52:55], v[152:155], v[180:183], v[52:55]
	v_mfma_f32_16x16x32_bf16 v[44:47], v[136:139], v[192:195], v[44:47]
	v_mfma_f32_16x16x32_bf16 v[36:39], v[152:155], v[192:195], v[36:39]
	v_mfma_f32_16x16x32_bf16 v[28:31], v[136:139], v[208:211], v[28:31]
	v_mfma_f32_16x16x32_bf16 v[20:23], v[152:155], v[208:211], v[20:23]
	v_mfma_f32_16x16x32_bf16 v[12:15], v[136:139], v[218:221], v[12:15]
	v_mfma_f32_16x16x32_bf16 v[0:3], v[152:155], v[218:221], v[0:3]
	v_mfma_f32_16x16x32_bf16 v[60:63], v[148:151], v[186:189], v[60:63]
	v_mfma_f32_16x16x32_bf16 v[52:55], v[156:159], v[186:189], v[52:55]
	v_mfma_f32_16x16x32_bf16 v[44:47], v[148:151], v[204:207], v[44:47]
	v_mfma_f32_16x16x32_bf16 v[36:39], v[156:159], v[204:207], v[36:39]
	v_mfma_f32_16x16x32_bf16 v[28:31], v[148:151], v[212:215], v[28:31]
	v_mfma_f32_16x16x32_bf16 v[20:23], v[156:159], v[212:215], v[20:23]
	v_mfma_f32_16x16x32_bf16 v[12:15], v[148:151], v[222:225], v[12:15]
	v_mfma_f32_16x16x32_bf16 v[0:3], v[156:159], v[222:225], v[0:3]
	s_setprio 0
	s_barrier
	s_add_u32 s46, s46, 0x100
	s_addc_u32 s47, s47, 0
	s_add_u32 s66, s66, 0x100
	s_addc_u32 s67, s67, 0
	s_cmp_ge_i32 s68, s53
	s_mov_b32 s48, s68
	s_cbranch_scc0 .LBB0_1257

; #define PG8_STAGE(bufoff, gbase, voff) do { _Pragma("unroll") for (int _i = 0; _i < 2; ++_i) \
;         __builtin_amdgcn_global_load_lds((const unsigned*)((const char*)(gbase) + (voff)[_i]), (PG8_LAS unsigned*)(lds + (bufoff) + ldsw + _i * 8192), 16, 0, 0); } while (0)
; #define PG8_LDA(dst, b, h) do { _Pragma("unroll") for (int m = 0; m < 4; ++m) _Pragma("unroll") for (int k = 0; k < 2; ++k) dst[m][k] = *(const PG8_LAS bf16x8*)(lds + PG8_SA(b, h) + aoff + m * 2048 + k * 1024); } while (0)
; #define PG8_LDB(dst, b, h) do { _Pragma("unroll") for (int n = 0; n < 2; ++n) _Pragma("unroll") for (int k = 0; k < 2; ++k) dst[n][k] = *(const PG8_LAS bf16x8*)(lds + PG8_SB(b, h) + boff + n * 2048 + k * 1024); } while (0)
; #define PG8_MMA(ai, bj, At, Bt) do { __builtin_amdgcn_s_setprio(1); _Pragma("unroll") for (int m = 0; m < 4; ++m) _Pragma("unroll") for (int n = 0; n < 2; ++n) _Pragma("unroll") for (int k = 0; k < 2; ++k) \
;         acc[ai][bj][m][n] = __builtin_amdgcn_mfma_f32_16x16x32_bf16(Bt[n][k], At[m][k], acc[ai][bj][m][n], 0, 0, 0); __builtin_amdgcn_s_setprio(0); } while (0)
; #define PG8_WAIT_V(n) asm volatile("s_waitcnt vmcnt(" #n ")" ::: "memory")
; #define PG8_WAIT_L(n) asm volatile("s_waitcnt lgkmcnt(" #n ")" ::: "memory")
; template <class Epi, class Sched, bool ALIGN_EPI = false, bool SP2 = false>
; __device__ __forceinline__ void gemm_phase(PG8_LAS unsigned char* lds, const Gemm g, const Sched& S, const Epi& E) {
;     ...
;             const bool last = (t == nt - 2);
;             const char* a1 = cA + (long)(t + 1) * kstepA;
;             const char* a2 = last ? nA : cA + (long)(t + 2) * kstepA; const char* b2 = last ? nB : cB + (long)(t + 2) * kstep;
;             const char* a3 = a2 + kstepA; const char* b3 = b2 + kstep;
;             if (last && has_next) S.a_ready(nxt);
;             if constexpr (SP2) {
;             PG8_LDB(B0, 0, 0); PG8_LDB(B1, 0, 1); PG8_SCHED; PG8_LDA(At, 0, 0); PG8_STAGE(PG8_SA(1, 1), a1 + hstepA, voffA);
;             PG8_WAIT_V(8); PG8_WAIT_L(0); PG8_BAR; PG8_MMA(0, 0, At, B0); PG8_MMA(0, 1, At, B1); PG8_BAR; PG8_SCHED;
;             PG8_LDA(At, 0, 1); PG8_STAGE(PG8_SB(0, 0), b2, voffB); PG8_STAGE(PG8_SB(0, 1), b2 + hstepB, voffB); PG8_STAGE(PG8_SA(0, 0), a2, voffA);
;             PG8_WAIT_V(8); PG8_WAIT_L(0); PG8_BAR; PG8_MMA(1, 0, At, B0); PG8_MMA(1, 1, At, B1); PG8_BAR; PG8_SCHED;
.LBB0_1333:
	ds_read_b128 v[144:147], v155
	ds_read_b128 v[148:151], v155 offset:1024
	ds_read_b128 v[158:161], v155 offset:2048
	ds_read_b128 v[162:165], v155 offset:3072
	ds_read_b128 v[166:169], v156
	ds_read_b128 v[170:173], v156 offset:1024
	ds_read_b128 v[174:177], v156 offset:2048
	ds_read_b128 v[178:181], v156 offset:3072
	s_add_i32 s66, s48, 2
	s_add_u32 s49, s46, 0xffff0080
	s_addc_u32 s50, s47, -1
	s_cmp_eq_u32 s59, s48
	s_cselect_b32 s48, s63, s64
	s_cselect_b32 s51, s9, s50
	s_cselect_b32 s50, s37, s49
	s_cselect_b32 s49, s41, s65
	v_lshl_add_u64 v[214:215], s[46:47], 0, v[136:137]
	s_add_i32 m0, s20, 0xc000
	ds_read_b128 v[182:185], v157
	ds_read_b128 v[186:189], v157 offset:1024
	ds_read_b128 v[190:193], v157 offset:2048
	ds_read_b128 v[194:197], v157 offset:3072
	ds_read_b128 v[198:201], v157 offset:4096
	ds_read_b128 v[202:205], v157 offset:5120
	ds_read_b128 v[206:209], v157 offset:6144
	ds_read_b128 v[210:213], v157 offset:7168
	global_load_lds_dwordx4 v[214:215], off
	v_lshl_add_u64 v[214:215], s[46:47], 0, v[138:139]
	s_add_i32 m0, s20, 0xe000
	s_nop 0
	global_load_lds_dwordx4 v[214:215], off
	s_waitcnt vmcnt(8)
	s_waitcnt lgkmcnt(0)
	s_barrier
	s_setprio 1
	v_mfma_f32_16x16x32_bf16 v[124:127], v[144:147], v[182:185], v[124:127]
	v_mfma_f32_16x16x32_bf16 v[120:123], v[158:161], v[182:185], v[120:123]
	v_mfma_f32_16x16x32_bf16 v[116:119], v[144:147], v[190:193], v[116:119]
	v_mfma_f32_16x16x32_bf16 v[112:115], v[158:161], v[190:193], v[112:115]
	v_mfma_f32_16x16x32_bf16 v[104:107], v[144:147], v[198:201], v[104:107]
	v_mfma_f32_16x16x32_bf16 v[96:99], v[158:161], v[198:201], v[96:99]
	v_mfma_f32_16x16x32_bf16 v[88:91], v[144:147], v[206:209], v[88:91]
	v_mfma_f32_16x16x32_bf16 v[80:83], v[158:161], v[206:209], v[80:83]
	v_mfma_f32_16x16x32_bf16 v[124:127], v[148:151], v[186:189], v[124:127]
	v_mfma_f32_16x16x32_bf16 v[120:123], v[162:165], v[186:189], v[120:123]
	v_mfma_f32_16x16x32_bf16 v[116:119], v[148:151], v[194:197], v[116:119]
	v_mfma_f32_16x16x32_bf16 v[112:115], v[162:165], v[194:197], v[112:115]
	v_mfma_f32_16x16x32_bf16 v[104:107], v[148:151], v[202:205], v[104:107]
	v_mfma_f32_16x16x32_bf16 v[96:99], v[162:165], v[202:205], v[96:99]
	v_mfma_f32_16x16x32_bf16 v[88:91], v[148:151], v[210:213], v[88:91]
	v_mfma_f32_16x16x32_bf16 v[80:83], v[162:165], v[210:213], v[80:83]
	v_mfma_f32_16x16x32_bf16 v[108:111], v[166:169], v[182:185], v[108:111]
	v_mfma_f32_16x16x32_bf16 v[100:103], v[174:177], v[182:185], v[100:103]
	v_mfma_f32_16x16x32_bf16 v[92:95], v[166:169], v[190:193], v[92:95]
	v_mfma_f32_16x16x32_bf16 v[84:87], v[174:177], v[190:193], v[84:87]
	v_mfma_f32_16x16x32_bf16 v[76:79], v[166:169], v[198:201], v[76:79]
	v_mfma_f32_16x16x32_bf16 v[72:75], v[174:177], v[198:201], v[72:75]
	v_mfma_f32_16x16x32_bf16 v[68:71], v[166:169], v[206:209], v[68:71]
	v_mfma_f32_16x16x32_bf16 v[64:67], v[174:177], v[206:209], v[64:67]
	v_mfma_f32_16x16x32_bf16 v[108:111], v[170:173], v[186:189], v[108:111]
	v_mfma_f32_16x16x32_bf16 v[100:103], v[178:181], v[186:189], v[100:103]
	v_mfma_f32_16x16x32_bf16 v[92:95], v[170:173], v[194:197], v[92:95]
	v_mfma_f32_16x16x32_bf16 v[84:87], v[178:181], v[194:197], v[84:87]
	v_mfma_f32_16x16x32_bf16 v[76:79], v[170:173], v[202:205], v[76:79]
	v_mfma_f32_16x16x32_bf16 v[72:75], v[178:181], v[202:205], v[72:75]
	v_mfma_f32_16x16x32_bf16 v[68:71], v[170:173], v[210:213], v[68:71]
	v_mfma_f32_16x16x32_bf16 v[64:67], v[178:181], v[210:213], v[64:67]
	s_setprio 0
	s_barrier
	s_add_i32 s67, s61, s19
	v_lshl_add_u64 v[214:215], s[48:49], 0, v[130:131]
	s_mov_b32 m0, s67
	ds_read_b128 v[182:185], v157 offset:16384
	ds_read_b128 v[186:189], v157 offset:17408
	ds_read_b128 v[190:193], v157 offset:18432
	ds_read_b128 v[194:197], v157 offset:19456
	ds_read_b128 v[198:201], v157 offset:20480
	ds_read_b128 v[202:205], v157 offset:21504
	ds_read_b128 v[206:209], v157 offset:22528
	ds_read_b128 v[210:213], v157 offset:23552
	global_load_lds_dwordx4 v[214:215], off
	s_add_i32 m0, s67, 0x2000
	s_add_u32 s68, s48, 0x10000
	v_lshl_add_u64 v[216:217], s[48:49], 0, v[134:135]
	s_addc_u32 s69, s49, 0
	s_add_i32 s67, s62, s19
	global_load_lds_dwordx4 v[216:217], off
	v_lshl_add_u64 v[218:219], s[68:69], 0, v[130:131]
	s_mov_b32 m0, s67
	v_lshl_add_u64 v[220:221], s[50:51], 0, v[132:133]
	global_load_lds_dwordx4 v[218:219], off
	v_lshl_add_u64 v[218:219], s[68:69], 0, v[134:135]
	s_add_i32 m0, s67, 0x2000
	s_nop 0
	global_load_lds_dwordx4 v[218:219], off
	v_lshl_add_u64 v[218:219], s[50:51], 0, v[128:129]
	s_mov_b32 m0, s20
	s_nop 0
	global_load_lds_dwordx4 v[218:219], off
	s_mov_b32 m0, s21
	s_nop 0
	global_load_lds_dwordx4 v[220:221], off
	s_waitcnt vmcnt(8)
	s_waitcnt lgkmcnt(0)
	s_barrier
; #define PG8_STAGE(bufoff, gbase, voff) do { _Pragma("unroll") for (int _i = 0; _i < 2; ++_i) \
;         __builtin_amdgcn_global_load_lds((const unsigned*)((const char*)(gbase) + (voff)[_i]), (PG8_LAS unsigned*)(lds + (bufoff) + ldsw + _i * 8192), 16, 0, 0); } while (0)
; #define PG8_LDA(dst, b, h) do { _Pragma("unroll") for (int m = 0; m < 4; ++m) _Pragma("unroll") for (int k = 0; k < 2; ++k) dst[m][k] = *(const PG8_LAS bf16x8*)(lds + PG8_SA(b, h) + aoff + m * 2048 + k * 1024); } while (0)
; #define PG8_LDB(dst, b, h) do { _Pragma("unroll") for (int n = 0; n < 2; ++n) _Pragma("unroll") for (int k = 0; k < 2; ++k) dst[n][k] = *(const PG8_LAS bf16x8*)(lds + PG8_SB(b, h) + boff + n * 2048 + k * 1024); } while (0)
; #define PG8_MMA(ai, bj, At, Bt) do { __builtin_amdgcn_s_setprio(1); _Pragma("unroll") for (int m = 0; m < 4; ++m) _Pragma("unroll") for (int n = 0; n < 2; ++n) _Pragma("unroll") for (int k = 0; k < 2; ++k) \
;         acc[ai][bj][m][n] = __builtin_amdgcn_mfma_f32_16x16x32_bf16(Bt[n][k], At[m][k], acc[ai][bj][m][n], 0, 0, 0); __builtin_amdgcn_s_setprio(0); } while (0)
; #define PG8_WAIT_V(n) asm volatile("s_waitcnt vmcnt(" #n ")" ::: "memory")
; #define PG8_WAIT_L(n) asm volatile("s_waitcnt lgkmcnt(" #n ")" ::: "memory")
; #define PG8_BAR __builtin_amdgcn_s_barrier()
; #define PG8_SCHED __builtin_amdgcn_sched_barrier(0)
; template <class Epi, class Sched, bool ALIGN_EPI = false, bool SP2 = false>
; __device__ __forceinline__ void gemm_phase(PG8_LAS unsigned char* lds, const Gemm g, const Sched& S, const Epi& E) {
;     ...
;             PG8_WAIT_V(8); PG8_WAIT_L(0); PG8_BAR; PG8_MMA(1, 0, At, B0); PG8_MMA(1, 1, At, B1); PG8_BAR; PG8_SCHED;
;             PG8_LDB(B0, 1, 0); PG8_LDB(B1, 1, 1); PG8_SCHED; PG8_LDA(At, 1, 0); PG8_STAGE(PG8_SA(0, 1), a2 + hstepA, voffA);
;             PG8_WAIT_V(8); PG8_WAIT_L(0); PG8_BAR; PG8_MMA(0, 0, At, B0); PG8_MMA(0, 1, At, B1); PG8_BAR; PG8_SCHED;
	s_setprio 1
	v_mfma_f32_16x16x32_bf16 v[60:63], v[144:147], v[182:185], v[60:63]
	v_mfma_f32_16x16x32_bf16 v[56:59], v[158:161], v[182:185], v[56:59]
	v_mfma_f32_16x16x32_bf16 v[52:55], v[144:147], v[190:193], v[52:55]
	v_mfma_f32_16x16x32_bf16 v[48:51], v[158:161], v[190:193], v[48:51]
	v_mfma_f32_16x16x32_bf16 v[40:43], v[144:147], v[198:201], v[40:43]
	v_mfma_f32_16x16x32_bf16 v[32:35], v[158:161], v[198:201], v[32:35]
	v_mfma_f32_16x16x32_bf16 v[24:27], v[144:147], v[206:209], v[24:27]
	v_mfma_f32_16x16x32_bf16 v[16:19], v[158:161], v[206:209], v[16:19]
	v_mfma_f32_16x16x32_bf16 v[60:63], v[148:151], v[186:189], v[60:63]
	v_mfma_f32_16x16x32_bf16 v[56:59], v[162:165], v[186:189], v[56:59]
	v_mfma_f32_16x16x32_bf16 v[52:55], v[148:151], v[194:197], v[52:55]
	v_mfma_f32_16x16x32_bf16 v[48:51], v[162:165], v[194:197], v[48:51]
	v_mfma_f32_16x16x32_bf16 v[40:43], v[148:151], v[202:205], v[40:43]
	v_mfma_f32_16x16x32_bf16 v[32:35], v[162:165], v[202:205], v[32:35]
	v_mfma_f32_16x16x32_bf16 v[24:27], v[148:151], v[210:213], v[24:27]
	v_mfma_f32_16x16x32_bf16 v[16:19], v[162:165], v[210:213], v[16:19]
	v_mfma_f32_16x16x32_bf16 v[44:47], v[166:169], v[182:185], v[44:47]
	v_mfma_f32_16x16x32_bf16 v[36:39], v[174:177], v[182:185], v[36:39]
	v_mfma_f32_16x16x32_bf16 v[28:31], v[166:169], v[190:193], v[28:31]
	v_mfma_f32_16x16x32_bf16 v[20:23], v[174:177], v[190:193], v[20:23]
	v_mfma_f32_16x16x32_bf16 v[12:15], v[166:169], v[198:201], v[12:15]
	v_mfma_f32_16x16x32_bf16 v[8:11], v[174:177], v[198:201], v[8:11]
	v_mfma_f32_16x16x32_bf16 v[4:7], v[166:169], v[206:209], v[4:7]
	v_mfma_f32_16x16x32_bf16 v[0:3], v[174:177], v[206:209], v[0:3]
	v_mfma_f32_16x16x32_bf16 v[44:47], v[170:173], v[186:189], v[44:47]
	v_mfma_f32_16x16x32_bf16 v[36:39], v[178:181], v[186:189], v[36:39]
	v_mfma_f32_16x16x32_bf16 v[28:31], v[170:173], v[194:197], v[28:31]
	v_mfma_f32_16x16x32_bf16 v[20:23], v[178:181], v[194:197], v[20:23]
	v_mfma_f32_16x16x32_bf16 v[12:15], v[170:173], v[202:205], v[12:15]
	v_mfma_f32_16x16x32_bf16 v[8:11], v[178:181], v[202:205], v[8:11]
	v_mfma_f32_16x16x32_bf16 v[4:7], v[170:173], v[210:213], v[4:7]
	v_mfma_f32_16x16x32_bf16 v[0:3], v[178:181], v[210:213], v[0:3]
	s_setprio 0
	s_barrier
	s_add_i32 s67, 0, 0x18000
	s_add_i32 s68, 0, 0x1c000
	v_add_u32_e32 v162, s67, v154
	v_add_u32_e32 v178, s68, v154
	ds_read_b128 v[144:147], v162
	ds_read_b128 v[148:151], v162 offset:1024
	ds_read_b128 v[158:161], v162 offset:2048
	ds_read_b128 v[162:165], v162 offset:3072
	ds_read_b128 v[166:169], v178
	ds_read_b128 v[170:173], v178 offset:1024
	ds_read_b128 v[174:177], v178 offset:2048
	ds_read_b128 v[178:181], v178 offset:3072
	s_add_u32 s50, s50, 0x10000
	s_addc_u32 s51, s51, 0
	s_mov_b32 m0, s33
	v_lshl_add_u64 v[222:223], s[50:51], 0, v[128:129]
	ds_read_b128 v[182:185], v157 offset:32768
	ds_read_b128 v[186:189], v157 offset:33792
	ds_read_b128 v[190:193], v157 offset:34816
	ds_read_b128 v[194:197], v157 offset:35840
	ds_read_b128 v[198:201], v157 offset:36864
	ds_read_b128 v[202:205], v157 offset:37888
	ds_read_b128 v[206:209], v157 offset:38912
	ds_read_b128 v[210:213], v157 offset:39936
	global_load_lds_dwordx4 v[222:223], off
	v_lshl_add_u64 v[222:223], s[50:51], 0, v[132:133]
	s_mov_b32 m0, s35
	s_nop 0
	global_load_lds_dwordx4 v[222:223], off
	s_waitcnt vmcnt(8)
	s_waitcnt lgkmcnt(0)
	s_barrier
	s_setprio 1
	v_mfma_f32_16x16x32_bf16 v[124:127], v[144:147], v[182:185], v[124:127]
	v_mfma_f32_16x16x32_bf16 v[120:123], v[158:161], v[182:185], v[120:123]
	v_mfma_f32_16x16x32_bf16 v[116:119], v[144:147], v[190:193], v[116:119]
	v_mfma_f32_16x16x32_bf16 v[112:115], v[158:161], v[190:193], v[112:115]
	v_mfma_f32_16x16x32_bf16 v[104:107], v[144:147], v[198:201], v[104:107]
	v_mfma_f32_16x16x32_bf16 v[96:99], v[158:161], v[198:201], v[96:99]
	v_mfma_f32_16x16x32_bf16 v[88:91], v[144:147], v[206:209], v[88:91]
	v_mfma_f32_16x16x32_bf16 v[80:83], v[158:161], v[206:209], v[80:83]
	v_mfma_f32_16x16x32_bf16 v[124:127], v[148:151], v[186:189], v[124:127]
	v_mfma_f32_16x16x32_bf16 v[120:123], v[162:165], v[186:189], v[120:123]
	v_mfma_f32_16x16x32_bf16 v[116:119], v[148:151], v[194:197], v[116:119]
	v_mfma_f32_16x16x32_bf16 v[112:115], v[162:165], v[194:197], v[112:115]
	v_mfma_f32_16x16x32_bf16 v[104:107], v[148:151], v[202:205], v[104:107]
	v_mfma_f32_16x16x32_bf16 v[96:99], v[162:165], v[202:205], v[96:99]
	v_mfma_f32_16x16x32_bf16 v[88:91], v[148:151], v[210:213], v[88:91]
	v_mfma_f32_16x16x32_bf16 v[80:83], v[162:165], v[210:213], v[80:83]
	v_mfma_f32_16x16x32_bf16 v[108:111], v[166:169], v[182:185], v[108:111]
	v_mfma_f32_16x16x32_bf16 v[100:103], v[174:177], v[182:185], v[100:103]
	v_mfma_f32_16x16x32_bf16 v[92:95], v[166:169], v[190:193], v[92:95]
	v_mfma_f32_16x16x32_bf16 v[84:87], v[174:177], v[190:193], v[84:87]
	v_mfma_f32_16x16x32_bf16 v[76:79], v[166:169], v[198:201], v[76:79]
	v_mfma_f32_16x16x32_bf16 v[72:75], v[174:177], v[198:201], v[72:75]
	v_mfma_f32_16x16x32_bf16 v[68:71], v[166:169], v[206:209], v[68:71]
	v_mfma_f32_16x16x32_bf16 v[64:67], v[174:177], v[206:209], v[64:67]
	v_mfma_f32_16x16x32_bf16 v[108:111], v[170:173], v[186:189], v[108:111]
	v_mfma_f32_16x16x32_bf16 v[100:103], v[178:181], v[186:189], v[100:103]
	v_mfma_f32_16x16x32_bf16 v[92:95], v[170:173], v[194:197], v[92:95]
	v_mfma_f32_16x16x32_bf16 v[84:87], v[178:181], v[194:197], v[84:87]
	v_mfma_f32_16x16x32_bf16 v[76:79], v[170:173], v[202:205], v[76:79]
	v_mfma_f32_16x16x32_bf16 v[72:75], v[178:181], v[202:205], v[72:75]
	v_mfma_f32_16x16x32_bf16 v[68:71], v[170:173], v[210:213], v[68:71]
	v_mfma_f32_16x16x32_bf16 v[64:67], v[178:181], v[210:213], v[64:67]
	s_setprio 0
	s_barrier
; #define PG8_STAGE(bufoff, gbase, voff) do { _Pragma("unroll") for (int _i = 0; _i < 2; ++_i) \
;         __builtin_amdgcn_global_load_lds((const unsigned*)((const char*)(gbase) + (voff)[_i]), (PG8_LAS unsigned*)(lds + (bufoff) + ldsw + _i * 8192), 16, 0, 0); } while (0)
; #define PG8_LDA(dst, b, h) do { _Pragma("unroll") for (int m = 0; m < 4; ++m) _Pragma("unroll") for (int k = 0; k < 2; ++k) dst[m][k] = *(const PG8_LAS bf16x8*)(lds + PG8_SA(b, h) + aoff + m * 2048 + k * 1024); } while (0)
; #define PG8_MMA(ai, bj, At, Bt) do { __builtin_amdgcn_s_setprio(1); _Pragma("unroll") for (int m = 0; m < 4; ++m) _Pragma("unroll") for (int n = 0; n < 2; ++n) _Pragma("unroll") for (int k = 0; k < 2; ++k) \
;         acc[ai][bj][m][n] = __builtin_amdgcn_mfma_f32_16x16x32_bf16(Bt[n][k], At[m][k], acc[ai][bj][m][n], 0, 0, 0); __builtin_amdgcn_s_setprio(0); } while (0)
; #define PG8_WAIT_V(n) asm volatile("s_waitcnt vmcnt(" #n ")" ::: "memory")
; #define PG8_WAIT_L(n) asm volatile("s_waitcnt lgkmcnt(" #n ")" ::: "memory")
; #define PG8_BAR __builtin_amdgcn_s_barrier()
; #define PG8_SCHED __builtin_amdgcn_sched_barrier(0)
;     __device__ __forceinline__ void operator()(const f32x4 (&acc)[2][2][4][2], const Unit& u, int wr, int wc, int fr_in, int fq_in) const {
;     ...
;             for (int n = 0; n < 2; ++n) bv[bj][n] = bias ? *(const f32x4*)(bias + bcol0 + bj * HALF + 4 * n) : (f32x4){0.f, 0.f, 0.f, 0.f};
; #pragma unroll
;         for (int ai = 0; ai < 2; ++ai)
; #pragma unroll
;             for (int m = 0; m < 4; ++m) { bf16_t* rowp = base + (size_t)(row0 + ai * HALF + m * 16) * ldc + col0;
; #pragma unroll
;                 for (int bj = 0; bj < 2; ++bj) { f32x4 v0 = acc[ai][bj][m][0] + bv[bj][0], v1 = acc[ai][bj][m][1] + bv[bj][1];
; template <class Epi, class Sched, bool ALIGN_EPI = false, bool SP2 = false>
; __device__ __forceinline__ void gemm_phase(PG8_LAS unsigned char* lds, const Gemm g, const Sched& S, const Epi& E) {
;     ...
;             PG8_LDA(At, 1, 1); PG8_STAGE(PG8_SB(1, 0), b3, voffB); PG8_STAGE(PG8_SB(1, 1), b3 + hstepB, voffB); PG8_STAGE(PG8_SA(1, 0), a3, voffA);
;             PG8_WAIT_V(8); PG8_WAIT_L(0); PG8_BAR; PG8_MMA(1, 0, At, B0); PG8_MMA(1, 1, At, B1); PG8_BAR; PG8_SCHED;
	s_add_i32 s50, s67, s19
	v_lshl_add_u64 v[214:215], v[214:215], 0, s[24:25]
	s_mov_b32 m0, s50
	ds_read_b128 v[182:185], v157 offset:49152
	ds_read_b128 v[186:189], v157 offset:50176
	ds_read_b128 v[190:193], v157 offset:51200
	ds_read_b128 v[194:197], v157 offset:52224
	ds_read_b128 v[198:201], v157 offset:53248
	ds_read_b128 v[202:205], v157 offset:54272
	ds_read_b128 v[206:209], v157 offset:55296
	ds_read_b128 v[210:213], v157 offset:56320
	global_load_lds_dwordx4 v[214:215], off
	s_add_i32 m0, s50, 0x2000
	s_add_u32 s48, s48, 0x10080
	v_lshl_add_u64 v[214:215], v[216:217], 0, s[24:25]
	s_addc_u32 s49, s49, 0
	s_add_i32 s50, s68, s19
	global_load_lds_dwordx4 v[214:215], off
	v_lshl_add_u64 v[214:215], s[48:49], 0, v[130:131]
	s_mov_b32 m0, s50
	s_nop 0
	global_load_lds_dwordx4 v[214:215], off
	v_lshl_add_u64 v[214:215], s[48:49], 0, v[134:135]
	s_add_i32 m0, s50, 0x2000
	s_nop 0
	global_load_lds_dwordx4 v[214:215], off
	v_lshl_add_u64 v[214:215], v[218:219], 0, s[24:25]
	s_mov_b32 m0, s57
	s_nop 0
	global_load_lds_dwordx4 v[214:215], off
	v_lshl_add_u64 v[214:215], v[220:221], 0, s[24:25]
	s_mov_b32 m0, s58
	s_nop 0
	global_load_lds_dwordx4 v[214:215], off
	s_waitcnt vmcnt(8)
	s_waitcnt lgkmcnt(0)
	s_barrier
	s_setprio 1
	v_mfma_f32_16x16x32_bf16 v[60:63], v[144:147], v[182:185], v[60:63]
	v_mfma_f32_16x16x32_bf16 v[56:59], v[158:161], v[182:185], v[56:59]
	v_mfma_f32_16x16x32_bf16 v[52:55], v[144:147], v[190:193], v[52:55]
	v_mfma_f32_16x16x32_bf16 v[48:51], v[158:161], v[190:193], v[48:51]
	v_mfma_f32_16x16x32_bf16 v[40:43], v[144:147], v[198:201], v[40:43]
	v_mfma_f32_16x16x32_bf16 v[32:35], v[158:161], v[198:201], v[32:35]
	v_mfma_f32_16x16x32_bf16 v[24:27], v[144:147], v[206:209], v[24:27]
	v_mfma_f32_16x16x32_bf16 v[16:19], v[158:161], v[206:209], v[16:19]
	v_mfma_f32_16x16x32_bf16 v[60:63], v[148:151], v[186:189], v[60:63]
	v_mfma_f32_16x16x32_bf16 v[56:59], v[162:165], v[186:189], v[56:59]
	v_mfma_f32_16x16x32_bf16 v[52:55], v[148:151], v[194:197], v[52:55]
	v_mfma_f32_16x16x32_bf16 v[48:51], v[162:165], v[194:197], v[48:51]
	v_mfma_f32_16x16x32_bf16 v[40:43], v[148:151], v[202:205], v[40:43]
	v_mfma_f32_16x16x32_bf16 v[32:35], v[162:165], v[202:205], v[32:35]
	v_mfma_f32_16x16x32_bf16 v[24:27], v[148:151], v[210:213], v[24:27]
	v_mfma_f32_16x16x32_bf16 v[16:19], v[162:165], v[210:213], v[16:19]
	v_mfma_f32_16x16x32_bf16 v[44:47], v[166:169], v[182:185], v[44:47]
	v_mfma_f32_16x16x32_bf16 v[36:39], v[174:177], v[182:185], v[36:39]
	v_mfma_f32_16x16x32_bf16 v[28:31], v[166:169], v[190:193], v[28:31]
	v_mfma_f32_16x16x32_bf16 v[20:23], v[174:177], v[190:193], v[20:23]
	v_mfma_f32_16x16x32_bf16 v[12:15], v[166:169], v[198:201], v[12:15]
	v_mfma_f32_16x16x32_bf16 v[8:11], v[174:177], v[198:201], v[8:11]
	v_mfma_f32_16x16x32_bf16 v[4:7], v[166:169], v[206:209], v[4:7]
	v_mfma_f32_16x16x32_bf16 v[0:3], v[174:177], v[206:209], v[0:3]
	v_mfma_f32_16x16x32_bf16 v[44:47], v[170:173], v[186:189], v[44:47]
	v_mfma_f32_16x16x32_bf16 v[36:39], v[178:181], v[186:189], v[36:39]
	v_mfma_f32_16x16x32_bf16 v[28:31], v[170:173], v[194:197], v[28:31]
	v_mfma_f32_16x16x32_bf16 v[20:23], v[178:181], v[194:197], v[20:23]
	v_mfma_f32_16x16x32_bf16 v[12:15], v[170:173], v[202:205], v[12:15]
	v_mfma_f32_16x16x32_bf16 v[8:11], v[178:181], v[202:205], v[8:11]
	v_mfma_f32_16x16x32_bf16 v[4:7], v[170:173], v[210:213], v[4:7]
	v_mfma_f32_16x16x32_bf16 v[0:3], v[178:181], v[210:213], v[0:3]
	s_setprio 0
	s_barrier
	s_add_u32 s46, s46, 0x100
	s_addc_u32 s47, s47, 0
	s_add_u32 s64, s64, 0x100
	s_addc_u32 s65, s65, 0
	s_cmp_ge_i32 s66, s53
	s_mov_b32 s48, s66
	s_cbranch_scc0 .LBB0_1333
	v_pk_add_f32 v[126:127], v[126:127], 0 op_sel_hi:[1,0]
	v_pk_add_f32 v[124:125], v[124:125], 0 op_sel_hi:[1,0]
	v_pk_add_f32 v[122:123], v[122:123], 0 op_sel_hi:[1,0]
	v_pk_add_f32 v[120:121], v[120:121], 0 op_sel_hi:[1,0]
	v_pk_add_f32 v[144:145], v[110:111], 0 op_sel_hi:[1,0]
	v_pk_add_f32 v[146:147], v[108:109], 0 op_sel_hi:[1,0]
	v_pk_add_f32 v[148:149], v[102:103], 0 op_sel_hi:[1,0]
	v_pk_add_f32 v[150:151], v[100:101], 0 op_sel_hi:[1,0]
	v_pk_add_f32 v[100:101], v[118:119], 0 op_sel_hi:[1,0]
	v_pk_add_f32 v[102:103], v[116:117], 0 op_sel_hi:[1,0]
	v_pk_add_f32 v[108:109], v[114:115], 0 op_sel_hi:[1,0]
	v_pk_add_f32 v[110:111], v[112:113], 0 op_sel_hi:[1,0]
	v_pk_add_f32 v[112:113], v[94:95], 0 op_sel_hi:[1,0]
	v_pk_add_f32 v[114:115], v[92:93], 0 op_sel_hi:[1,0]
	v_pk_add_f32 v[116:117], v[86:87], 0 op_sel_hi:[1,0]
	v_pk_add_f32 v[118:119], v[84:85], 0 op_sel_hi:[1,0]
	v_pk_add_f32 v[84:85], v[106:107], 0 op_sel_hi:[1,0]
	v_pk_add_f32 v[86:87], v[104:105], 0 op_sel_hi:[1,0]
	v_pk_add_f32 v[92:93], v[98:99], 0 op_sel_hi:[1,0]
	v_pk_add_f32 v[94:95], v[96:97], 0 op_sel_hi:[1,0]
	v_pk_add_f32 v[96:97], v[78:79], 0 op_sel_hi:[1,0]
	v_pk_add_f32 v[98:99], v[76:77], 0 op_sel_hi:[1,0]
	v_pk_add_f32 v[104:105], v[74:75], 0 op_sel_hi:[1,0]
	v_pk_add_f32 v[106:107], v[72:73], 0 op_sel_hi:[1,0]
	v_pk_add_f32 v[72:73], v[90:91], 0 op_sel_hi:[1,0]
	v_pk_add_f32 v[74:75], v[88:89], 0 op_sel_hi:[1,0]
	v_pk_add_f32 v[76:77], v[82:83], 0 op_sel_hi:[1,0]
	v_pk_add_f32 v[78:79], v[80:81], 0 op_sel_hi:[1,0]
	v_pk_add_f32 v[70:71], v[70:71], 0 op_sel_hi:[1,0]
	v_pk_add_f32 v[68:69], v[68:69], 0 op_sel_hi:[1,0]
	v_pk_add_f32 v[66:67], v[66:67], 0 op_sel_hi:[1,0]
	v_pk_add_f32 v[64:65], v[64:65], 0 op_sel_hi:[1,0]
	v_pk_add_f32 v[62:63], v[62:63], 0 op_sel_hi:[1,0]
	v_pk_add_f32 v[60:61], v[60:61], 0 op_sel_hi:[1,0]
	v_pk_add_f32 v[58:59], v[58:59], 0 op_sel_hi:[1,0]
	v_pk_add_f32 v[56:57], v[56:57], 0 op_sel_hi:[1,0]
	v_pk_add_f32 v[80:81], v[46:47], 0 op_sel_hi:[1,0]
	v_pk_add_f32 v[82:83], v[44:45], 0 op_sel_hi:[1,0]
	v_pk_add_f32 v[88:89], v[38:39], 0 op_sel_hi:[1,0]
	v_pk_add_f32 v[90:91], v[36:37], 0 op_sel_hi:[1,0]
	v_pk_add_f32 v[36:37], v[54:55], 0 op_sel_hi:[1,0]
	v_pk_add_f32 v[38:39], v[52:53], 0 op_sel_hi:[1,0]
	v_pk_add_f32 v[44:45], v[50:51], 0 op_sel_hi:[1,0]
	v_pk_add_f32 v[46:47], v[48:49], 0 op_sel_hi:[1,0]
	v_pk_add_f32 v[48:49], v[30:31], 0 op_sel_hi:[1,0]
	v_pk_add_f32 v[50:51], v[28:29], 0 op_sel_hi:[1,0]
	v_pk_add_f32 v[52:53], v[22:23], 0 op_sel_hi:[1,0]
	v_pk_add_f32 v[54:55], v[20:21], 0 op_sel_hi:[1,0]
	v_pk_add_f32 v[20:21], v[42:43], 0 op_sel_hi:[1,0]
	v_pk_add_f32 v[22:23], v[40:41], 0 op_sel_hi:[1,0]
	v_pk_add_f32 v[28:29], v[34:35], 0 op_sel_hi:[1,0]
	v_pk_add_f32 v[30:31], v[32:33], 0 op_sel_hi:[1,0]
	v_pk_add_f32 v[32:33], v[14:15], 0 op_sel_hi:[1,0]
	v_pk_add_f32 v[34:35], v[12:13], 0 op_sel_hi:[1,0]
	v_pk_add_f32 v[40:41], v[10:11], 0 op_sel_hi:[1,0]
	v_pk_add_f32 v[42:43], v[8:9], 0 op_sel_hi:[1,0]
	v_pk_add_f32 v[8:9], v[26:27], 0 op_sel_hi:[1,0]
	v_pk_add_f32 v[10:11], v[24:25], 0 op_sel_hi:[1,0]
	v_pk_add_f32 v[12:13], v[18:19], 0 op_sel_hi:[1,0]
	v_pk_add_f32 v[14:15], v[16:17], 0 op_sel_hi:[1,0]
	v_pk_add_f32 v[6:7], v[6:7], 0 op_sel_hi:[1,0]
	v_pk_add_f32 v[4:5], v[4:5], 0 op_sel_hi:[1,0]
	v_pk_add_f32 v[2:3], v[2:3], 0 op_sel_hi:[1,0]
	v_pk_add_f32 v[0:1], v[0:1], 0 op_sel_hi:[1,0]

; #define PG8_STAGE(bufoff, gbase, voff) do { _Pragma("unroll") for (int _i = 0; _i < 2; ++_i) \
;         __builtin_amdgcn_global_load_lds((const unsigned*)((const char*)(gbase) + (voff)[_i]), (PG8_LAS unsigned*)(lds + (bufoff) + ldsw + _i * 8192), 16, 0, 0); } while (0)
; #define PG8_LDA(dst, b, h) do { _Pragma("unroll") for (int m = 0; m < 4; ++m) _Pragma("unroll") for (int k = 0; k < 2; ++k) dst[m][k] = *(const PG8_LAS bf16x8*)(lds + PG8_SA(b, h) + aoff + m * 2048 + k * 1024); } while (0)
; #define PG8_LDB(dst, b, h) do { _Pragma("unroll") for (int n = 0; n < 2; ++n) _Pragma("unroll") for (int k = 0; k < 2; ++k) dst[n][k] = *(const PG8_LAS bf16x8*)(lds + PG8_SB(b, h) + boff + n * 2048 + k * 1024); } while (0)
; #define PG8_MMA(ai, bj, At, Bt) do { __builtin_amdgcn_s_setprio(1); _Pragma("unroll") for (int m = 0; m < 4; ++m) _Pragma("unroll") for (int n = 0; n < 2; ++n) _Pragma("unroll") for (int k = 0; k < 2; ++k) \
;         acc[ai][bj][m][n] = __builtin_amdgcn_mfma_f32_16x16x32_bf16(Bt[n][k], At[m][k], acc[ai][bj][m][n], 0, 0, 0); __builtin_amdgcn_s_setprio(0); } while (0)
; #define PG8_WAIT_V(n) asm volatile("s_waitcnt vmcnt(" #n ")" ::: "memory")
; #define PG8_WAIT_L(n) asm volatile("s_waitcnt lgkmcnt(" #n ")" ::: "memory")
; template <class Epi, class Sched, bool ALIGN_EPI = false, bool SP2 = false>
; __device__ __forceinline__ void gemm_phase(PG8_LAS unsigned char* lds, const Gemm g, const Sched& S, const Epi& E) {
;     ...
;             const bool last = (t == nt - 2);
;             const char* a1 = cA + (long)(t + 1) * kstepA;
;             const char* a2 = last ? nA : cA + (long)(t + 2) * kstepA; const char* b2 = last ? nB : cB + (long)(t + 2) * kstep;
;             const char* a3 = a2 + kstepA; const char* b3 = b2 + kstep;
;             if (last && has_next) S.a_ready(nxt);
;             if constexpr (SP2) {
;             PG8_LDB(B0, 0, 0); PG8_LDB(B1, 0, 1); PG8_SCHED; PG8_LDA(At, 0, 0); PG8_STAGE(PG8_SA(1, 1), a1 + hstepA, voffA);
;             PG8_WAIT_V(8); PG8_WAIT_L(0); PG8_BAR; PG8_MMA(0, 0, At, B0); PG8_MMA(0, 1, At, B1); PG8_BAR; PG8_SCHED;
;             PG8_LDA(At, 0, 1); PG8_STAGE(PG8_SB(0, 0), b2, voffB); PG8_STAGE(PG8_SB(0, 1), b2 + hstepB, voffB); PG8_STAGE(PG8_SA(0, 0), a2, voffA);
;             PG8_WAIT_V(8); PG8_WAIT_L(0); PG8_BAR; PG8_MMA(1, 0, At, B0); PG8_MMA(1, 1, At, B1); PG8_BAR; PG8_SCHED;
.LBB0_1362:
	ds_read_b128 v[128:131], v183
	ds_read_b128 v[132:135], v183 offset:1024
	ds_read_b128 v[136:139], v183 offset:2048
	ds_read_b128 v[140:143], v183 offset:3072
	ds_read_b128 v[144:147], v187
	ds_read_b128 v[148:151], v187 offset:1024
	ds_read_b128 v[152:155], v187 offset:2048
	ds_read_b128 v[196:199], v187 offset:3072
	s_add_i32 s69, s50, 2
	s_add_u32 s51, s48, 0x3fc000
	s_addc_u32 s52, s49, 0
	s_cmp_eq_u32 s64, s50
	s_cselect_b32 s54, s9, s51
	s_cselect_b32 s55, s8, s52
	s_cselect_b32 s53, s11, s47
	s_cselect_b32 s52, s41, s43
	s_add_u32 s50, s54, 0x400000
	s_addc_u32 s51, s55, 0
	v_lshl_add_u64 v[180:181], s[48:49], 0, v[166:167]
	s_add_i32 m0, s19, 0xc000
	ds_read_b128 v[200:203], v191
	ds_read_b128 v[204:207], v191 offset:1024
	ds_read_b128 v[208:211], v191 offset:2048
	ds_read_b128 v[212:215], v191 offset:3072
	ds_read_b128 v[216:219], v191 offset:4096
	ds_read_b128 v[220:223], v191 offset:5120
	ds_read_b128 v[224:227], v191 offset:6144
	ds_read_b128 v[228:231], v191 offset:7168
	global_load_lds_dwordx4 v[180:181], off
	v_lshl_add_u64 v[180:181], s[48:49], 0, v[168:169]
	s_add_i32 m0, s19, 0xe000
	s_nop 0
	global_load_lds_dwordx4 v[180:181], off
	s_waitcnt vmcnt(8)
	s_waitcnt lgkmcnt(0)
	s_barrier
	s_setprio 1
	v_mfma_f32_16x16x32_bf16 v[124:127], v[128:131], v[200:203], v[124:127]
	v_mfma_f32_16x16x32_bf16 v[120:123], v[136:139], v[200:203], v[120:123]
	v_mfma_f32_16x16x32_bf16 v[116:119], v[128:131], v[208:211], v[116:119]
	v_mfma_f32_16x16x32_bf16 v[112:115], v[136:139], v[208:211], v[112:115]
	v_mfma_f32_16x16x32_bf16 v[108:111], v[128:131], v[216:219], v[108:111]
	v_mfma_f32_16x16x32_bf16 v[104:107], v[136:139], v[216:219], v[104:107]
	v_mfma_f32_16x16x32_bf16 v[100:103], v[128:131], v[224:227], v[100:103]
	v_mfma_f32_16x16x32_bf16 v[96:99], v[136:139], v[224:227], v[96:99]
	v_mfma_f32_16x16x32_bf16 v[124:127], v[132:135], v[204:207], v[124:127]
	v_mfma_f32_16x16x32_bf16 v[120:123], v[140:143], v[204:207], v[120:123]
	v_mfma_f32_16x16x32_bf16 v[116:119], v[132:135], v[212:215], v[116:119]
	v_mfma_f32_16x16x32_bf16 v[112:115], v[140:143], v[212:215], v[112:115]
	v_mfma_f32_16x16x32_bf16 v[108:111], v[132:135], v[220:223], v[108:111]
	v_mfma_f32_16x16x32_bf16 v[104:107], v[140:143], v[220:223], v[104:107]
	v_mfma_f32_16x16x32_bf16 v[100:103], v[132:135], v[228:231], v[100:103]
	v_mfma_f32_16x16x32_bf16 v[96:99], v[140:143], v[228:231], v[96:99]
	v_mfma_f32_16x16x32_bf16 v[60:63], v[144:147], v[200:203], v[60:63]
	v_mfma_f32_16x16x32_bf16 v[56:59], v[152:155], v[200:203], v[56:59]
	v_mfma_f32_16x16x32_bf16 v[52:55], v[144:147], v[208:211], v[52:55]
	v_mfma_f32_16x16x32_bf16 v[48:51], v[152:155], v[208:211], v[48:51]
	v_mfma_f32_16x16x32_bf16 v[44:47], v[144:147], v[216:219], v[44:47]
	v_mfma_f32_16x16x32_bf16 v[40:43], v[152:155], v[216:219], v[40:43]
	v_mfma_f32_16x16x32_bf16 v[36:39], v[144:147], v[224:227], v[36:39]
	v_mfma_f32_16x16x32_bf16 v[32:35], v[152:155], v[224:227], v[32:35]
	v_mfma_f32_16x16x32_bf16 v[60:63], v[148:151], v[204:207], v[60:63]
	v_mfma_f32_16x16x32_bf16 v[56:59], v[196:199], v[204:207], v[56:59]
	v_mfma_f32_16x16x32_bf16 v[52:55], v[148:151], v[212:215], v[52:55]
	v_mfma_f32_16x16x32_bf16 v[48:51], v[196:199], v[212:215], v[48:51]
	v_mfma_f32_16x16x32_bf16 v[44:47], v[148:151], v[220:223], v[44:47]
	v_mfma_f32_16x16x32_bf16 v[40:43], v[196:199], v[220:223], v[40:43]
	v_mfma_f32_16x16x32_bf16 v[36:39], v[148:151], v[228:231], v[36:39]
	v_mfma_f32_16x16x32_bf16 v[32:35], v[196:199], v[228:231], v[32:35]
	s_setprio 0
	s_barrier
	s_add_i32 s70, s67, s16
	v_lshl_add_u64 v[180:181], s[52:53], 0, v[158:159]
	s_mov_b32 m0, s70
	ds_read_b128 v[200:203], v191 offset:16384
	ds_read_b128 v[204:207], v191 offset:17408
	ds_read_b128 v[208:211], v191 offset:18432
	ds_read_b128 v[212:215], v191 offset:19456
	ds_read_b128 v[216:219], v191 offset:20480
	ds_read_b128 v[220:223], v191 offset:21504
	ds_read_b128 v[224:227], v191 offset:22528
	ds_read_b128 v[228:231], v191 offset:23552
	global_load_lds_dwordx4 v[180:181], off
	s_add_i32 m0, s70, 0x2000
	s_add_u32 s70, s52, 0x4000
	v_lshl_add_u64 v[180:181], s[52:53], 0, v[162:163]
	s_addc_u32 s71, s53, 0
	s_add_i32 s72, s68, s16
	global_load_lds_dwordx4 v[180:181], off
	v_lshl_add_u64 v[180:181], s[70:71], 0, v[158:159]
	s_mov_b32 m0, s72
	s_nop 0
	global_load_lds_dwordx4 v[180:181], off
	v_lshl_add_u64 v[180:181], s[70:71], 0, v[162:163]
	s_add_i32 m0, s72, 0x2000
	s_nop 0
	global_load_lds_dwordx4 v[180:181], off
	v_lshl_add_u64 v[180:181], s[54:55], 0, v[156:157]
	s_mov_b32 m0, s19
	s_nop 0
	global_load_lds_dwordx4 v[180:181], off
	v_lshl_add_u64 v[180:181], s[54:55], 0, v[160:161]
	s_mov_b32 m0, s33
	s_nop 0
	global_load_lds_dwordx4 v[180:181], off
	s_waitcnt vmcnt(8)
	s_waitcnt lgkmcnt(0)
	s_barrier
; #define PG8_STAGE(bufoff, gbase, voff) do { _Pragma("unroll") for (int _i = 0; _i < 2; ++_i) \
;         __builtin_amdgcn_global_load_lds((const unsigned*)((const char*)(gbase) + (voff)[_i]), (PG8_LAS unsigned*)(lds + (bufoff) + ldsw + _i * 8192), 16, 0, 0); } while (0)
; #define PG8_LDA(dst, b, h) do { _Pragma("unroll") for (int m = 0; m < 4; ++m) _Pragma("unroll") for (int k = 0; k < 2; ++k) dst[m][k] = *(const PG8_LAS bf16x8*)(lds + PG8_SA(b, h) + aoff + m * 2048 + k * 1024); } while (0)
; #define PG8_LDB(dst, b, h) do { _Pragma("unroll") for (int n = 0; n < 2; ++n) _Pragma("unroll") for (int k = 0; k < 2; ++k) dst[n][k] = *(const PG8_LAS bf16x8*)(lds + PG8_SB(b, h) + boff + n * 2048 + k * 1024); } while (0)
; #define PG8_MMA(ai, bj, At, Bt) do { __builtin_amdgcn_s_setprio(1); _Pragma("unroll") for (int m = 0; m < 4; ++m) _Pragma("unroll") for (int n = 0; n < 2; ++n) _Pragma("unroll") for (int k = 0; k < 2; ++k) \
;         acc[ai][bj][m][n] = __builtin_amdgcn_mfma_f32_16x16x32_bf16(Bt[n][k], At[m][k], acc[ai][bj][m][n], 0, 0, 0); __builtin_amdgcn_s_setprio(0); } while (0)
; #define PG8_WAIT_V(n) asm volatile("s_waitcnt vmcnt(" #n ")" ::: "memory")
; #define PG8_WAIT_L(n) asm volatile("s_waitcnt lgkmcnt(" #n ")" ::: "memory")
; #define PG8_BAR __builtin_amdgcn_s_barrier()
; #define PG8_SCHED __builtin_amdgcn_sched_barrier(0)
; template <class Epi, class Sched, bool ALIGN_EPI = false, bool SP2 = false>
; __device__ __forceinline__ void gemm_phase(PG8_LAS unsigned char* lds, const Gemm g, const Sched& S, const Epi& E) {
;     ...
;             PG8_WAIT_V(8); PG8_WAIT_L(0); PG8_BAR; PG8_MMA(1, 0, At, B0); PG8_MMA(1, 1, At, B1); PG8_BAR; PG8_SCHED;
;             PG8_LDB(B0, 1, 0); PG8_LDB(B1, 1, 1); PG8_SCHED; PG8_LDA(At, 1, 0); PG8_STAGE(PG8_SA(0, 1), a2 + hstepA, voffA);
;             PG8_WAIT_V(8); PG8_WAIT_L(0); PG8_BAR; PG8_MMA(0, 0, At, B0); PG8_MMA(0, 1, At, B1); PG8_BAR; PG8_SCHED;
	s_setprio 1
	v_mfma_f32_16x16x32_bf16 v[92:95], v[128:131], v[200:203], v[92:95]
	v_mfma_f32_16x16x32_bf16 v[88:91], v[136:139], v[200:203], v[88:91]
	v_mfma_f32_16x16x32_bf16 v[84:87], v[128:131], v[208:211], v[84:87]
	v_mfma_f32_16x16x32_bf16 v[80:83], v[136:139], v[208:211], v[80:83]
	v_mfma_f32_16x16x32_bf16 v[76:79], v[128:131], v[216:219], v[76:79]
	v_mfma_f32_16x16x32_bf16 v[72:75], v[136:139], v[216:219], v[72:75]
	v_mfma_f32_16x16x32_bf16 v[68:71], v[128:131], v[224:227], v[68:71]
	v_mfma_f32_16x16x32_bf16 v[64:67], v[136:139], v[224:227], v[64:67]
	v_mfma_f32_16x16x32_bf16 v[92:95], v[132:135], v[204:207], v[92:95]
	v_mfma_f32_16x16x32_bf16 v[88:91], v[140:143], v[204:207], v[88:91]
	v_mfma_f32_16x16x32_bf16 v[84:87], v[132:135], v[212:215], v[84:87]
	v_mfma_f32_16x16x32_bf16 v[80:83], v[140:143], v[212:215], v[80:83]
	v_mfma_f32_16x16x32_bf16 v[76:79], v[132:135], v[220:223], v[76:79]
	v_mfma_f32_16x16x32_bf16 v[72:75], v[140:143], v[220:223], v[72:75]
	v_mfma_f32_16x16x32_bf16 v[68:71], v[132:135], v[228:231], v[68:71]
	v_mfma_f32_16x16x32_bf16 v[64:67], v[140:143], v[228:231], v[64:67]
	v_mfma_f32_16x16x32_bf16 v[28:31], v[144:147], v[200:203], v[28:31]
	v_mfma_f32_16x16x32_bf16 v[24:27], v[152:155], v[200:203], v[24:27]
	v_mfma_f32_16x16x32_bf16 v[20:23], v[144:147], v[208:211], v[20:23]
	v_mfma_f32_16x16x32_bf16 v[16:19], v[152:155], v[208:211], v[16:19]
	v_mfma_f32_16x16x32_bf16 v[12:15], v[144:147], v[216:219], v[12:15]
	v_mfma_f32_16x16x32_bf16 v[8:11], v[152:155], v[216:219], v[8:11]
	v_mfma_f32_16x16x32_bf16 v[4:7], v[144:147], v[224:227], v[4:7]
	v_mfma_f32_16x16x32_bf16 v[0:3], v[152:155], v[224:227], v[0:3]
	v_mfma_f32_16x16x32_bf16 v[28:31], v[148:151], v[204:207], v[28:31]
	v_mfma_f32_16x16x32_bf16 v[24:27], v[196:199], v[204:207], v[24:27]
	v_mfma_f32_16x16x32_bf16 v[20:23], v[148:151], v[212:215], v[20:23]
	v_mfma_f32_16x16x32_bf16 v[16:19], v[196:199], v[212:215], v[16:19]
	v_mfma_f32_16x16x32_bf16 v[12:15], v[148:151], v[220:223], v[12:15]
	v_mfma_f32_16x16x32_bf16 v[8:11], v[196:199], v[220:223], v[8:11]
	v_mfma_f32_16x16x32_bf16 v[4:7], v[148:151], v[228:231], v[4:7]
	v_mfma_f32_16x16x32_bf16 v[0:3], v[196:199], v[228:231], v[0:3]
	s_setprio 0
	s_barrier
	s_add_i32 s70, 0, 0x18000
	s_add_i32 s71, 0, 0x1c000
	v_add_u32_e32 v140, s70, v179
	v_add_u32_e32 v165, s71, v179
	ds_read_b128 v[128:131], v140
	ds_read_b128 v[132:135], v140 offset:1024
	ds_read_b128 v[136:139], v140 offset:2048
	ds_read_b128 v[140:143], v140 offset:3072
	ds_read_b128 v[144:147], v165
	ds_read_b128 v[148:151], v165 offset:1024
	ds_read_b128 v[152:155], v165 offset:2048
	ds_read_b128 v[196:199], v165 offset:3072
	s_add_u32 s54, s54, 0x4000
	s_addc_u32 s55, s55, 0
	s_mov_b32 m0, s35
	v_lshl_add_u64 v[180:181], s[54:55], 0, v[156:157]
	ds_read_b128 v[200:203], v191 offset:32768
	ds_read_b128 v[204:207], v191 offset:33792
	ds_read_b128 v[208:211], v191 offset:34816
	ds_read_b128 v[212:215], v191 offset:35840
	ds_read_b128 v[216:219], v191 offset:36864
	ds_read_b128 v[220:223], v191 offset:37888
	ds_read_b128 v[224:227], v191 offset:38912
	ds_read_b128 v[228:231], v191 offset:39936
	global_load_lds_dwordx4 v[180:181], off
	v_lshl_add_u64 v[180:181], s[54:55], 0, v[160:161]
	s_mov_b32 m0, s57
	s_nop 0
	global_load_lds_dwordx4 v[180:181], off
	s_waitcnt vmcnt(8)
	s_waitcnt lgkmcnt(0)
	s_barrier
	s_setprio 1
	v_mfma_f32_16x16x32_bf16 v[124:127], v[128:131], v[200:203], v[124:127]
	v_mfma_f32_16x16x32_bf16 v[120:123], v[136:139], v[200:203], v[120:123]
	v_mfma_f32_16x16x32_bf16 v[116:119], v[128:131], v[208:211], v[116:119]
	v_mfma_f32_16x16x32_bf16 v[112:115], v[136:139], v[208:211], v[112:115]
	v_mfma_f32_16x16x32_bf16 v[108:111], v[128:131], v[216:219], v[108:111]
	v_mfma_f32_16x16x32_bf16 v[104:107], v[136:139], v[216:219], v[104:107]
	v_mfma_f32_16x16x32_bf16 v[100:103], v[128:131], v[224:227], v[100:103]
	v_mfma_f32_16x16x32_bf16 v[96:99], v[136:139], v[224:227], v[96:99]
	v_mfma_f32_16x16x32_bf16 v[124:127], v[132:135], v[204:207], v[124:127]
	v_mfma_f32_16x16x32_bf16 v[120:123], v[140:143], v[204:207], v[120:123]
	v_mfma_f32_16x16x32_bf16 v[116:119], v[132:135], v[212:215], v[116:119]
	v_mfma_f32_16x16x32_bf16 v[112:115], v[140:143], v[212:215], v[112:115]
	v_mfma_f32_16x16x32_bf16 v[108:111], v[132:135], v[220:223], v[108:111]
	v_mfma_f32_16x16x32_bf16 v[104:107], v[140:143], v[220:223], v[104:107]
	v_mfma_f32_16x16x32_bf16 v[100:103], v[132:135], v[228:231], v[100:103]
	v_mfma_f32_16x16x32_bf16 v[96:99], v[140:143], v[228:231], v[96:99]
	v_mfma_f32_16x16x32_bf16 v[60:63], v[144:147], v[200:203], v[60:63]
	v_mfma_f32_16x16x32_bf16 v[56:59], v[152:155], v[200:203], v[56:59]
	v_mfma_f32_16x16x32_bf16 v[52:55], v[144:147], v[208:211], v[52:55]
	v_mfma_f32_16x16x32_bf16 v[48:51], v[152:155], v[208:211], v[48:51]
	v_mfma_f32_16x16x32_bf16 v[44:47], v[144:147], v[216:219], v[44:47]
	v_mfma_f32_16x16x32_bf16 v[40:43], v[152:155], v[216:219], v[40:43]
	v_mfma_f32_16x16x32_bf16 v[36:39], v[144:147], v[224:227], v[36:39]
	v_mfma_f32_16x16x32_bf16 v[32:35], v[152:155], v[224:227], v[32:35]
	v_mfma_f32_16x16x32_bf16 v[60:63], v[148:151], v[204:207], v[60:63]
	v_mfma_f32_16x16x32_bf16 v[56:59], v[196:199], v[204:207], v[56:59]
	v_mfma_f32_16x16x32_bf16 v[52:55], v[148:151], v[212:215], v[52:55]
	v_mfma_f32_16x16x32_bf16 v[48:51], v[196:199], v[212:215], v[48:51]
	v_mfma_f32_16x16x32_bf16 v[44:47], v[148:151], v[220:223], v[44:47]
	v_mfma_f32_16x16x32_bf16 v[40:43], v[196:199], v[220:223], v[40:43]
	v_mfma_f32_16x16x32_bf16 v[36:39], v[148:151], v[228:231], v[36:39]
	v_mfma_f32_16x16x32_bf16 v[32:35], v[196:199], v[228:231], v[32:35]
	s_setprio 0
	s_barrier
; #define PG8_STAGE(bufoff, gbase, voff) do { _Pragma("unroll") for (int _i = 0; _i < 2; ++_i) \
;         __builtin_amdgcn_global_load_lds((const unsigned*)((const char*)(gbase) + (voff)[_i]), (PG8_LAS unsigned*)(lds + (bufoff) + ldsw + _i * 8192), 16, 0, 0); } while (0)
; #define PG8_LDA(dst, b, h) do { _Pragma("unroll") for (int m = 0; m < 4; ++m) _Pragma("unroll") for (int k = 0; k < 2; ++k) dst[m][k] = *(const PG8_LAS bf16x8*)(lds + PG8_SA(b, h) + aoff + m * 2048 + k * 1024); } while (0)
; #define PG8_MMA(ai, bj, At, Bt) do { __builtin_amdgcn_s_setprio(1); _Pragma("unroll") for (int m = 0; m < 4; ++m) _Pragma("unroll") for (int n = 0; n < 2; ++n) _Pragma("unroll") for (int k = 0; k < 2; ++k) \
;         acc[ai][bj][m][n] = __builtin_amdgcn_mfma_f32_16x16x32_bf16(Bt[n][k], At[m][k], acc[ai][bj][m][n], 0, 0, 0); __builtin_amdgcn_s_setprio(0); } while (0)
; #define PG8_WAIT_V(n) asm volatile("s_waitcnt vmcnt(" #n ")" ::: "memory")
; #define PG8_WAIT_L(n) asm volatile("s_waitcnt lgkmcnt(" #n ")" ::: "memory")
; #define PG8_BAR __builtin_amdgcn_s_barrier()
; #define PG8_SCHED __builtin_amdgcn_sched_barrier(0)
; template <class Epi, class Sched, bool ALIGN_EPI = false, bool SP2 = false>
; __device__ __forceinline__ void gemm_phase(PG8_LAS unsigned char* lds, const Gemm g, const Sched& S, const Epi& E) {
;     ...
;             PG8_LDA(At, 1, 1); PG8_STAGE(PG8_SB(1, 0), b3, voffB); PG8_STAGE(PG8_SB(1, 1), b3 + hstepB, voffB); PG8_STAGE(PG8_SA(1, 0), a3, voffA);
;             PG8_WAIT_V(8); PG8_WAIT_L(0); PG8_BAR; PG8_MMA(1, 0, At, B0); PG8_MMA(1, 1, At, B1); PG8_BAR; PG8_SCHED;
	s_add_u32 s54, s52, 0x20000
	s_addc_u32 s55, s53, 0
	s_add_i32 s70, s70, s16
	v_lshl_add_u64 v[180:181], s[54:55], 0, v[158:159]
	s_mov_b32 m0, s70
	ds_read_b128 v[200:203], v191 offset:49152
	ds_read_b128 v[204:207], v191 offset:50176
	ds_read_b128 v[208:211], v191 offset:51200
	ds_read_b128 v[212:215], v191 offset:52224
	ds_read_b128 v[216:219], v191 offset:53248
	ds_read_b128 v[220:223], v191 offset:54272
	ds_read_b128 v[224:227], v191 offset:55296
	ds_read_b128 v[228:231], v191 offset:56320
	global_load_lds_dwordx4 v[180:181], off
	s_add_i32 m0, s70, 0x2000
	s_add_u32 s52, s52, 0x24000
	v_lshl_add_u64 v[180:181], s[54:55], 0, v[162:163]
	s_addc_u32 s53, s53, 0
	s_add_i32 s54, s71, s16
	global_load_lds_dwordx4 v[180:181], off
	v_lshl_add_u64 v[180:181], s[52:53], 0, v[158:159]
	s_mov_b32 m0, s54
	s_nop 0
	global_load_lds_dwordx4 v[180:181], off
	v_lshl_add_u64 v[180:181], s[52:53], 0, v[162:163]
	s_add_i32 m0, s54, 0x2000
	s_nop 0
	global_load_lds_dwordx4 v[180:181], off
	v_lshl_add_u64 v[180:181], s[50:51], 0, v[156:157]
	s_mov_b32 m0, s62
	s_nop 0
	global_load_lds_dwordx4 v[180:181], off
	v_lshl_add_u64 v[180:181], s[50:51], 0, v[160:161]
	s_mov_b32 m0, s63
	s_nop 0
	global_load_lds_dwordx4 v[180:181], off
	s_waitcnt vmcnt(8)
	s_waitcnt lgkmcnt(0)
	s_barrier
	s_setprio 1
	v_mfma_f32_16x16x32_bf16 v[92:95], v[128:131], v[200:203], v[92:95]
	v_mfma_f32_16x16x32_bf16 v[88:91], v[136:139], v[200:203], v[88:91]
	v_mfma_f32_16x16x32_bf16 v[84:87], v[128:131], v[208:211], v[84:87]
	v_mfma_f32_16x16x32_bf16 v[80:83], v[136:139], v[208:211], v[80:83]
	v_mfma_f32_16x16x32_bf16 v[76:79], v[128:131], v[216:219], v[76:79]
	v_mfma_f32_16x16x32_bf16 v[72:75], v[136:139], v[216:219], v[72:75]
	v_mfma_f32_16x16x32_bf16 v[68:71], v[128:131], v[224:227], v[68:71]
	v_mfma_f32_16x16x32_bf16 v[64:67], v[136:139], v[224:227], v[64:67]
	v_mfma_f32_16x16x32_bf16 v[92:95], v[132:135], v[204:207], v[92:95]
	v_mfma_f32_16x16x32_bf16 v[88:91], v[140:143], v[204:207], v[88:91]
	v_mfma_f32_16x16x32_bf16 v[84:87], v[132:135], v[212:215], v[84:87]
	v_mfma_f32_16x16x32_bf16 v[80:83], v[140:143], v[212:215], v[80:83]
	v_mfma_f32_16x16x32_bf16 v[76:79], v[132:135], v[220:223], v[76:79]
	v_mfma_f32_16x16x32_bf16 v[72:75], v[140:143], v[220:223], v[72:75]
	v_mfma_f32_16x16x32_bf16 v[68:71], v[132:135], v[228:231], v[68:71]
	v_mfma_f32_16x16x32_bf16 v[64:67], v[140:143], v[228:231], v[64:67]
	v_mfma_f32_16x16x32_bf16 v[28:31], v[144:147], v[200:203], v[28:31]
	v_mfma_f32_16x16x32_bf16 v[24:27], v[152:155], v[200:203], v[24:27]
	v_mfma_f32_16x16x32_bf16 v[20:23], v[144:147], v[208:211], v[20:23]
	v_mfma_f32_16x16x32_bf16 v[16:19], v[152:155], v[208:211], v[16:19]
	v_mfma_f32_16x16x32_bf16 v[12:15], v[144:147], v[216:219], v[12:15]
	v_mfma_f32_16x16x32_bf16 v[8:11], v[152:155], v[216:219], v[8:11]
	v_mfma_f32_16x16x32_bf16 v[4:7], v[144:147], v[224:227], v[4:7]
	v_mfma_f32_16x16x32_bf16 v[0:3], v[152:155], v[224:227], v[0:3]
	v_mfma_f32_16x16x32_bf16 v[28:31], v[148:151], v[204:207], v[28:31]
	v_mfma_f32_16x16x32_bf16 v[24:27], v[196:199], v[204:207], v[24:27]
	v_mfma_f32_16x16x32_bf16 v[20:23], v[148:151], v[212:215], v[20:23]
	v_mfma_f32_16x16x32_bf16 v[16:19], v[196:199], v[212:215], v[16:19]
	v_mfma_f32_16x16x32_bf16 v[12:15], v[148:151], v[220:223], v[12:15]
	v_mfma_f32_16x16x32_bf16 v[8:11], v[196:199], v[220:223], v[8:11]
	v_mfma_f32_16x16x32_bf16 v[4:7], v[148:151], v[228:231], v[4:7]
	v_mfma_f32_16x16x32_bf16 v[0:3], v[196:199], v[228:231], v[0:3]
	s_setprio 0
	s_barrier
	s_add_u32 s43, s43, 0x40000
	s_addc_u32 s47, s47, 0
	s_add_u32 s48, s48, 0x800000
	s_addc_u32 s49, s49, 0
	s_cmp_ge_i32 s69, s59
	s_mov_b32 s50, s69
	s_cbranch_scc0 .LBB0_1362

; #define PG8_STAGE(bufoff, gbase, voff) do { _Pragma("unroll") for (int _i = 0; _i < 2; ++_i) \
;         __builtin_amdgcn_global_load_lds((const unsigned*)((const char*)(gbase) + (voff)[_i]), (PG8_LAS unsigned*)(lds + (bufoff) + ldsw + _i * 8192), 16, 0, 0); } while (0)
; #define PG8_LDA(dst, b, h) do { _Pragma("unroll") for (int m = 0; m < 4; ++m) _Pragma("unroll") for (int k = 0; k < 2; ++k) dst[m][k] = *(const PG8_LAS bf16x8*)(lds + PG8_SA(b, h) + aoff + m * 2048 + k * 1024); } while (0)
; #define PG8_LDB(dst, b, h) do { _Pragma("unroll") for (int n = 0; n < 2; ++n) _Pragma("unroll") for (int k = 0; k < 2; ++k) dst[n][k] = *(const PG8_LAS bf16x8*)(lds + PG8_SB(b, h) + boff + n * 2048 + k * 1024); } while (0)
; #define PG8_MMA(ai, bj, At, Bt) do { __builtin_amdgcn_s_setprio(1); _Pragma("unroll") for (int m = 0; m < 4; ++m) _Pragma("unroll") for (int n = 0; n < 2; ++n) _Pragma("unroll") for (int k = 0; k < 2; ++k) \
;         acc[ai][bj][m][n] = __builtin_amdgcn_mfma_f32_16x16x32_bf16(Bt[n][k], At[m][k], acc[ai][bj][m][n], 0, 0, 0); __builtin_amdgcn_s_setprio(0); } while (0)
; #define PG8_WAIT_V(n) asm volatile("s_waitcnt vmcnt(" #n ")" ::: "memory")
; #define PG8_WAIT_L(n) asm volatile("s_waitcnt lgkmcnt(" #n ")" ::: "memory")
; template <class Epi, class Sched, bool ALIGN_EPI = false, bool SP2 = false>
; __device__ __forceinline__ void gemm_phase(PG8_LAS unsigned char* lds, const Gemm g, const Sched& S, const Epi& E) {
;     ...
;             const bool last = (t == nt - 2);
;             const char* a1 = cA + (long)(t + 1) * kstepA;
;             const char* a2 = last ? nA : cA + (long)(t + 2) * kstepA; const char* b2 = last ? nB : cB + (long)(t + 2) * kstep;
;             const char* a3 = a2 + kstepA; const char* b3 = b2 + kstep;
;             if (last && has_next) S.a_ready(nxt);
;             if constexpr (SP2) {
;             PG8_LDB(B0, 0, 0); PG8_LDB(B1, 0, 1); PG8_SCHED; PG8_LDA(At, 0, 0); PG8_STAGE(PG8_SA(1, 1), a1 + hstepA, voffA);
;             PG8_WAIT_V(8); PG8_WAIT_L(0); PG8_BAR; PG8_MMA(0, 0, At, B0); PG8_MMA(0, 1, At, B1); PG8_BAR; PG8_SCHED;
;             PG8_LDA(At, 0, 1); PG8_STAGE(PG8_SB(0, 0), b2, voffB); PG8_STAGE(PG8_SB(0, 1), b2 + hstepB, voffB); PG8_STAGE(PG8_SA(0, 0), a2, voffA);
;             PG8_WAIT_V(8); PG8_WAIT_L(0); PG8_BAR; PG8_MMA(1, 0, At, B0); PG8_MMA(1, 1, At, B1); PG8_BAR; PG8_SCHED;
.LBB0_1455:
	ds_read_b128 v[104:107], v199
	ds_read_b128 v[108:111], v199 offset:1024
	ds_read_b128 v[112:115], v199 offset:2048
	ds_read_b128 v[116:119], v199 offset:3072
	ds_read_b128 v[120:123], v203
	ds_read_b128 v[124:127], v203 offset:1024
	ds_read_b128 v[136:139], v203 offset:2048
	ds_read_b128 v[140:143], v203 offset:3072
	s_add_i32 s21, s20, 2
	s_add_u32 s22, s12, 0xfffc0080
	s_addc_u32 s23, s13, -1
	s_cmp_eq_u32 s72, s20
	s_cselect_b32 s25, s14, s23
	s_cselect_b32 s24, s15, s22
	s_cselect_b32 s23, s16, s19
	s_cselect_b32 s22, s17, s18
	v_lshl_add_u64 v[184:185], s[12:13], 0, v[180:181]
	s_add_i32 m0, s34, 0xc000
	ds_read_b128 v[160:163], v207
	ds_read_b128 v[164:167], v207 offset:1024
	ds_read_b128 v[168:171], v207 offset:2048
	ds_read_b128 v[208:211], v207 offset:3072
	ds_read_b128 v[212:215], v207 offset:4096
	ds_read_b128 v[216:219], v207 offset:5120
	ds_read_b128 v[220:223], v207 offset:6144
	ds_read_b128 v[224:227], v207 offset:7168
	global_load_lds_dwordx4 v[184:185], off
	v_lshl_add_u64 v[184:185], s[12:13], 0, v[182:183]
	s_add_i32 m0, s34, 0xe000
	s_nop 0
	global_load_lds_dwordx4 v[184:185], off
	s_waitcnt vmcnt(8)
	s_waitcnt lgkmcnt(0)
	s_barrier
	s_setprio 1
	v_mfma_f32_16x16x32_bf16 v[156:159], v[104:107], v[160:163], v[156:159]
	v_mfma_f32_16x16x32_bf16 v[152:155], v[112:115], v[160:163], v[152:155]
	v_mfma_f32_16x16x32_bf16 v[148:151], v[104:107], v[168:171], v[148:151]
	v_mfma_f32_16x16x32_bf16 v[144:147], v[112:115], v[168:171], v[144:147]
	v_mfma_f32_16x16x32_bf16 v[132:135], v[104:107], v[212:215], v[132:135]
	v_mfma_f32_16x16x32_bf16 v[128:131], v[112:115], v[212:215], v[128:131]
	v_mfma_f32_16x16x32_bf16 v[100:103], v[104:107], v[220:223], v[100:103]
	v_mfma_f32_16x16x32_bf16 v[96:99], v[112:115], v[220:223], v[96:99]
	v_mfma_f32_16x16x32_bf16 v[156:159], v[108:111], v[164:167], v[156:159]
	v_mfma_f32_16x16x32_bf16 v[152:155], v[116:119], v[164:167], v[152:155]
	v_mfma_f32_16x16x32_bf16 v[148:151], v[108:111], v[208:211], v[148:151]
	v_mfma_f32_16x16x32_bf16 v[144:147], v[116:119], v[208:211], v[144:147]
	v_mfma_f32_16x16x32_bf16 v[132:135], v[108:111], v[216:219], v[132:135]
	v_mfma_f32_16x16x32_bf16 v[128:131], v[116:119], v[216:219], v[128:131]
	v_mfma_f32_16x16x32_bf16 v[100:103], v[108:111], v[224:227], v[100:103]
	v_mfma_f32_16x16x32_bf16 v[96:99], v[116:119], v[224:227], v[96:99]
	v_mfma_f32_16x16x32_bf16 v[60:63], v[120:123], v[160:163], v[60:63]
	v_mfma_f32_16x16x32_bf16 v[56:59], v[136:139], v[160:163], v[56:59]
	v_mfma_f32_16x16x32_bf16 v[52:55], v[120:123], v[168:171], v[52:55]
	v_mfma_f32_16x16x32_bf16 v[48:51], v[136:139], v[168:171], v[48:51]
	v_mfma_f32_16x16x32_bf16 v[44:47], v[120:123], v[212:215], v[44:47]
	v_mfma_f32_16x16x32_bf16 v[40:43], v[136:139], v[212:215], v[40:43]
	v_mfma_f32_16x16x32_bf16 v[36:39], v[120:123], v[220:223], v[36:39]
	v_mfma_f32_16x16x32_bf16 v[32:35], v[136:139], v[220:223], v[32:35]
	v_mfma_f32_16x16x32_bf16 v[60:63], v[124:127], v[164:167], v[60:63]
	v_mfma_f32_16x16x32_bf16 v[56:59], v[140:143], v[164:167], v[56:59]
	v_mfma_f32_16x16x32_bf16 v[52:55], v[124:127], v[208:211], v[52:55]
	v_mfma_f32_16x16x32_bf16 v[48:51], v[140:143], v[208:211], v[48:51]
	v_mfma_f32_16x16x32_bf16 v[44:47], v[124:127], v[216:219], v[44:47]
	v_mfma_f32_16x16x32_bf16 v[40:43], v[140:143], v[216:219], v[40:43]
	v_mfma_f32_16x16x32_bf16 v[36:39], v[124:127], v[224:227], v[36:39]
	v_mfma_f32_16x16x32_bf16 v[32:35], v[140:143], v[224:227], v[32:35]
	s_setprio 0
	s_barrier
	s_add_i32 s20, s76, s31
	v_lshl_add_u64 v[184:185], s[22:23], 0, v[174:175]
	s_mov_b32 m0, s20
	ds_read_b128 v[160:163], v207 offset:16384
	ds_read_b128 v[164:167], v207 offset:17408
	ds_read_b128 v[168:171], v207 offset:18432
	ds_read_b128 v[208:211], v207 offset:19456
	ds_read_b128 v[212:215], v207 offset:20480
	ds_read_b128 v[216:219], v207 offset:21504
	ds_read_b128 v[220:223], v207 offset:22528
	ds_read_b128 v[224:227], v207 offset:23552
	global_load_lds_dwordx4 v[184:185], off
	s_add_i32 m0, s20, 0x2000
	s_add_u32 s70, s22, 0x40000
	v_lshl_add_u64 v[188:189], s[22:23], 0, v[178:179]
	s_addc_u32 s71, s23, 0
	s_add_i32 s20, s77, s31
	global_load_lds_dwordx4 v[188:189], off
	v_lshl_add_u64 v[192:193], s[70:71], 0, v[174:175]
	s_mov_b32 m0, s20
	v_lshl_add_u64 v[196:197], s[24:25], 0, v[176:177]
	global_load_lds_dwordx4 v[192:193], off
	v_lshl_add_u64 v[192:193], s[70:71], 0, v[178:179]
	s_add_i32 m0, s20, 0x2000
	s_nop 0
	global_load_lds_dwordx4 v[192:193], off
	v_lshl_add_u64 v[192:193], s[24:25], 0, v[172:173]
	s_mov_b32 m0, s34
	s_nop 0
	global_load_lds_dwordx4 v[192:193], off
	s_mov_b32 m0, s35
	s_nop 0
	global_load_lds_dwordx4 v[196:197], off
	s_waitcnt vmcnt(8)
	s_waitcnt lgkmcnt(0)
	s_barrier
; #define PG8_STAGE(bufoff, gbase, voff) do { _Pragma("unroll") for (int _i = 0; _i < 2; ++_i) \
;         __builtin_amdgcn_global_load_lds((const unsigned*)((const char*)(gbase) + (voff)[_i]), (PG8_LAS unsigned*)(lds + (bufoff) + ldsw + _i * 8192), 16, 0, 0); } while (0)
; #define PG8_LDA(dst, b, h) do { _Pragma("unroll") for (int m = 0; m < 4; ++m) _Pragma("unroll") for (int k = 0; k < 2; ++k) dst[m][k] = *(const PG8_LAS bf16x8*)(lds + PG8_SA(b, h) + aoff + m * 2048 + k * 1024); } while (0)
; #define PG8_LDB(dst, b, h) do { _Pragma("unroll") for (int n = 0; n < 2; ++n) _Pragma("unroll") for (int k = 0; k < 2; ++k) dst[n][k] = *(const PG8_LAS bf16x8*)(lds + PG8_SB(b, h) + boff + n * 2048 + k * 1024); } while (0)
; #define PG8_MMA(ai, bj, At, Bt) do { __builtin_amdgcn_s_setprio(1); _Pragma("unroll") for (int m = 0; m < 4; ++m) _Pragma("unroll") for (int n = 0; n < 2; ++n) _Pragma("unroll") for (int k = 0; k < 2; ++k) \
;         acc[ai][bj][m][n] = __builtin_amdgcn_mfma_f32_16x16x32_bf16(Bt[n][k], At[m][k], acc[ai][bj][m][n], 0, 0, 0); __builtin_amdgcn_s_setprio(0); } while (0)
; #define PG8_WAIT_V(n) asm volatile("s_waitcnt vmcnt(" #n ")" ::: "memory")
; #define PG8_WAIT_L(n) asm volatile("s_waitcnt lgkmcnt(" #n ")" ::: "memory")
; #define PG8_BAR __builtin_amdgcn_s_barrier()
; #define PG8_SCHED __builtin_amdgcn_sched_barrier(0)
; template <class Epi, class Sched, bool ALIGN_EPI = false, bool SP2 = false>
; __device__ __forceinline__ void gemm_phase(PG8_LAS unsigned char* lds, const Gemm g, const Sched& S, const Epi& E) {
;     ...
;             PG8_WAIT_V(8); PG8_WAIT_L(0); PG8_BAR; PG8_MMA(1, 0, At, B0); PG8_MMA(1, 1, At, B1); PG8_BAR; PG8_SCHED;
;             PG8_LDB(B0, 1, 0); PG8_LDB(B1, 1, 1); PG8_SCHED; PG8_LDA(At, 1, 0); PG8_STAGE(PG8_SA(0, 1), a2 + hstepA, voffA);
;             PG8_WAIT_V(8); PG8_WAIT_L(0); PG8_BAR; PG8_MMA(0, 0, At, B0); PG8_MMA(0, 1, At, B1); PG8_BAR; PG8_SCHED;
	s_setprio 1
	v_mfma_f32_16x16x32_bf16 v[92:95], v[104:107], v[160:163], v[92:95]
	v_mfma_f32_16x16x32_bf16 v[88:91], v[112:115], v[160:163], v[88:91]
	v_mfma_f32_16x16x32_bf16 v[84:87], v[104:107], v[168:171], v[84:87]
	v_mfma_f32_16x16x32_bf16 v[80:83], v[112:115], v[168:171], v[80:83]
	v_mfma_f32_16x16x32_bf16 v[76:79], v[104:107], v[212:215], v[76:79]
	v_mfma_f32_16x16x32_bf16 v[72:75], v[112:115], v[212:215], v[72:75]
	v_mfma_f32_16x16x32_bf16 v[68:71], v[104:107], v[220:223], v[68:71]
	v_mfma_f32_16x16x32_bf16 v[64:67], v[112:115], v[220:223], v[64:67]
	v_mfma_f32_16x16x32_bf16 v[92:95], v[108:111], v[164:167], v[92:95]
	v_mfma_f32_16x16x32_bf16 v[88:91], v[116:119], v[164:167], v[88:91]
	v_mfma_f32_16x16x32_bf16 v[84:87], v[108:111], v[208:211], v[84:87]
	v_mfma_f32_16x16x32_bf16 v[80:83], v[116:119], v[208:211], v[80:83]
	v_mfma_f32_16x16x32_bf16 v[76:79], v[108:111], v[216:219], v[76:79]
	v_mfma_f32_16x16x32_bf16 v[72:75], v[116:119], v[216:219], v[72:75]
	v_mfma_f32_16x16x32_bf16 v[68:71], v[108:111], v[224:227], v[68:71]
	v_mfma_f32_16x16x32_bf16 v[64:67], v[116:119], v[224:227], v[64:67]
	v_mfma_f32_16x16x32_bf16 v[28:31], v[120:123], v[160:163], v[28:31]
	v_mfma_f32_16x16x32_bf16 v[24:27], v[136:139], v[160:163], v[24:27]
	v_mfma_f32_16x16x32_bf16 v[20:23], v[120:123], v[168:171], v[20:23]
	v_mfma_f32_16x16x32_bf16 v[16:19], v[136:139], v[168:171], v[16:19]
	v_mfma_f32_16x16x32_bf16 v[12:15], v[120:123], v[212:215], v[12:15]
	v_mfma_f32_16x16x32_bf16 v[8:11], v[136:139], v[212:215], v[8:11]
	v_mfma_f32_16x16x32_bf16 v[4:7], v[120:123], v[220:223], v[4:7]
	v_mfma_f32_16x16x32_bf16 v[0:3], v[136:139], v[220:223], v[0:3]
	v_mfma_f32_16x16x32_bf16 v[28:31], v[124:127], v[164:167], v[28:31]
	v_mfma_f32_16x16x32_bf16 v[24:27], v[140:143], v[164:167], v[24:27]
	v_mfma_f32_16x16x32_bf16 v[20:23], v[124:127], v[208:211], v[20:23]
	v_mfma_f32_16x16x32_bf16 v[16:19], v[140:143], v[208:211], v[16:19]
	v_mfma_f32_16x16x32_bf16 v[12:15], v[124:127], v[216:219], v[12:15]
	v_mfma_f32_16x16x32_bf16 v[8:11], v[140:143], v[216:219], v[8:11]
	v_mfma_f32_16x16x32_bf16 v[4:7], v[124:127], v[224:227], v[4:7]
	v_mfma_f32_16x16x32_bf16 v[0:3], v[140:143], v[224:227], v[0:3]
	s_setprio 0
	s_barrier
	s_add_i32 s20, 0, 0x18000
	s_add_i32 s33, 0, 0x1c000
	v_add_u32_e32 v116, s20, v195
	v_add_u32_e32 v140, s33, v195
	ds_read_b128 v[104:107], v116
	ds_read_b128 v[108:111], v116 offset:1024
	ds_read_b128 v[112:115], v116 offset:2048
	ds_read_b128 v[116:119], v116 offset:3072
	ds_read_b128 v[120:123], v140
	ds_read_b128 v[124:127], v140 offset:1024
	ds_read_b128 v[136:139], v140 offset:2048
	ds_read_b128 v[140:143], v140 offset:3072
	s_add_u32 s24, s24, 0x40000
	s_addc_u32 s25, s25, 0
	s_mov_b32 m0, s36
	v_lshl_add_u64 v[200:201], s[24:25], 0, v[172:173]
	ds_read_b128 v[160:163], v207 offset:32768
	ds_read_b128 v[164:167], v207 offset:33792
	ds_read_b128 v[168:171], v207 offset:34816
	ds_read_b128 v[208:211], v207 offset:35840
	ds_read_b128 v[212:215], v207 offset:36864
	ds_read_b128 v[216:219], v207 offset:37888
	ds_read_b128 v[220:223], v207 offset:38912
	ds_read_b128 v[224:227], v207 offset:39936
	global_load_lds_dwordx4 v[200:201], off
	v_lshl_add_u64 v[200:201], s[24:25], 0, v[176:177]
	s_mov_b32 m0, s37
	s_nop 0
	global_load_lds_dwordx4 v[200:201], off
	s_waitcnt vmcnt(8)
	s_waitcnt lgkmcnt(0)
	s_barrier
	s_setprio 1
	v_mfma_f32_16x16x32_bf16 v[156:159], v[104:107], v[160:163], v[156:159]
	v_mfma_f32_16x16x32_bf16 v[152:155], v[112:115], v[160:163], v[152:155]
	v_mfma_f32_16x16x32_bf16 v[148:151], v[104:107], v[168:171], v[148:151]
	v_mfma_f32_16x16x32_bf16 v[144:147], v[112:115], v[168:171], v[144:147]
	v_mfma_f32_16x16x32_bf16 v[132:135], v[104:107], v[212:215], v[132:135]
	v_mfma_f32_16x16x32_bf16 v[128:131], v[112:115], v[212:215], v[128:131]
	v_mfma_f32_16x16x32_bf16 v[100:103], v[104:107], v[220:223], v[100:103]
	v_mfma_f32_16x16x32_bf16 v[96:99], v[112:115], v[220:223], v[96:99]
	v_mfma_f32_16x16x32_bf16 v[156:159], v[108:111], v[164:167], v[156:159]
	v_mfma_f32_16x16x32_bf16 v[152:155], v[116:119], v[164:167], v[152:155]
	v_mfma_f32_16x16x32_bf16 v[148:151], v[108:111], v[208:211], v[148:151]
	v_mfma_f32_16x16x32_bf16 v[144:147], v[116:119], v[208:211], v[144:147]
	v_mfma_f32_16x16x32_bf16 v[132:135], v[108:111], v[216:219], v[132:135]
	v_mfma_f32_16x16x32_bf16 v[128:131], v[116:119], v[216:219], v[128:131]
	v_mfma_f32_16x16x32_bf16 v[100:103], v[108:111], v[224:227], v[100:103]
	v_mfma_f32_16x16x32_bf16 v[96:99], v[116:119], v[224:227], v[96:99]
	v_mfma_f32_16x16x32_bf16 v[60:63], v[120:123], v[160:163], v[60:63]
	v_mfma_f32_16x16x32_bf16 v[56:59], v[136:139], v[160:163], v[56:59]
	v_mfma_f32_16x16x32_bf16 v[52:55], v[120:123], v[168:171], v[52:55]
	v_mfma_f32_16x16x32_bf16 v[48:51], v[136:139], v[168:171], v[48:51]
	v_mfma_f32_16x16x32_bf16 v[44:47], v[120:123], v[212:215], v[44:47]
	v_mfma_f32_16x16x32_bf16 v[40:43], v[136:139], v[212:215], v[40:43]
	v_mfma_f32_16x16x32_bf16 v[36:39], v[120:123], v[220:223], v[36:39]
	v_mfma_f32_16x16x32_bf16 v[32:35], v[136:139], v[220:223], v[32:35]
	v_mfma_f32_16x16x32_bf16 v[60:63], v[124:127], v[164:167], v[60:63]
	v_mfma_f32_16x16x32_bf16 v[56:59], v[140:143], v[164:167], v[56:59]
	v_mfma_f32_16x16x32_bf16 v[52:55], v[124:127], v[208:211], v[52:55]
	v_mfma_f32_16x16x32_bf16 v[48:51], v[140:143], v[208:211], v[48:51]
	v_mfma_f32_16x16x32_bf16 v[44:47], v[124:127], v[216:219], v[44:47]
	v_mfma_f32_16x16x32_bf16 v[40:43], v[140:143], v[216:219], v[40:43]
	v_mfma_f32_16x16x32_bf16 v[36:39], v[124:127], v[224:227], v[36:39]
	v_mfma_f32_16x16x32_bf16 v[32:35], v[140:143], v[224:227], v[32:35]
	s_setprio 0
	s_barrier
; #define PG8_STAGE(bufoff, gbase, voff) do { _Pragma("unroll") for (int _i = 0; _i < 2; ++_i) \
;         __builtin_amdgcn_global_load_lds((const unsigned*)((const char*)(gbase) + (voff)[_i]), (PG8_LAS unsigned*)(lds + (bufoff) + ldsw + _i * 8192), 16, 0, 0); } while (0)
; #define PG8_LDA(dst, b, h) do { _Pragma("unroll") for (int m = 0; m < 4; ++m) _Pragma("unroll") for (int k = 0; k < 2; ++k) dst[m][k] = *(const PG8_LAS bf16x8*)(lds + PG8_SA(b, h) + aoff + m * 2048 + k * 1024); } while (0)
; #define PG8_MMA(ai, bj, At, Bt) do { __builtin_amdgcn_s_setprio(1); _Pragma("unroll") for (int m = 0; m < 4; ++m) _Pragma("unroll") for (int n = 0; n < 2; ++n) _Pragma("unroll") for (int k = 0; k < 2; ++k) \
;         acc[ai][bj][m][n] = __builtin_amdgcn_mfma_f32_16x16x32_bf16(Bt[n][k], At[m][k], acc[ai][bj][m][n], 0, 0, 0); __builtin_amdgcn_s_setprio(0); } while (0)
; #define PG8_WAIT_V(n) asm volatile("s_waitcnt vmcnt(" #n ")" ::: "memory")
; #define PG8_WAIT_L(n) asm volatile("s_waitcnt lgkmcnt(" #n ")" ::: "memory")
; #define PG8_BAR __builtin_amdgcn_s_barrier()
; #define PG8_SCHED __builtin_amdgcn_sched_barrier(0)
; template <class Epi, class Sched, bool ALIGN_EPI = false, bool SP2 = false>
; __device__ __forceinline__ void gemm_phase(PG8_LAS unsigned char* lds, const Gemm g, const Sched& S, const Epi& E) {
;     ...
;             PG8_LDA(At, 1, 1); PG8_STAGE(PG8_SB(1, 0), b3, voffB); PG8_STAGE(PG8_SB(1, 1), b3 + hstepB, voffB); PG8_STAGE(PG8_SA(1, 0), a3, voffA);
;             PG8_WAIT_V(8); PG8_WAIT_L(0); PG8_BAR; PG8_MMA(1, 0, At, B0); PG8_MMA(1, 1, At, B1); PG8_BAR; PG8_SCHED;
	s_add_i32 s20, s20, s31
	v_lshl_add_u64 v[184:185], v[184:185], 0, s[52:53]
	s_mov_b32 m0, s20
	ds_read_b128 v[160:163], v207 offset:49152
	ds_read_b128 v[164:167], v207 offset:50176
	ds_read_b128 v[168:171], v207 offset:51200
	ds_read_b128 v[208:211], v207 offset:52224
	ds_read_b128 v[212:215], v207 offset:53248
	ds_read_b128 v[216:219], v207 offset:54272
	ds_read_b128 v[220:223], v207 offset:55296
	ds_read_b128 v[224:227], v207 offset:56320
	global_load_lds_dwordx4 v[184:185], off
	s_add_i32 m0, s20, 0x2000
	s_add_u32 s22, s22, 0x40080
	v_lshl_add_u64 v[184:185], v[188:189], 0, s[52:53]
	s_addc_u32 s23, s23, 0
	s_add_i32 s20, s33, s31
	global_load_lds_dwordx4 v[184:185], off
	v_lshl_add_u64 v[184:185], s[22:23], 0, v[174:175]
	s_mov_b32 m0, s20
	s_nop 0
	global_load_lds_dwordx4 v[184:185], off
	v_lshl_add_u64 v[184:185], s[22:23], 0, v[178:179]
	s_add_i32 m0, s20, 0x2000
	s_nop 0
	global_load_lds_dwordx4 v[184:185], off
	v_lshl_add_u64 v[184:185], v[192:193], 0, s[52:53]
	s_mov_b32 m0, s68
	s_nop 0
	global_load_lds_dwordx4 v[184:185], off
	v_lshl_add_u64 v[184:185], v[196:197], 0, s[52:53]
	s_mov_b32 m0, s69
	s_nop 0
	global_load_lds_dwordx4 v[184:185], off
	s_waitcnt vmcnt(8)
	s_waitcnt lgkmcnt(0)
	s_barrier
	s_setprio 1
	v_mfma_f32_16x16x32_bf16 v[92:95], v[104:107], v[160:163], v[92:95]
	v_mfma_f32_16x16x32_bf16 v[88:91], v[112:115], v[160:163], v[88:91]
	v_mfma_f32_16x16x32_bf16 v[84:87], v[104:107], v[168:171], v[84:87]
	v_mfma_f32_16x16x32_bf16 v[80:83], v[112:115], v[168:171], v[80:83]
	v_mfma_f32_16x16x32_bf16 v[76:79], v[104:107], v[212:215], v[76:79]
	v_mfma_f32_16x16x32_bf16 v[72:75], v[112:115], v[212:215], v[72:75]
	v_mfma_f32_16x16x32_bf16 v[68:71], v[104:107], v[220:223], v[68:71]
	v_mfma_f32_16x16x32_bf16 v[64:67], v[112:115], v[220:223], v[64:67]
	v_mfma_f32_16x16x32_bf16 v[92:95], v[108:111], v[164:167], v[92:95]
	v_mfma_f32_16x16x32_bf16 v[88:91], v[116:119], v[164:167], v[88:91]
	v_mfma_f32_16x16x32_bf16 v[84:87], v[108:111], v[208:211], v[84:87]
	v_mfma_f32_16x16x32_bf16 v[80:83], v[116:119], v[208:211], v[80:83]
	v_mfma_f32_16x16x32_bf16 v[76:79], v[108:111], v[216:219], v[76:79]
	v_mfma_f32_16x16x32_bf16 v[72:75], v[116:119], v[216:219], v[72:75]
	v_mfma_f32_16x16x32_bf16 v[68:71], v[108:111], v[224:227], v[68:71]
	v_mfma_f32_16x16x32_bf16 v[64:67], v[116:119], v[224:227], v[64:67]
	v_mfma_f32_16x16x32_bf16 v[28:31], v[120:123], v[160:163], v[28:31]
	v_mfma_f32_16x16x32_bf16 v[24:27], v[136:139], v[160:163], v[24:27]
	v_mfma_f32_16x16x32_bf16 v[20:23], v[120:123], v[168:171], v[20:23]
	v_mfma_f32_16x16x32_bf16 v[16:19], v[136:139], v[168:171], v[16:19]
	v_mfma_f32_16x16x32_bf16 v[12:15], v[120:123], v[212:215], v[12:15]
	v_mfma_f32_16x16x32_bf16 v[8:11], v[136:139], v[212:215], v[8:11]
	v_mfma_f32_16x16x32_bf16 v[4:7], v[120:123], v[220:223], v[4:7]
	v_mfma_f32_16x16x32_bf16 v[0:3], v[136:139], v[220:223], v[0:3]
	v_mfma_f32_16x16x32_bf16 v[28:31], v[124:127], v[164:167], v[28:31]
	v_mfma_f32_16x16x32_bf16 v[24:27], v[140:143], v[164:167], v[24:27]
	v_mfma_f32_16x16x32_bf16 v[20:23], v[124:127], v[208:211], v[20:23]
	v_mfma_f32_16x16x32_bf16 v[16:19], v[140:143], v[208:211], v[16:19]
	v_mfma_f32_16x16x32_bf16 v[12:15], v[124:127], v[216:219], v[12:15]
	v_mfma_f32_16x16x32_bf16 v[8:11], v[140:143], v[216:219], v[8:11]
	v_mfma_f32_16x16x32_bf16 v[4:7], v[124:127], v[224:227], v[4:7]
	v_mfma_f32_16x16x32_bf16 v[0:3], v[140:143], v[224:227], v[0:3]
	s_setprio 0
	s_barrier
	s_add_u32 s12, s12, 0x100
	s_addc_u32 s13, s13, 0
	s_add_u32 s18, s18, 0x100
	s_addc_u32 s19, s19, 0
	s_cmp_ge_i32 s21, s27
	s_mov_b32 s20, s21
	s_cbranch_scc0 .LBB0_1455

; #define PG8_STAGE(bufoff, gbase, voff) do { _Pragma("unroll") for (int _i = 0; _i < 2; ++_i) \
;         __builtin_amdgcn_global_load_lds((const unsigned*)((const char*)(gbase) + (voff)[_i]), (PG8_LAS unsigned*)(lds + (bufoff) + ldsw + _i * 8192), 16, 0, 0); } while (0)
; #define PG8_LDA(dst, b, h) do { _Pragma("unroll") for (int m = 0; m < 4; ++m) _Pragma("unroll") for (int k = 0; k < 2; ++k) dst[m][k] = *(const PG8_LAS bf16x8*)(lds + PG8_SA(b, h) + aoff + m * 2048 + k * 1024); } while (0)
; #define PG8_LDB(dst, b, h) do { _Pragma("unroll") for (int n = 0; n < 2; ++n) _Pragma("unroll") for (int k = 0; k < 2; ++k) dst[n][k] = *(const PG8_LAS bf16x8*)(lds + PG8_SB(b, h) + boff + n * 2048 + k * 1024); } while (0)
; #define PG8_MMA(ai, bj, At, Bt) do { __builtin_amdgcn_s_setprio(1); _Pragma("unroll") for (int m = 0; m < 4; ++m) _Pragma("unroll") for (int n = 0; n < 2; ++n) _Pragma("unroll") for (int k = 0; k < 2; ++k) \
;         acc[ai][bj][m][n] = __builtin_amdgcn_mfma_f32_16x16x32_bf16(Bt[n][k], At[m][k], acc[ai][bj][m][n], 0, 0, 0); __builtin_amdgcn_s_setprio(0); } while (0)
; #define PG8_WAIT_V(n) asm volatile("s_waitcnt vmcnt(" #n ")" ::: "memory")
; #define PG8_WAIT_L(n) asm volatile("s_waitcnt lgkmcnt(" #n ")" ::: "memory")
; template <class Epi, class Sched, bool ALIGN_EPI = false, bool SP2 = false>
; __device__ __forceinline__ void gemm_phase(PG8_LAS unsigned char* lds, const Gemm g, const Sched& S, const Epi& E) {
;     ...
;             const bool last = (t == nt - 2);
;             const char* a1 = cA + (long)(t + 1) * kstepA;
;             const char* a2 = last ? nA : cA + (long)(t + 2) * kstepA; const char* b2 = last ? nB : cB + (long)(t + 2) * kstep;
;             const char* a3 = a2 + kstepA; const char* b3 = b2 + kstep;
;             if (last && has_next) S.a_ready(nxt);
;             if constexpr (SP2) {
;             PG8_LDB(B0, 0, 0); PG8_LDB(B1, 0, 1); PG8_SCHED; PG8_LDA(At, 0, 0); PG8_STAGE(PG8_SA(1, 1), a1 + hstepA, voffA);
;             PG8_WAIT_V(8); PG8_WAIT_L(0); PG8_BAR; PG8_MMA(0, 0, At, B0); PG8_MMA(0, 1, At, B1); PG8_BAR; PG8_SCHED;
;             PG8_LDA(At, 0, 1); PG8_STAGE(PG8_SB(0, 0), b2, voffB); PG8_STAGE(PG8_SB(0, 1), b2 + hstepB, voffB); PG8_STAGE(PG8_SA(0, 0), a2, voffA);
;             PG8_WAIT_V(8); PG8_WAIT_L(0); PG8_BAR; PG8_MMA(1, 0, At, B0); PG8_MMA(1, 1, At, B1); PG8_BAR; PG8_SCHED;
.LBB0_1523:
	ds_read_b128 v[152:155], v149
	ds_read_b128 v[156:159], v149 offset:1024
	ds_read_b128 v[160:163], v149 offset:2048
	ds_read_b128 v[164:167], v149 offset:3072
	ds_read_b128 v[168:171], v150
	ds_read_b128 v[172:175], v150 offset:1024
	ds_read_b128 v[176:179], v150 offset:2048
	ds_read_b128 v[180:183], v150 offset:3072
	s_add_i32 s60, s36, 2
	s_add_u32 s37, s34, 0xfffc0080
	s_addc_u32 s42, s35, -1
	s_cmp_eq_u32 s50, s36
	s_cselect_b32 s36, s57, s58
	s_cselect_b32 s43, s23, s42
	s_cselect_b32 s42, s25, s37
	s_cselect_b32 s37, s56, s59
	v_lshl_add_u64 v[144:145], s[34:35], 0, v[136:137]
	s_add_i32 m0, s20, 0xc000
	ds_read_b128 v[184:187], v151
	ds_read_b128 v[188:191], v151 offset:1024
	ds_read_b128 v[192:195], v151 offset:2048
	ds_read_b128 v[196:199], v151 offset:3072
	ds_read_b128 v[200:203], v151 offset:4096
	ds_read_b128 v[204:207], v151 offset:5120
	ds_read_b128 v[208:211], v151 offset:6144
	ds_read_b128 v[212:215], v151 offset:7168
	global_load_lds_dwordx4 v[144:145], off
	v_lshl_add_u64 v[144:145], s[34:35], 0, v[138:139]
	s_add_i32 m0, s20, 0xe000
	s_nop 0
	global_load_lds_dwordx4 v[144:145], off
	s_waitcnt vmcnt(8)
	s_waitcnt lgkmcnt(0)
	s_barrier
	s_setprio 1
	v_mfma_f32_16x16x32_bf16 v[120:123], v[152:155], v[184:187], v[120:123]
	v_mfma_f32_16x16x32_bf16 v[116:119], v[160:163], v[184:187], v[116:119]
	v_mfma_f32_16x16x32_bf16 v[108:111], v[152:155], v[192:195], v[108:111]
	v_mfma_f32_16x16x32_bf16 v[100:103], v[160:163], v[192:195], v[100:103]
	v_mfma_f32_16x16x32_bf16 v[92:95], v[152:155], v[200:203], v[92:95]
	v_mfma_f32_16x16x32_bf16 v[84:87], v[160:163], v[200:203], v[84:87]
	v_mfma_f32_16x16x32_bf16 v[76:79], v[152:155], v[208:211], v[76:79]
	v_mfma_f32_16x16x32_bf16 v[68:71], v[160:163], v[208:211], v[68:71]
	v_mfma_f32_16x16x32_bf16 v[120:123], v[156:159], v[188:191], v[120:123]
	v_mfma_f32_16x16x32_bf16 v[116:119], v[164:167], v[188:191], v[116:119]
	v_mfma_f32_16x16x32_bf16 v[108:111], v[156:159], v[196:199], v[108:111]
	v_mfma_f32_16x16x32_bf16 v[100:103], v[164:167], v[196:199], v[100:103]
	v_mfma_f32_16x16x32_bf16 v[92:95], v[156:159], v[204:207], v[92:95]
	v_mfma_f32_16x16x32_bf16 v[84:87], v[164:167], v[204:207], v[84:87]
	v_mfma_f32_16x16x32_bf16 v[76:79], v[156:159], v[212:215], v[76:79]
	v_mfma_f32_16x16x32_bf16 v[68:71], v[164:167], v[212:215], v[68:71]
	v_mfma_f32_16x16x32_bf16 v[124:127], v[168:171], v[184:187], v[124:127]
	v_mfma_f32_16x16x32_bf16 v[112:115], v[176:179], v[184:187], v[112:115]
	v_mfma_f32_16x16x32_bf16 v[104:107], v[168:171], v[192:195], v[104:107]
	v_mfma_f32_16x16x32_bf16 v[96:99], v[176:179], v[192:195], v[96:99]
	v_mfma_f32_16x16x32_bf16 v[88:91], v[168:171], v[200:203], v[88:91]
	v_mfma_f32_16x16x32_bf16 v[80:83], v[176:179], v[200:203], v[80:83]
	v_mfma_f32_16x16x32_bf16 v[72:75], v[168:171], v[208:211], v[72:75]
	v_mfma_f32_16x16x32_bf16 v[64:67], v[176:179], v[208:211], v[64:67]
	v_mfma_f32_16x16x32_bf16 v[124:127], v[172:175], v[188:191], v[124:127]
	v_mfma_f32_16x16x32_bf16 v[112:115], v[180:183], v[188:191], v[112:115]
	v_mfma_f32_16x16x32_bf16 v[104:107], v[172:175], v[196:199], v[104:107]
	v_mfma_f32_16x16x32_bf16 v[96:99], v[180:183], v[196:199], v[96:99]
	v_mfma_f32_16x16x32_bf16 v[88:91], v[172:175], v[204:207], v[88:91]
	v_mfma_f32_16x16x32_bf16 v[80:83], v[180:183], v[204:207], v[80:83]
	v_mfma_f32_16x16x32_bf16 v[72:75], v[172:175], v[212:215], v[72:75]
	v_mfma_f32_16x16x32_bf16 v[64:67], v[180:183], v[212:215], v[64:67]
	s_setprio 0
	s_barrier
	s_add_i32 s61, s54, s17
	v_lshl_add_u64 v[144:145], s[36:37], 0, v[132:133]
	s_mov_b32 m0, s61
	ds_read_b128 v[184:187], v151 offset:16384
	ds_read_b128 v[188:191], v151 offset:17408
	ds_read_b128 v[192:195], v151 offset:18432
	ds_read_b128 v[196:199], v151 offset:19456
	ds_read_b128 v[200:203], v151 offset:20480
	ds_read_b128 v[204:207], v151 offset:21504
	ds_read_b128 v[208:211], v151 offset:22528
	ds_read_b128 v[212:215], v151 offset:23552
	global_load_lds_dwordx4 v[144:145], off
	s_add_i32 m0, s61, 0x2000
	s_add_u32 s62, s36, 0x40000
	v_lshl_add_u64 v[216:217], s[36:37], 0, v[128:129]
	s_addc_u32 s63, s37, 0
	s_add_i32 s61, s55, s17
	global_load_lds_dwordx4 v[216:217], off
	v_lshl_add_u64 v[218:219], s[62:63], 0, v[132:133]
	s_mov_b32 m0, s61
	v_lshl_add_u64 v[220:221], s[42:43], 0, v[130:131]
	global_load_lds_dwordx4 v[218:219], off
	v_lshl_add_u64 v[218:219], s[62:63], 0, v[128:129]
	s_add_i32 m0, s61, 0x2000
	s_nop 0
	global_load_lds_dwordx4 v[218:219], off
	v_lshl_add_u64 v[218:219], s[42:43], 0, v[134:135]
	s_mov_b32 m0, s20
	s_nop 0
	global_load_lds_dwordx4 v[218:219], off
	s_mov_b32 m0, s21
	s_nop 0
	global_load_lds_dwordx4 v[220:221], off
	s_waitcnt vmcnt(8)
	s_waitcnt lgkmcnt(0)
	s_barrier
; #define PG8_STAGE(bufoff, gbase, voff) do { _Pragma("unroll") for (int _i = 0; _i < 2; ++_i) \
;         __builtin_amdgcn_global_load_lds((const unsigned*)((const char*)(gbase) + (voff)[_i]), (PG8_LAS unsigned*)(lds + (bufoff) + ldsw + _i * 8192), 16, 0, 0); } while (0)
; #define PG8_LDA(dst, b, h) do { _Pragma("unroll") for (int m = 0; m < 4; ++m) _Pragma("unroll") for (int k = 0; k < 2; ++k) dst[m][k] = *(const PG8_LAS bf16x8*)(lds + PG8_SA(b, h) + aoff + m * 2048 + k * 1024); } while (0)
; #define PG8_LDB(dst, b, h) do { _Pragma("unroll") for (int n = 0; n < 2; ++n) _Pragma("unroll") for (int k = 0; k < 2; ++k) dst[n][k] = *(const PG8_LAS bf16x8*)(lds + PG8_SB(b, h) + boff + n * 2048 + k * 1024); } while (0)
; #define PG8_MMA(ai, bj, At, Bt) do { __builtin_amdgcn_s_setprio(1); _Pragma("unroll") for (int m = 0; m < 4; ++m) _Pragma("unroll") for (int n = 0; n < 2; ++n) _Pragma("unroll") for (int k = 0; k < 2; ++k) \
;         acc[ai][bj][m][n] = __builtin_amdgcn_mfma_f32_16x16x32_bf16(Bt[n][k], At[m][k], acc[ai][bj][m][n], 0, 0, 0); __builtin_amdgcn_s_setprio(0); } while (0)
; #define PG8_WAIT_V(n) asm volatile("s_waitcnt vmcnt(" #n ")" ::: "memory")
; #define PG8_WAIT_L(n) asm volatile("s_waitcnt lgkmcnt(" #n ")" ::: "memory")
; #define PG8_BAR __builtin_amdgcn_s_barrier()
; #define PG8_SCHED __builtin_amdgcn_sched_barrier(0)
; template <class Epi, class Sched, bool ALIGN_EPI = false, bool SP2 = false>
; __device__ __forceinline__ void gemm_phase(PG8_LAS unsigned char* lds, const Gemm g, const Sched& S, const Epi& E) {
;     ...
;             PG8_WAIT_V(8); PG8_WAIT_L(0); PG8_BAR; PG8_MMA(1, 0, At, B0); PG8_MMA(1, 1, At, B1); PG8_BAR; PG8_SCHED;
;             PG8_LDB(B0, 1, 0); PG8_LDB(B1, 1, 1); PG8_SCHED; PG8_LDA(At, 1, 0); PG8_STAGE(PG8_SA(0, 1), a2 + hstepA, voffA);
;             PG8_WAIT_V(8); PG8_WAIT_L(0); PG8_BAR; PG8_MMA(0, 0, At, B0); PG8_MMA(0, 1, At, B1); PG8_BAR; PG8_SCHED;
	s_setprio 1
	v_mfma_f32_16x16x32_bf16 v[60:63], v[152:155], v[184:187], v[60:63]
	v_mfma_f32_16x16x32_bf16 v[52:55], v[160:163], v[184:187], v[52:55]
	v_mfma_f32_16x16x32_bf16 v[44:47], v[152:155], v[192:195], v[44:47]
	v_mfma_f32_16x16x32_bf16 v[36:39], v[160:163], v[192:195], v[36:39]
	v_mfma_f32_16x16x32_bf16 v[28:31], v[152:155], v[200:203], v[28:31]
	v_mfma_f32_16x16x32_bf16 v[20:23], v[160:163], v[200:203], v[20:23]
	v_mfma_f32_16x16x32_bf16 v[12:15], v[152:155], v[208:211], v[12:15]
	v_mfma_f32_16x16x32_bf16 v[4:7], v[160:163], v[208:211], v[4:7]
	v_mfma_f32_16x16x32_bf16 v[60:63], v[156:159], v[188:191], v[60:63]
	v_mfma_f32_16x16x32_bf16 v[52:55], v[164:167], v[188:191], v[52:55]
	v_mfma_f32_16x16x32_bf16 v[44:47], v[156:159], v[196:199], v[44:47]
	v_mfma_f32_16x16x32_bf16 v[36:39], v[164:167], v[196:199], v[36:39]
	v_mfma_f32_16x16x32_bf16 v[28:31], v[156:159], v[204:207], v[28:31]
	v_mfma_f32_16x16x32_bf16 v[20:23], v[164:167], v[204:207], v[20:23]
	v_mfma_f32_16x16x32_bf16 v[12:15], v[156:159], v[212:215], v[12:15]
	v_mfma_f32_16x16x32_bf16 v[4:7], v[164:167], v[212:215], v[4:7]
	v_mfma_f32_16x16x32_bf16 v[56:59], v[168:171], v[184:187], v[56:59]
	v_mfma_f32_16x16x32_bf16 v[48:51], v[176:179], v[184:187], v[48:51]
	v_mfma_f32_16x16x32_bf16 v[40:43], v[168:171], v[192:195], v[40:43]
	v_mfma_f32_16x16x32_bf16 v[32:35], v[176:179], v[192:195], v[32:35]
	v_mfma_f32_16x16x32_bf16 v[24:27], v[168:171], v[200:203], v[24:27]
	v_mfma_f32_16x16x32_bf16 v[16:19], v[176:179], v[200:203], v[16:19]
	v_mfma_f32_16x16x32_bf16 v[8:11], v[168:171], v[208:211], v[8:11]
	v_mfma_f32_16x16x32_bf16 v[0:3], v[176:179], v[208:211], v[0:3]
	v_mfma_f32_16x16x32_bf16 v[56:59], v[172:175], v[188:191], v[56:59]
	v_mfma_f32_16x16x32_bf16 v[48:51], v[180:183], v[188:191], v[48:51]
	v_mfma_f32_16x16x32_bf16 v[40:43], v[172:175], v[196:199], v[40:43]
	v_mfma_f32_16x16x32_bf16 v[32:35], v[180:183], v[196:199], v[32:35]
	v_mfma_f32_16x16x32_bf16 v[24:27], v[172:175], v[204:207], v[24:27]
	v_mfma_f32_16x16x32_bf16 v[16:19], v[180:183], v[204:207], v[16:19]
	v_mfma_f32_16x16x32_bf16 v[8:11], v[172:175], v[212:215], v[8:11]
	v_mfma_f32_16x16x32_bf16 v[0:3], v[180:183], v[212:215], v[0:3]
	s_setprio 0
	s_barrier
	s_add_i32 s61, 0, 0x18000
	s_add_i32 s62, 0, 0x1c000
	v_add_u32_e32 v164, s61, v148
	v_add_u32_e32 v180, s62, v148
	ds_read_b128 v[152:155], v164
	ds_read_b128 v[156:159], v164 offset:1024
	ds_read_b128 v[160:163], v164 offset:2048
	ds_read_b128 v[164:167], v164 offset:3072
	ds_read_b128 v[168:171], v180
	ds_read_b128 v[172:175], v180 offset:1024
	ds_read_b128 v[176:179], v180 offset:2048
	ds_read_b128 v[180:183], v180 offset:3072
	s_add_u32 s42, s42, 0x40000
	s_addc_u32 s43, s43, 0
	s_mov_b32 m0, s33
	v_lshl_add_u64 v[222:223], s[42:43], 0, v[134:135]
	ds_read_b128 v[184:187], v151 offset:32768
	ds_read_b128 v[188:191], v151 offset:33792
	ds_read_b128 v[192:195], v151 offset:34816
	ds_read_b128 v[196:199], v151 offset:35840
	ds_read_b128 v[200:203], v151 offset:36864
	ds_read_b128 v[204:207], v151 offset:37888
	ds_read_b128 v[208:211], v151 offset:38912
	ds_read_b128 v[212:215], v151 offset:39936
	global_load_lds_dwordx4 v[222:223], off
	v_lshl_add_u64 v[222:223], s[42:43], 0, v[130:131]
	s_mov_b32 m0, s44
	s_nop 0
	global_load_lds_dwordx4 v[222:223], off
	s_waitcnt vmcnt(8)
	s_waitcnt lgkmcnt(0)
	s_barrier
	s_setprio 1
	v_mfma_f32_16x16x32_bf16 v[120:123], v[152:155], v[184:187], v[120:123]
	v_mfma_f32_16x16x32_bf16 v[116:119], v[160:163], v[184:187], v[116:119]
	v_mfma_f32_16x16x32_bf16 v[108:111], v[152:155], v[192:195], v[108:111]
	v_mfma_f32_16x16x32_bf16 v[100:103], v[160:163], v[192:195], v[100:103]
	v_mfma_f32_16x16x32_bf16 v[92:95], v[152:155], v[200:203], v[92:95]
	v_mfma_f32_16x16x32_bf16 v[84:87], v[160:163], v[200:203], v[84:87]
	v_mfma_f32_16x16x32_bf16 v[76:79], v[152:155], v[208:211], v[76:79]
	v_mfma_f32_16x16x32_bf16 v[68:71], v[160:163], v[208:211], v[68:71]
	v_mfma_f32_16x16x32_bf16 v[120:123], v[156:159], v[188:191], v[120:123]
	v_mfma_f32_16x16x32_bf16 v[116:119], v[164:167], v[188:191], v[116:119]
	v_mfma_f32_16x16x32_bf16 v[108:111], v[156:159], v[196:199], v[108:111]
	v_mfma_f32_16x16x32_bf16 v[100:103], v[164:167], v[196:199], v[100:103]
	v_mfma_f32_16x16x32_bf16 v[92:95], v[156:159], v[204:207], v[92:95]
	v_mfma_f32_16x16x32_bf16 v[84:87], v[164:167], v[204:207], v[84:87]
	v_mfma_f32_16x16x32_bf16 v[76:79], v[156:159], v[212:215], v[76:79]
	v_mfma_f32_16x16x32_bf16 v[68:71], v[164:167], v[212:215], v[68:71]
	v_mfma_f32_16x16x32_bf16 v[124:127], v[168:171], v[184:187], v[124:127]
	v_mfma_f32_16x16x32_bf16 v[112:115], v[176:179], v[184:187], v[112:115]
	v_mfma_f32_16x16x32_bf16 v[104:107], v[168:171], v[192:195], v[104:107]
	v_mfma_f32_16x16x32_bf16 v[96:99], v[176:179], v[192:195], v[96:99]
	v_mfma_f32_16x16x32_bf16 v[88:91], v[168:171], v[200:203], v[88:91]
	v_mfma_f32_16x16x32_bf16 v[80:83], v[176:179], v[200:203], v[80:83]
	v_mfma_f32_16x16x32_bf16 v[72:75], v[168:171], v[208:211], v[72:75]
	v_mfma_f32_16x16x32_bf16 v[64:67], v[176:179], v[208:211], v[64:67]
	v_mfma_f32_16x16x32_bf16 v[124:127], v[172:175], v[188:191], v[124:127]
	v_mfma_f32_16x16x32_bf16 v[112:115], v[180:183], v[188:191], v[112:115]
	v_mfma_f32_16x16x32_bf16 v[104:107], v[172:175], v[196:199], v[104:107]
	v_mfma_f32_16x16x32_bf16 v[96:99], v[180:183], v[196:199], v[96:99]
	v_mfma_f32_16x16x32_bf16 v[88:91], v[172:175], v[204:207], v[88:91]
	v_mfma_f32_16x16x32_bf16 v[80:83], v[180:183], v[204:207], v[80:83]
	v_mfma_f32_16x16x32_bf16 v[72:75], v[172:175], v[212:215], v[72:75]
	v_mfma_f32_16x16x32_bf16 v[64:67], v[180:183], v[212:215], v[64:67]
	s_setprio 0
	s_barrier
; #define PG8_STAGE(bufoff, gbase, voff) do { _Pragma("unroll") for (int _i = 0; _i < 2; ++_i) \
;         __builtin_amdgcn_global_load_lds((const unsigned*)((const char*)(gbase) + (voff)[_i]), (PG8_LAS unsigned*)(lds + (bufoff) + ldsw + _i * 8192), 16, 0, 0); } while (0)
; #define PG8_LDA(dst, b, h) do { _Pragma("unroll") for (int m = 0; m < 4; ++m) _Pragma("unroll") for (int k = 0; k < 2; ++k) dst[m][k] = *(const PG8_LAS bf16x8*)(lds + PG8_SA(b, h) + aoff + m * 2048 + k * 1024); } while (0)
; #define PG8_MMA(ai, bj, At, Bt) do { __builtin_amdgcn_s_setprio(1); _Pragma("unroll") for (int m = 0; m < 4; ++m) _Pragma("unroll") for (int n = 0; n < 2; ++n) _Pragma("unroll") for (int k = 0; k < 2; ++k) \
;         acc[ai][bj][m][n] = __builtin_amdgcn_mfma_f32_16x16x32_bf16(Bt[n][k], At[m][k], acc[ai][bj][m][n], 0, 0, 0); __builtin_amdgcn_s_setprio(0); } while (0)
; #define PG8_WAIT_V(n) asm volatile("s_waitcnt vmcnt(" #n ")" ::: "memory")
; #define PG8_WAIT_L(n) asm volatile("s_waitcnt lgkmcnt(" #n ")" ::: "memory")
; #define PG8_BAR __builtin_amdgcn_s_barrier()
; #define PG8_SCHED __builtin_amdgcn_sched_barrier(0)
; template <class Epi, class Sched, bool ALIGN_EPI = false, bool SP2 = false>
; __device__ __forceinline__ void gemm_phase(PG8_LAS unsigned char* lds, const Gemm g, const Sched& S, const Epi& E) {
;     ...
;             PG8_LDA(At, 1, 1); PG8_STAGE(PG8_SB(1, 0), b3, voffB); PG8_STAGE(PG8_SB(1, 1), b3 + hstepB, voffB); PG8_STAGE(PG8_SA(1, 0), a3, voffA);
;             PG8_WAIT_V(8); PG8_WAIT_L(0); PG8_BAR; PG8_MMA(1, 0, At, B0); PG8_MMA(1, 1, At, B1); PG8_BAR; PG8_SCHED;
	s_add_i32 s42, s61, s17
	v_lshl_add_u64 v[144:145], v[144:145], 0, s[10:11]
	s_mov_b32 m0, s42
	ds_read_b128 v[184:187], v151 offset:49152
	ds_read_b128 v[188:191], v151 offset:50176
	ds_read_b128 v[192:195], v151 offset:51200
	ds_read_b128 v[196:199], v151 offset:52224
	ds_read_b128 v[200:203], v151 offset:53248
	ds_read_b128 v[204:207], v151 offset:54272
	ds_read_b128 v[208:211], v151 offset:55296
	ds_read_b128 v[212:215], v151 offset:56320
	global_load_lds_dwordx4 v[144:145], off
	s_add_i32 m0, s42, 0x2000
	s_add_u32 s36, s36, 0x40080
	v_lshl_add_u64 v[144:145], v[216:217], 0, s[10:11]
	s_addc_u32 s37, s37, 0
	s_add_i32 s42, s62, s17
	global_load_lds_dwordx4 v[144:145], off
	v_lshl_add_u64 v[144:145], s[36:37], 0, v[132:133]
	s_mov_b32 m0, s42
	s_nop 0
	global_load_lds_dwordx4 v[144:145], off
	v_lshl_add_u64 v[144:145], s[36:37], 0, v[128:129]
	s_add_i32 m0, s42, 0x2000
	s_nop 0
	global_load_lds_dwordx4 v[144:145], off
	v_lshl_add_u64 v[144:145], v[218:219], 0, s[10:11]
	s_mov_b32 m0, s48
	s_nop 0
	global_load_lds_dwordx4 v[144:145], off
	v_lshl_add_u64 v[144:145], v[220:221], 0, s[10:11]
	s_mov_b32 m0, s49
	s_nop 0
	global_load_lds_dwordx4 v[144:145], off
	s_waitcnt vmcnt(8)
	s_waitcnt lgkmcnt(0)
	s_barrier
	s_setprio 1
	v_mfma_f32_16x16x32_bf16 v[60:63], v[152:155], v[184:187], v[60:63]
	v_mfma_f32_16x16x32_bf16 v[52:55], v[160:163], v[184:187], v[52:55]
	v_mfma_f32_16x16x32_bf16 v[44:47], v[152:155], v[192:195], v[44:47]
	v_mfma_f32_16x16x32_bf16 v[36:39], v[160:163], v[192:195], v[36:39]
	v_mfma_f32_16x16x32_bf16 v[28:31], v[152:155], v[200:203], v[28:31]
	v_mfma_f32_16x16x32_bf16 v[20:23], v[160:163], v[200:203], v[20:23]
	v_mfma_f32_16x16x32_bf16 v[12:15], v[152:155], v[208:211], v[12:15]
	v_mfma_f32_16x16x32_bf16 v[4:7], v[160:163], v[208:211], v[4:7]
	v_mfma_f32_16x16x32_bf16 v[60:63], v[156:159], v[188:191], v[60:63]
	v_mfma_f32_16x16x32_bf16 v[52:55], v[164:167], v[188:191], v[52:55]
	v_mfma_f32_16x16x32_bf16 v[44:47], v[156:159], v[196:199], v[44:47]
	v_mfma_f32_16x16x32_bf16 v[36:39], v[164:167], v[196:199], v[36:39]
	v_mfma_f32_16x16x32_bf16 v[28:31], v[156:159], v[204:207], v[28:31]
	v_mfma_f32_16x16x32_bf16 v[20:23], v[164:167], v[204:207], v[20:23]
	v_mfma_f32_16x16x32_bf16 v[12:15], v[156:159], v[212:215], v[12:15]
	v_mfma_f32_16x16x32_bf16 v[4:7], v[164:167], v[212:215], v[4:7]
	v_mfma_f32_16x16x32_bf16 v[56:59], v[168:171], v[184:187], v[56:59]
	v_mfma_f32_16x16x32_bf16 v[48:51], v[176:179], v[184:187], v[48:51]
	v_mfma_f32_16x16x32_bf16 v[40:43], v[168:171], v[192:195], v[40:43]
	v_mfma_f32_16x16x32_bf16 v[32:35], v[176:179], v[192:195], v[32:35]
	v_mfma_f32_16x16x32_bf16 v[24:27], v[168:171], v[200:203], v[24:27]
	v_mfma_f32_16x16x32_bf16 v[16:19], v[176:179], v[200:203], v[16:19]
	v_mfma_f32_16x16x32_bf16 v[8:11], v[168:171], v[208:211], v[8:11]
	v_mfma_f32_16x16x32_bf16 v[0:3], v[176:179], v[208:211], v[0:3]
	v_mfma_f32_16x16x32_bf16 v[56:59], v[172:175], v[188:191], v[56:59]
	v_mfma_f32_16x16x32_bf16 v[48:51], v[180:183], v[188:191], v[48:51]
	v_mfma_f32_16x16x32_bf16 v[40:43], v[172:175], v[196:199], v[40:43]
	v_mfma_f32_16x16x32_bf16 v[32:35], v[180:183], v[196:199], v[32:35]
	v_mfma_f32_16x16x32_bf16 v[24:27], v[172:175], v[204:207], v[24:27]
	v_mfma_f32_16x16x32_bf16 v[16:19], v[180:183], v[204:207], v[16:19]
	v_mfma_f32_16x16x32_bf16 v[8:11], v[172:175], v[212:215], v[8:11]
	v_mfma_f32_16x16x32_bf16 v[0:3], v[180:183], v[212:215], v[0:3]
	s_setprio 0
	s_barrier
	s_add_u32 s34, s34, 0x100
	s_addc_u32 s35, s35, 0
	s_add_u32 s58, s58, 0x100
	s_addc_u32 s59, s59, 0
	s_cmp_ge_i32 s60, s46
	s_mov_b32 s36, s60
	s_cbranch_scc0 .LBB0_1523

; #define PG8_STAGE(bufoff, gbase, voff) do { _Pragma("unroll") for (int _i = 0; _i < 2; ++_i) \
;         __builtin_amdgcn_global_load_lds((const unsigned*)((const char*)(gbase) + (voff)[_i]), (PG8_LAS unsigned*)(lds + (bufoff) + ldsw + _i * 8192), 16, 0, 0); } while (0)
; #define PG8_LDA(dst, b, h) do { _Pragma("unroll") for (int m = 0; m < 4; ++m) _Pragma("unroll") for (int k = 0; k < 2; ++k) dst[m][k] = *(const PG8_LAS bf16x8*)(lds + PG8_SA(b, h) + aoff + m * 2048 + k * 1024); } while (0)
; #define PG8_LDB(dst, b, h) do { _Pragma("unroll") for (int n = 0; n < 2; ++n) _Pragma("unroll") for (int k = 0; k < 2; ++k) dst[n][k] = *(const PG8_LAS bf16x8*)(lds + PG8_SB(b, h) + boff + n * 2048 + k * 1024); } while (0)
; #define PG8_MMA(ai, bj, At, Bt) do { __builtin_amdgcn_s_setprio(1); _Pragma("unroll") for (int m = 0; m < 4; ++m) _Pragma("unroll") for (int n = 0; n < 2; ++n) _Pragma("unroll") for (int k = 0; k < 2; ++k) \
;         acc[ai][bj][m][n] = __builtin_amdgcn_mfma_f32_16x16x32_bf16(Bt[n][k], At[m][k], acc[ai][bj][m][n], 0, 0, 0); __builtin_amdgcn_s_setprio(0); } while (0)
; #define PG8_WAIT_V(n) asm volatile("s_waitcnt vmcnt(" #n ")" ::: "memory")
; #define PG8_WAIT_L(n) asm volatile("s_waitcnt lgkmcnt(" #n ")" ::: "memory")
; template <class Epi, class Sched, bool ALIGN_EPI = false, bool SP2 = false>
; __device__ __forceinline__ void gemm_phase(PG8_LAS unsigned char* lds, const Gemm g, const Sched& S, const Epi& E) {
;     ...
;             const bool last = (t == nt - 2);
;             const char* a1 = cA + (long)(t + 1) * kstepA;
;             const char* a2 = last ? nA : cA + (long)(t + 2) * kstepA; const char* b2 = last ? nB : cB + (long)(t + 2) * kstep;
;             const char* a3 = a2 + kstepA; const char* b3 = b2 + kstep;
;             if (last && has_next) S.a_ready(nxt);
;             if constexpr (SP2) {
;             PG8_LDB(B0, 0, 0); PG8_LDB(B1, 0, 1); PG8_SCHED; PG8_LDA(At, 0, 0); PG8_STAGE(PG8_SA(1, 1), a1 + hstepA, voffA);
;             PG8_WAIT_V(8); PG8_WAIT_L(0); PG8_BAR; PG8_MMA(0, 0, At, B0); PG8_MMA(0, 1, At, B1); PG8_BAR; PG8_SCHED;
;             PG8_LDA(At, 0, 1); PG8_STAGE(PG8_SB(0, 0), b2, voffB); PG8_STAGE(PG8_SB(0, 1), b2 + hstepB, voffB); PG8_STAGE(PG8_SA(0, 0), a2, voffA);
;             PG8_WAIT_V(8); PG8_WAIT_L(0); PG8_BAR; PG8_MMA(1, 0, At, B0); PG8_MMA(1, 1, At, B1); PG8_BAR; PG8_SCHED;
.LBB0_1602:
	ds_read_b128 v[128:131], v185
	ds_read_b128 v[132:135], v185 offset:1024
	ds_read_b128 v[158:161], v185 offset:2048
	ds_read_b128 v[162:165], v185 offset:3072
	ds_read_b128 v[166:169], v186
	ds_read_b128 v[170:173], v186 offset:1024
	ds_read_b128 v[174:177], v186 offset:2048
	ds_read_b128 v[178:181], v186 offset:3072
	s_add_i32 s64, s44, 2
	s_add_u32 s45, s42, 0x3fc000
	s_addc_u32 s46, s43, 0
	s_cmp_eq_u32 s57, s44
	s_cselect_b32 s48, s8, s45
	s_cselect_b32 s49, s5, s46
	s_cselect_b32 s46, s29, s31
	s_cselect_b32 s47, s9, s41
	s_add_u32 s44, s48, 0x400000
	s_addc_u32 s45, s49, 0
	v_lshl_add_u64 v[182:183], s[42:43], 0, v[146:147]
	s_add_i32 m0, s20, 0xc000
	ds_read_b128 v[190:193], v187
	ds_read_b128 v[194:197], v187 offset:1024
	ds_read_b128 v[198:201], v187 offset:2048
	ds_read_b128 v[202:205], v187 offset:3072
	ds_read_b128 v[206:209], v187 offset:4096
	ds_read_b128 v[210:213], v187 offset:5120
	ds_read_b128 v[214:217], v187 offset:6144
	ds_read_b128 v[218:221], v187 offset:7168
	global_load_lds_dwordx4 v[182:183], off
	v_lshl_add_u64 v[182:183], s[42:43], 0, v[148:149]
	s_add_i32 m0, s20, 0xe000
	s_nop 0
	global_load_lds_dwordx4 v[182:183], off
	s_waitcnt vmcnt(8)
	s_waitcnt lgkmcnt(0)
	s_barrier
	s_setprio 1
	v_mfma_f32_16x16x32_bf16 v[124:127], v[128:131], v[190:193], v[124:127]
	v_mfma_f32_16x16x32_bf16 v[96:99], v[158:161], v[190:193], v[96:99]
	v_mfma_f32_16x16x32_bf16 v[120:123], v[128:131], v[198:201], v[120:123]
	v_mfma_f32_16x16x32_bf16 v[100:103], v[158:161], v[198:201], v[100:103]
	v_mfma_f32_16x16x32_bf16 v[116:119], v[128:131], v[206:209], v[116:119]
	v_mfma_f32_16x16x32_bf16 v[112:115], v[158:161], v[206:209], v[112:115]
	v_mfma_f32_16x16x32_bf16 v[108:111], v[128:131], v[214:217], v[108:111]
	v_mfma_f32_16x16x32_bf16 v[104:107], v[158:161], v[214:217], v[104:107]
	v_mfma_f32_16x16x32_bf16 v[124:127], v[132:135], v[194:197], v[124:127]
	v_mfma_f32_16x16x32_bf16 v[96:99], v[162:165], v[194:197], v[96:99]
	v_mfma_f32_16x16x32_bf16 v[120:123], v[132:135], v[202:205], v[120:123]
	v_mfma_f32_16x16x32_bf16 v[100:103], v[162:165], v[202:205], v[100:103]
	v_mfma_f32_16x16x32_bf16 v[116:119], v[132:135], v[210:213], v[116:119]
	v_mfma_f32_16x16x32_bf16 v[112:115], v[162:165], v[210:213], v[112:115]
	v_mfma_f32_16x16x32_bf16 v[108:111], v[132:135], v[218:221], v[108:111]
	v_mfma_f32_16x16x32_bf16 v[104:107], v[162:165], v[218:221], v[104:107]
	v_mfma_f32_16x16x32_bf16 v[60:63], v[166:169], v[190:193], v[60:63]
	v_mfma_f32_16x16x32_bf16 v[56:59], v[174:177], v[190:193], v[56:59]
	v_mfma_f32_16x16x32_bf16 v[52:55], v[166:169], v[198:201], v[52:55]
	v_mfma_f32_16x16x32_bf16 v[48:51], v[174:177], v[198:201], v[48:51]
	v_mfma_f32_16x16x32_bf16 v[44:47], v[166:169], v[206:209], v[44:47]
	v_mfma_f32_16x16x32_bf16 v[40:43], v[174:177], v[206:209], v[40:43]
	v_mfma_f32_16x16x32_bf16 v[36:39], v[166:169], v[214:217], v[36:39]
	v_mfma_f32_16x16x32_bf16 v[32:35], v[174:177], v[214:217], v[32:35]
	v_mfma_f32_16x16x32_bf16 v[60:63], v[170:173], v[194:197], v[60:63]
	v_mfma_f32_16x16x32_bf16 v[56:59], v[178:181], v[194:197], v[56:59]
	v_mfma_f32_16x16x32_bf16 v[52:55], v[170:173], v[202:205], v[52:55]
	v_mfma_f32_16x16x32_bf16 v[48:51], v[178:181], v[202:205], v[48:51]
	v_mfma_f32_16x16x32_bf16 v[44:47], v[170:173], v[210:213], v[44:47]
	v_mfma_f32_16x16x32_bf16 v[40:43], v[178:181], v[210:213], v[40:43]
	v_mfma_f32_16x16x32_bf16 v[36:39], v[170:173], v[218:221], v[36:39]
	v_mfma_f32_16x16x32_bf16 v[32:35], v[178:181], v[218:221], v[32:35]
	s_setprio 0
	s_barrier
	s_add_i32 s65, s62, s19
	v_lshl_add_u64 v[182:183], s[46:47], 0, v[138:139]
	s_mov_b32 m0, s65
	ds_read_b128 v[190:193], v187 offset:16384
	ds_read_b128 v[194:197], v187 offset:17408
	ds_read_b128 v[198:201], v187 offset:18432
	ds_read_b128 v[202:205], v187 offset:19456
	ds_read_b128 v[206:209], v187 offset:20480
	ds_read_b128 v[210:213], v187 offset:21504
	ds_read_b128 v[214:217], v187 offset:22528
	ds_read_b128 v[218:221], v187 offset:23552
	global_load_lds_dwordx4 v[182:183], off
	s_add_i32 m0, s65, 0x2000
	s_add_u32 s66, s46, 0x4000
	v_lshl_add_u64 v[182:183], s[46:47], 0, v[142:143]
	s_addc_u32 s67, s47, 0
	s_add_i32 s65, s63, s19
	global_load_lds_dwordx4 v[182:183], off
	v_lshl_add_u64 v[182:183], s[66:67], 0, v[138:139]
	s_mov_b32 m0, s65
	s_nop 0
	global_load_lds_dwordx4 v[182:183], off
	v_lshl_add_u64 v[182:183], s[66:67], 0, v[142:143]
	s_add_i32 m0, s65, 0x2000
	s_nop 0
	global_load_lds_dwordx4 v[182:183], off
	v_lshl_add_u64 v[182:183], s[48:49], 0, v[136:137]
	s_mov_b32 m0, s20
	s_nop 0
	global_load_lds_dwordx4 v[182:183], off
	v_lshl_add_u64 v[182:183], s[48:49], 0, v[140:141]
	s_mov_b32 m0, s21
	s_nop 0
	global_load_lds_dwordx4 v[182:183], off
	s_waitcnt vmcnt(8)
	s_waitcnt lgkmcnt(0)
	s_barrier
; #define PG8_STAGE(bufoff, gbase, voff) do { _Pragma("unroll") for (int _i = 0; _i < 2; ++_i) \
;         __builtin_amdgcn_global_load_lds((const unsigned*)((const char*)(gbase) + (voff)[_i]), (PG8_LAS unsigned*)(lds + (bufoff) + ldsw + _i * 8192), 16, 0, 0); } while (0)
; #define PG8_LDA(dst, b, h) do { _Pragma("unroll") for (int m = 0; m < 4; ++m) _Pragma("unroll") for (int k = 0; k < 2; ++k) dst[m][k] = *(const PG8_LAS bf16x8*)(lds + PG8_SA(b, h) + aoff + m * 2048 + k * 1024); } while (0)
; #define PG8_LDB(dst, b, h) do { _Pragma("unroll") for (int n = 0; n < 2; ++n) _Pragma("unroll") for (int k = 0; k < 2; ++k) dst[n][k] = *(const PG8_LAS bf16x8*)(lds + PG8_SB(b, h) + boff + n * 2048 + k * 1024); } while (0)
; #define PG8_MMA(ai, bj, At, Bt) do { __builtin_amdgcn_s_setprio(1); _Pragma("unroll") for (int m = 0; m < 4; ++m) _Pragma("unroll") for (int n = 0; n < 2; ++n) _Pragma("unroll") for (int k = 0; k < 2; ++k) \
;         acc[ai][bj][m][n] = __builtin_amdgcn_mfma_f32_16x16x32_bf16(Bt[n][k], At[m][k], acc[ai][bj][m][n], 0, 0, 0); __builtin_amdgcn_s_setprio(0); } while (0)
; #define PG8_WAIT_V(n) asm volatile("s_waitcnt vmcnt(" #n ")" ::: "memory")
; #define PG8_WAIT_L(n) asm volatile("s_waitcnt lgkmcnt(" #n ")" ::: "memory")
; #define PG8_BAR __builtin_amdgcn_s_barrier()
; #define PG8_SCHED __builtin_amdgcn_sched_barrier(0)
; template <class Epi, class Sched, bool ALIGN_EPI = false, bool SP2 = false>
; __device__ __forceinline__ void gemm_phase(PG8_LAS unsigned char* lds, const Gemm g, const Sched& S, const Epi& E) {
;     ...
;             PG8_WAIT_V(8); PG8_WAIT_L(0); PG8_BAR; PG8_MMA(1, 0, At, B0); PG8_MMA(1, 1, At, B1); PG8_BAR; PG8_SCHED;
;             PG8_LDB(B0, 1, 0); PG8_LDB(B1, 1, 1); PG8_SCHED; PG8_LDA(At, 1, 0); PG8_STAGE(PG8_SA(0, 1), a2 + hstepA, voffA);
;             PG8_WAIT_V(8); PG8_WAIT_L(0); PG8_BAR; PG8_MMA(0, 0, At, B0); PG8_MMA(0, 1, At, B1); PG8_BAR; PG8_SCHED;
	s_setprio 1
	v_mfma_f32_16x16x32_bf16 v[92:95], v[128:131], v[190:193], v[92:95]
	v_mfma_f32_16x16x32_bf16 v[88:91], v[158:161], v[190:193], v[88:91]
	v_mfma_f32_16x16x32_bf16 v[84:87], v[128:131], v[198:201], v[84:87]
	v_mfma_f32_16x16x32_bf16 v[80:83], v[158:161], v[198:201], v[80:83]
	v_mfma_f32_16x16x32_bf16 v[76:79], v[128:131], v[206:209], v[76:79]
	v_mfma_f32_16x16x32_bf16 v[72:75], v[158:161], v[206:209], v[72:75]
	v_mfma_f32_16x16x32_bf16 v[68:71], v[128:131], v[214:217], v[68:71]
	v_mfma_f32_16x16x32_bf16 v[64:67], v[158:161], v[214:217], v[64:67]
	v_mfma_f32_16x16x32_bf16 v[92:95], v[132:135], v[194:197], v[92:95]
	v_mfma_f32_16x16x32_bf16 v[88:91], v[162:165], v[194:197], v[88:91]
	v_mfma_f32_16x16x32_bf16 v[84:87], v[132:135], v[202:205], v[84:87]
	v_mfma_f32_16x16x32_bf16 v[80:83], v[162:165], v[202:205], v[80:83]
	v_mfma_f32_16x16x32_bf16 v[76:79], v[132:135], v[210:213], v[76:79]
	v_mfma_f32_16x16x32_bf16 v[72:75], v[162:165], v[210:213], v[72:75]
	v_mfma_f32_16x16x32_bf16 v[68:71], v[132:135], v[218:221], v[68:71]
	v_mfma_f32_16x16x32_bf16 v[64:67], v[162:165], v[218:221], v[64:67]
	v_mfma_f32_16x16x32_bf16 v[28:31], v[166:169], v[190:193], v[28:31]
	v_mfma_f32_16x16x32_bf16 v[24:27], v[174:177], v[190:193], v[24:27]
	v_mfma_f32_16x16x32_bf16 v[20:23], v[166:169], v[198:201], v[20:23]
	v_mfma_f32_16x16x32_bf16 v[16:19], v[174:177], v[198:201], v[16:19]
	v_mfma_f32_16x16x32_bf16 v[12:15], v[166:169], v[206:209], v[12:15]
	v_mfma_f32_16x16x32_bf16 v[8:11], v[174:177], v[206:209], v[8:11]
	v_mfma_f32_16x16x32_bf16 v[4:7], v[166:169], v[214:217], v[4:7]
	v_mfma_f32_16x16x32_bf16 v[0:3], v[174:177], v[214:217], v[0:3]
	v_mfma_f32_16x16x32_bf16 v[28:31], v[170:173], v[194:197], v[28:31]
	v_mfma_f32_16x16x32_bf16 v[24:27], v[178:181], v[194:197], v[24:27]
	v_mfma_f32_16x16x32_bf16 v[20:23], v[170:173], v[202:205], v[20:23]
	v_mfma_f32_16x16x32_bf16 v[16:19], v[178:181], v[202:205], v[16:19]
	v_mfma_f32_16x16x32_bf16 v[12:15], v[170:173], v[210:213], v[12:15]
	v_mfma_f32_16x16x32_bf16 v[8:11], v[178:181], v[210:213], v[8:11]
	v_mfma_f32_16x16x32_bf16 v[4:7], v[170:173], v[218:221], v[4:7]
	v_mfma_f32_16x16x32_bf16 v[0:3], v[178:181], v[218:221], v[0:3]
	s_setprio 0
	s_barrier
	s_add_i32 s65, 0, 0x18000
	v_add_u32_e32 v145, s65, v184
	s_add_i32 s66, 0, 0x1c000
	ds_read_b128 v[128:131], v145
	ds_read_b128 v[132:135], v145 offset:1024
	ds_read_b128 v[158:161], v145 offset:2048
	ds_read_b128 v[162:165], v145 offset:3072
	v_add_u32_e32 v145, s66, v184
	ds_read_b128 v[166:169], v145
	ds_read_b128 v[170:173], v145 offset:1024
	ds_read_b128 v[174:177], v145 offset:2048
	ds_read_b128 v[178:181], v145 offset:3072
	s_add_u32 s48, s48, 0x4000
	s_addc_u32 s49, s49, 0
	s_mov_b32 m0, s33
	v_lshl_add_u64 v[182:183], s[48:49], 0, v[136:137]
	ds_read_b128 v[190:193], v187 offset:32768
	ds_read_b128 v[194:197], v187 offset:33792
	ds_read_b128 v[198:201], v187 offset:34816
	ds_read_b128 v[202:205], v187 offset:35840
	ds_read_b128 v[206:209], v187 offset:36864
	ds_read_b128 v[210:213], v187 offset:37888
	ds_read_b128 v[214:217], v187 offset:38912
	ds_read_b128 v[218:221], v187 offset:39936
	global_load_lds_dwordx4 v[182:183], off
	v_lshl_add_u64 v[182:183], s[48:49], 0, v[140:141]
	s_mov_b32 m0, s50
	s_nop 0
	global_load_lds_dwordx4 v[182:183], off
	s_waitcnt vmcnt(8)
	s_waitcnt lgkmcnt(0)
	s_barrier
	s_setprio 1
	v_mfma_f32_16x16x32_bf16 v[124:127], v[128:131], v[190:193], v[124:127]
	v_mfma_f32_16x16x32_bf16 v[96:99], v[158:161], v[190:193], v[96:99]
	v_mfma_f32_16x16x32_bf16 v[120:123], v[128:131], v[198:201], v[120:123]
	v_mfma_f32_16x16x32_bf16 v[100:103], v[158:161], v[198:201], v[100:103]
	v_mfma_f32_16x16x32_bf16 v[116:119], v[128:131], v[206:209], v[116:119]
	v_mfma_f32_16x16x32_bf16 v[112:115], v[158:161], v[206:209], v[112:115]
	v_mfma_f32_16x16x32_bf16 v[108:111], v[128:131], v[214:217], v[108:111]
	v_mfma_f32_16x16x32_bf16 v[104:107], v[158:161], v[214:217], v[104:107]
	v_mfma_f32_16x16x32_bf16 v[124:127], v[132:135], v[194:197], v[124:127]
	v_mfma_f32_16x16x32_bf16 v[96:99], v[162:165], v[194:197], v[96:99]
	v_mfma_f32_16x16x32_bf16 v[120:123], v[132:135], v[202:205], v[120:123]
	v_mfma_f32_16x16x32_bf16 v[100:103], v[162:165], v[202:205], v[100:103]
	v_mfma_f32_16x16x32_bf16 v[116:119], v[132:135], v[210:213], v[116:119]
	v_mfma_f32_16x16x32_bf16 v[112:115], v[162:165], v[210:213], v[112:115]
	v_mfma_f32_16x16x32_bf16 v[108:111], v[132:135], v[218:221], v[108:111]
	v_mfma_f32_16x16x32_bf16 v[104:107], v[162:165], v[218:221], v[104:107]
	v_mfma_f32_16x16x32_bf16 v[60:63], v[166:169], v[190:193], v[60:63]
	v_mfma_f32_16x16x32_bf16 v[56:59], v[174:177], v[190:193], v[56:59]
	v_mfma_f32_16x16x32_bf16 v[52:55], v[166:169], v[198:201], v[52:55]
	v_mfma_f32_16x16x32_bf16 v[48:51], v[174:177], v[198:201], v[48:51]
	v_mfma_f32_16x16x32_bf16 v[44:47], v[166:169], v[206:209], v[44:47]
	v_mfma_f32_16x16x32_bf16 v[40:43], v[174:177], v[206:209], v[40:43]
	v_mfma_f32_16x16x32_bf16 v[36:39], v[166:169], v[214:217], v[36:39]
	v_mfma_f32_16x16x32_bf16 v[32:35], v[174:177], v[214:217], v[32:35]
	v_mfma_f32_16x16x32_bf16 v[60:63], v[170:173], v[194:197], v[60:63]
	v_mfma_f32_16x16x32_bf16 v[56:59], v[178:181], v[194:197], v[56:59]
	v_mfma_f32_16x16x32_bf16 v[52:55], v[170:173], v[202:205], v[52:55]
	v_mfma_f32_16x16x32_bf16 v[48:51], v[178:181], v[202:205], v[48:51]
	v_mfma_f32_16x16x32_bf16 v[44:47], v[170:173], v[210:213], v[44:47]
	v_mfma_f32_16x16x32_bf16 v[40:43], v[178:181], v[210:213], v[40:43]
	v_mfma_f32_16x16x32_bf16 v[36:39], v[170:173], v[218:221], v[36:39]
	v_mfma_f32_16x16x32_bf16 v[32:35], v[178:181], v[218:221], v[32:35]
	s_setprio 0
	s_barrier
; #define PG8_STAGE(bufoff, gbase, voff) do { _Pragma("unroll") for (int _i = 0; _i < 2; ++_i) \
;         __builtin_amdgcn_global_load_lds((const unsigned*)((const char*)(gbase) + (voff)[_i]), (PG8_LAS unsigned*)(lds + (bufoff) + ldsw + _i * 8192), 16, 0, 0); } while (0)
; #define PG8_LDA(dst, b, h) do { _Pragma("unroll") for (int m = 0; m < 4; ++m) _Pragma("unroll") for (int k = 0; k < 2; ++k) dst[m][k] = *(const PG8_LAS bf16x8*)(lds + PG8_SA(b, h) + aoff + m * 2048 + k * 1024); } while (0)
; #define PG8_MMA(ai, bj, At, Bt) do { __builtin_amdgcn_s_setprio(1); _Pragma("unroll") for (int m = 0; m < 4; ++m) _Pragma("unroll") for (int n = 0; n < 2; ++n) _Pragma("unroll") for (int k = 0; k < 2; ++k) \
;         acc[ai][bj][m][n] = __builtin_amdgcn_mfma_f32_16x16x32_bf16(Bt[n][k], At[m][k], acc[ai][bj][m][n], 0, 0, 0); __builtin_amdgcn_s_setprio(0); } while (0)
; #define PG8_WAIT_V(n) asm volatile("s_waitcnt vmcnt(" #n ")" ::: "memory")
; #define PG8_WAIT_L(n) asm volatile("s_waitcnt lgkmcnt(" #n ")" ::: "memory")
; #define PG8_BAR __builtin_amdgcn_s_barrier()
; #define PG8_SCHED __builtin_amdgcn_sched_barrier(0)
; template <class Epi, class Sched, bool ALIGN_EPI = false, bool SP2 = false>
; __device__ __forceinline__ void gemm_phase(PG8_LAS unsigned char* lds, const Gemm g, const Sched& S, const Epi& E) {
;     ...
;             PG8_LDA(At, 1, 1); PG8_STAGE(PG8_SB(1, 0), b3, voffB); PG8_STAGE(PG8_SB(1, 1), b3 + hstepB, voffB); PG8_STAGE(PG8_SA(1, 0), a3, voffA);
;             PG8_WAIT_V(8); PG8_WAIT_L(0); PG8_BAR; PG8_MMA(1, 0, At, B0); PG8_MMA(1, 1, At, B1); PG8_BAR; PG8_SCHED;
	s_add_u32 s48, s46, 0x20000
	s_addc_u32 s49, s47, 0
	s_add_i32 s65, s65, s19
	v_lshl_add_u64 v[182:183], s[48:49], 0, v[138:139]
	s_mov_b32 m0, s65
	ds_read_b128 v[190:193], v187 offset:49152
	ds_read_b128 v[194:197], v187 offset:50176
	ds_read_b128 v[198:201], v187 offset:51200
	ds_read_b128 v[202:205], v187 offset:52224
	ds_read_b128 v[206:209], v187 offset:53248
	ds_read_b128 v[210:213], v187 offset:54272
	ds_read_b128 v[214:217], v187 offset:55296
	ds_read_b128 v[218:221], v187 offset:56320
	global_load_lds_dwordx4 v[182:183], off
	s_add_i32 m0, s65, 0x2000
	s_add_u32 s46, s46, 0x24000
	v_lshl_add_u64 v[182:183], s[48:49], 0, v[142:143]
	s_addc_u32 s47, s47, 0
	s_add_i32 s48, s66, s19
	global_load_lds_dwordx4 v[182:183], off
	v_lshl_add_u64 v[182:183], s[46:47], 0, v[138:139]
	s_mov_b32 m0, s48
	s_nop 0
	global_load_lds_dwordx4 v[182:183], off
	v_lshl_add_u64 v[182:183], s[46:47], 0, v[142:143]
	s_add_i32 m0, s48, 0x2000
	s_nop 0
	global_load_lds_dwordx4 v[182:183], off
	v_lshl_add_u64 v[182:183], s[44:45], 0, v[136:137]
	s_mov_b32 m0, s55
	s_nop 0
	global_load_lds_dwordx4 v[182:183], off
	v_lshl_add_u64 v[182:183], s[44:45], 0, v[140:141]
	s_mov_b32 m0, s56
	s_nop 0
	global_load_lds_dwordx4 v[182:183], off
	s_waitcnt vmcnt(8)
	s_waitcnt lgkmcnt(0)
	s_barrier
	s_setprio 1
	v_mfma_f32_16x16x32_bf16 v[92:95], v[128:131], v[190:193], v[92:95]
	v_mfma_f32_16x16x32_bf16 v[88:91], v[158:161], v[190:193], v[88:91]
	v_mfma_f32_16x16x32_bf16 v[84:87], v[128:131], v[198:201], v[84:87]
	v_mfma_f32_16x16x32_bf16 v[80:83], v[158:161], v[198:201], v[80:83]
	v_mfma_f32_16x16x32_bf16 v[76:79], v[128:131], v[206:209], v[76:79]
	v_mfma_f32_16x16x32_bf16 v[72:75], v[158:161], v[206:209], v[72:75]
	v_mfma_f32_16x16x32_bf16 v[68:71], v[128:131], v[214:217], v[68:71]
	v_mfma_f32_16x16x32_bf16 v[64:67], v[158:161], v[214:217], v[64:67]
	v_mfma_f32_16x16x32_bf16 v[92:95], v[132:135], v[194:197], v[92:95]
	v_mfma_f32_16x16x32_bf16 v[88:91], v[162:165], v[194:197], v[88:91]
	v_mfma_f32_16x16x32_bf16 v[84:87], v[132:135], v[202:205], v[84:87]
	v_mfma_f32_16x16x32_bf16 v[80:83], v[162:165], v[202:205], v[80:83]
	v_mfma_f32_16x16x32_bf16 v[76:79], v[132:135], v[210:213], v[76:79]
	v_mfma_f32_16x16x32_bf16 v[72:75], v[162:165], v[210:213], v[72:75]
	v_mfma_f32_16x16x32_bf16 v[68:71], v[132:135], v[218:221], v[68:71]
	v_mfma_f32_16x16x32_bf16 v[64:67], v[162:165], v[218:221], v[64:67]
	v_mfma_f32_16x16x32_bf16 v[28:31], v[166:169], v[190:193], v[28:31]
	v_mfma_f32_16x16x32_bf16 v[24:27], v[174:177], v[190:193], v[24:27]
	v_mfma_f32_16x16x32_bf16 v[20:23], v[166:169], v[198:201], v[20:23]
	v_mfma_f32_16x16x32_bf16 v[16:19], v[174:177], v[198:201], v[16:19]
	v_mfma_f32_16x16x32_bf16 v[12:15], v[166:169], v[206:209], v[12:15]
	v_mfma_f32_16x16x32_bf16 v[8:11], v[174:177], v[206:209], v[8:11]
	v_mfma_f32_16x16x32_bf16 v[4:7], v[166:169], v[214:217], v[4:7]
	v_mfma_f32_16x16x32_bf16 v[0:3], v[174:177], v[214:217], v[0:3]
	v_mfma_f32_16x16x32_bf16 v[28:31], v[170:173], v[194:197], v[28:31]
	v_mfma_f32_16x16x32_bf16 v[24:27], v[178:181], v[194:197], v[24:27]
	v_mfma_f32_16x16x32_bf16 v[20:23], v[170:173], v[202:205], v[20:23]
	v_mfma_f32_16x16x32_bf16 v[16:19], v[178:181], v[202:205], v[16:19]
	v_mfma_f32_16x16x32_bf16 v[12:15], v[170:173], v[210:213], v[12:15]
	v_mfma_f32_16x16x32_bf16 v[8:11], v[178:181], v[210:213], v[8:11]
	v_mfma_f32_16x16x32_bf16 v[4:7], v[170:173], v[218:221], v[4:7]
	v_mfma_f32_16x16x32_bf16 v[0:3], v[178:181], v[218:221], v[0:3]
	s_setprio 0
	s_barrier
	s_add_u32 s31, s31, 0x40000
	s_addc_u32 s41, s41, 0
	s_add_u32 s42, s42, 0x800000
	s_addc_u32 s43, s43, 0
	s_cmp_ge_i32 s64, s52
	s_mov_b32 s44, s64
	s_cbranch_scc0 .LBB0_1602

; #define PG8_STAGE(bufoff, gbase, voff) do { _Pragma("unroll") for (int _i = 0; _i < 2; ++_i) \
;         __builtin_amdgcn_global_load_lds((const unsigned*)((const char*)(gbase) + (voff)[_i]), (PG8_LAS unsigned*)(lds + (bufoff) + ldsw + _i * 8192), 16, 0, 0); } while (0)
; #define PG8_LDA(dst, b, h) do { _Pragma("unroll") for (int m = 0; m < 4; ++m) _Pragma("unroll") for (int k = 0; k < 2; ++k) dst[m][k] = *(const PG8_LAS bf16x8*)(lds + PG8_SA(b, h) + aoff + m * 2048 + k * 1024); } while (0)
; #define PG8_LDB(dst, b, h) do { _Pragma("unroll") for (int n = 0; n < 2; ++n) _Pragma("unroll") for (int k = 0; k < 2; ++k) dst[n][k] = *(const PG8_LAS bf16x8*)(lds + PG8_SB(b, h) + boff + n * 2048 + k * 1024); } while (0)
; #define PG8_MMA(ai, bj, At, Bt) do { __builtin_amdgcn_s_setprio(1); _Pragma("unroll") for (int m = 0; m < 4; ++m) _Pragma("unroll") for (int n = 0; n < 2; ++n) _Pragma("unroll") for (int k = 0; k < 2; ++k) \
;         acc[ai][bj][m][n] = __builtin_amdgcn_mfma_f32_16x16x32_bf16(Bt[n][k], At[m][k], acc[ai][bj][m][n], 0, 0, 0); __builtin_amdgcn_s_setprio(0); } while (0)
; #define PG8_WAIT_V(n) asm volatile("s_waitcnt vmcnt(" #n ")" ::: "memory")
; #define PG8_WAIT_L(n) asm volatile("s_waitcnt lgkmcnt(" #n ")" ::: "memory")
; template <class Epi, class Sched, bool ALIGN_EPI = false, bool SP2 = false>
; __device__ __forceinline__ void gemm_phase(PG8_LAS unsigned char* lds, const Gemm g, const Sched& S, const Epi& E) {
;     ...
;             const bool last = (t == nt - 2);
;             const char* a1 = cA + (long)(t + 1) * kstepA;
;             const char* a2 = last ? nA : cA + (long)(t + 2) * kstepA; const char* b2 = last ? nB : cB + (long)(t + 2) * kstep;
;             const char* a3 = a2 + kstepA; const char* b3 = b2 + kstep;
;             if (last && has_next) S.a_ready(nxt);
;             if constexpr (SP2) {
;             PG8_LDB(B0, 0, 0); PG8_LDB(B1, 0, 1); PG8_SCHED; PG8_LDA(At, 0, 0); PG8_STAGE(PG8_SA(1, 1), a1 + hstepA, voffA);
;             PG8_WAIT_V(8); PG8_WAIT_L(0); PG8_BAR; PG8_MMA(0, 0, At, B0); PG8_MMA(0, 1, At, B1); PG8_BAR; PG8_SCHED;
;             PG8_LDA(At, 0, 1); PG8_STAGE(PG8_SB(0, 0), b2, voffB); PG8_STAGE(PG8_SB(0, 1), b2 + hstepB, voffB); PG8_STAGE(PG8_SA(0, 0), a2, voffA);
;             PG8_WAIT_V(8); PG8_WAIT_L(0); PG8_BAR; PG8_MMA(1, 0, At, B0); PG8_MMA(1, 1, At, B1); PG8_BAR; PG8_SCHED;
.LBB0_1695:
	ds_read_b128 v[120:123], v183
	ds_read_b128 v[124:127], v183 offset:1024
	ds_read_b128 v[136:139], v183 offset:2048
	ds_read_b128 v[140:143], v183 offset:3072
	ds_read_b128 v[144:147], v187
	ds_read_b128 v[148:151], v187 offset:1024
	ds_read_b128 v[192:195], v187 offset:2048
	ds_read_b128 v[196:199], v187 offset:3072
	s_add_i32 s67, s36, 2
	s_add_u32 s37, s12, 0xfffc0080
	s_addc_u32 s52, s13, -1
	s_cmp_eq_u32 s63, s36
	s_cselect_b32 s36, s21, s45
	s_cselect_b32 s53, s11, s52
	s_cselect_b32 s52, s19, s37
	s_cselect_b32 s37, s20, s47
	v_lshl_add_u64 v[168:169], s[12:13], 0, v[160:161]
	s_add_i32 m0, s58, 0xc000
	ds_read_b128 v[200:203], v191
	ds_read_b128 v[204:207], v191 offset:1024
	ds_read_b128 v[208:211], v191 offset:2048
	ds_read_b128 v[212:215], v191 offset:3072
	ds_read_b128 v[216:219], v191 offset:4096
	ds_read_b128 v[220:223], v191 offset:5120
	ds_read_b128 v[224:227], v191 offset:6144
	ds_read_b128 v[228:231], v191 offset:7168
	global_load_lds_dwordx4 v[168:169], off
	v_lshl_add_u64 v[168:169], s[12:13], 0, v[162:163]
	s_add_i32 m0, s58, 0xe000
	s_nop 0
	global_load_lds_dwordx4 v[168:169], off
	s_waitcnt vmcnt(8)
	s_waitcnt lgkmcnt(0)
	s_barrier
	s_setprio 1
	v_mfma_f32_16x16x32_bf16 v[132:135], v[120:123], v[200:203], v[132:135]
	v_mfma_f32_16x16x32_bf16 v[128:131], v[136:139], v[200:203], v[128:131]
	v_mfma_f32_16x16x32_bf16 v[116:119], v[120:123], v[208:211], v[116:119]
	v_mfma_f32_16x16x32_bf16 v[112:115], v[136:139], v[208:211], v[112:115]
	v_mfma_f32_16x16x32_bf16 v[108:111], v[120:123], v[216:219], v[108:111]
	v_mfma_f32_16x16x32_bf16 v[104:107], v[136:139], v[216:219], v[104:107]
	v_mfma_f32_16x16x32_bf16 v[100:103], v[120:123], v[224:227], v[100:103]
	v_mfma_f32_16x16x32_bf16 v[96:99], v[136:139], v[224:227], v[96:99]
	v_mfma_f32_16x16x32_bf16 v[132:135], v[124:127], v[204:207], v[132:135]
	v_mfma_f32_16x16x32_bf16 v[128:131], v[140:143], v[204:207], v[128:131]
	v_mfma_f32_16x16x32_bf16 v[116:119], v[124:127], v[212:215], v[116:119]
	v_mfma_f32_16x16x32_bf16 v[112:115], v[140:143], v[212:215], v[112:115]
	v_mfma_f32_16x16x32_bf16 v[108:111], v[124:127], v[220:223], v[108:111]
	v_mfma_f32_16x16x32_bf16 v[104:107], v[140:143], v[220:223], v[104:107]
	v_mfma_f32_16x16x32_bf16 v[100:103], v[124:127], v[228:231], v[100:103]
	v_mfma_f32_16x16x32_bf16 v[96:99], v[140:143], v[228:231], v[96:99]
	v_mfma_f32_16x16x32_bf16 v[60:63], v[144:147], v[200:203], v[60:63]
	v_mfma_f32_16x16x32_bf16 v[56:59], v[192:195], v[200:203], v[56:59]
	v_mfma_f32_16x16x32_bf16 v[52:55], v[144:147], v[208:211], v[52:55]
	v_mfma_f32_16x16x32_bf16 v[48:51], v[192:195], v[208:211], v[48:51]
	v_mfma_f32_16x16x32_bf16 v[44:47], v[144:147], v[216:219], v[44:47]
	v_mfma_f32_16x16x32_bf16 v[40:43], v[192:195], v[216:219], v[40:43]
	v_mfma_f32_16x16x32_bf16 v[36:39], v[144:147], v[224:227], v[36:39]
	v_mfma_f32_16x16x32_bf16 v[32:35], v[192:195], v[224:227], v[32:35]
	v_mfma_f32_16x16x32_bf16 v[60:63], v[148:151], v[204:207], v[60:63]
	v_mfma_f32_16x16x32_bf16 v[56:59], v[196:199], v[204:207], v[56:59]
	v_mfma_f32_16x16x32_bf16 v[52:55], v[148:151], v[212:215], v[52:55]
	v_mfma_f32_16x16x32_bf16 v[48:51], v[196:199], v[212:215], v[48:51]
	v_mfma_f32_16x16x32_bf16 v[44:47], v[148:151], v[220:223], v[44:47]
	v_mfma_f32_16x16x32_bf16 v[40:43], v[196:199], v[220:223], v[40:43]
	v_mfma_f32_16x16x32_bf16 v[36:39], v[148:151], v[228:231], v[36:39]
	v_mfma_f32_16x16x32_bf16 v[32:35], v[196:199], v[228:231], v[32:35]
	s_setprio 0
	s_barrier
	s_add_i32 s68, s65, s57
	v_lshl_add_u64 v[168:169], s[36:37], 0, v[154:155]
	s_mov_b32 m0, s68
	ds_read_b128 v[200:203], v191 offset:16384
	ds_read_b128 v[204:207], v191 offset:17408
	ds_read_b128 v[208:211], v191 offset:18432
	ds_read_b128 v[212:215], v191 offset:19456
	ds_read_b128 v[216:219], v191 offset:20480
	ds_read_b128 v[220:223], v191 offset:21504
	ds_read_b128 v[224:227], v191 offset:22528
	ds_read_b128 v[228:231], v191 offset:23552
	global_load_lds_dwordx4 v[168:169], off
	s_add_i32 m0, s68, 0x2000
	s_add_u32 s68, s36, 0x40000
	v_lshl_add_u64 v[172:173], s[36:37], 0, v[158:159]
	s_addc_u32 s69, s37, 0
	s_add_i32 s70, s66, s57
	global_load_lds_dwordx4 v[172:173], off
	v_lshl_add_u64 v[176:177], s[68:69], 0, v[154:155]
	s_mov_b32 m0, s70
	v_lshl_add_u64 v[180:181], s[52:53], 0, v[156:157]
	global_load_lds_dwordx4 v[176:177], off
	v_lshl_add_u64 v[176:177], s[68:69], 0, v[158:159]
	s_add_i32 m0, s70, 0x2000
	s_nop 0
	global_load_lds_dwordx4 v[176:177], off
	v_lshl_add_u64 v[176:177], s[52:53], 0, v[152:153]
	s_mov_b32 m0, s58
	s_nop 0
	global_load_lds_dwordx4 v[176:177], off
	s_mov_b32 m0, s33
	s_nop 0
	global_load_lds_dwordx4 v[180:181], off
	s_waitcnt vmcnt(8)
	s_waitcnt lgkmcnt(0)
	s_barrier
; #define PG8_STAGE(bufoff, gbase, voff) do { _Pragma("unroll") for (int _i = 0; _i < 2; ++_i) \
;         __builtin_amdgcn_global_load_lds((const unsigned*)((const char*)(gbase) + (voff)[_i]), (PG8_LAS unsigned*)(lds + (bufoff) + ldsw + _i * 8192), 16, 0, 0); } while (0)
; #define PG8_LDA(dst, b, h) do { _Pragma("unroll") for (int m = 0; m < 4; ++m) _Pragma("unroll") for (int k = 0; k < 2; ++k) dst[m][k] = *(const PG8_LAS bf16x8*)(lds + PG8_SA(b, h) + aoff + m * 2048 + k * 1024); } while (0)
; #define PG8_LDB(dst, b, h) do { _Pragma("unroll") for (int n = 0; n < 2; ++n) _Pragma("unroll") for (int k = 0; k < 2; ++k) dst[n][k] = *(const PG8_LAS bf16x8*)(lds + PG8_SB(b, h) + boff + n * 2048 + k * 1024); } while (0)
; #define PG8_MMA(ai, bj, At, Bt) do { __builtin_amdgcn_s_setprio(1); _Pragma("unroll") for (int m = 0; m < 4; ++m) _Pragma("unroll") for (int n = 0; n < 2; ++n) _Pragma("unroll") for (int k = 0; k < 2; ++k) \
;         acc[ai][bj][m][n] = __builtin_amdgcn_mfma_f32_16x16x32_bf16(Bt[n][k], At[m][k], acc[ai][bj][m][n], 0, 0, 0); __builtin_amdgcn_s_setprio(0); } while (0)
; #define PG8_WAIT_V(n) asm volatile("s_waitcnt vmcnt(" #n ")" ::: "memory")
; #define PG8_WAIT_L(n) asm volatile("s_waitcnt lgkmcnt(" #n ")" ::: "memory")
; #define PG8_BAR __builtin_amdgcn_s_barrier()
; #define PG8_SCHED __builtin_amdgcn_sched_barrier(0)
; template <class Epi, class Sched, bool ALIGN_EPI = false, bool SP2 = false>
; __device__ __forceinline__ void gemm_phase(PG8_LAS unsigned char* lds, const Gemm g, const Sched& S, const Epi& E) {
;     ...
;             PG8_WAIT_V(8); PG8_WAIT_L(0); PG8_BAR; PG8_MMA(1, 0, At, B0); PG8_MMA(1, 1, At, B1); PG8_BAR; PG8_SCHED;
;             PG8_LDB(B0, 1, 0); PG8_LDB(B1, 1, 1); PG8_SCHED; PG8_LDA(At, 1, 0); PG8_STAGE(PG8_SA(0, 1), a2 + hstepA, voffA);
;             PG8_WAIT_V(8); PG8_WAIT_L(0); PG8_BAR; PG8_MMA(0, 0, At, B0); PG8_MMA(0, 1, At, B1); PG8_BAR; PG8_SCHED;
	s_setprio 1
	v_mfma_f32_16x16x32_bf16 v[92:95], v[120:123], v[200:203], v[92:95]
	v_mfma_f32_16x16x32_bf16 v[88:91], v[136:139], v[200:203], v[88:91]
	v_mfma_f32_16x16x32_bf16 v[84:87], v[120:123], v[208:211], v[84:87]
	v_mfma_f32_16x16x32_bf16 v[80:83], v[136:139], v[208:211], v[80:83]
	v_mfma_f32_16x16x32_bf16 v[76:79], v[120:123], v[216:219], v[76:79]
	v_mfma_f32_16x16x32_bf16 v[72:75], v[136:139], v[216:219], v[72:75]
	v_mfma_f32_16x16x32_bf16 v[68:71], v[120:123], v[224:227], v[68:71]
	v_mfma_f32_16x16x32_bf16 v[64:67], v[136:139], v[224:227], v[64:67]
	v_mfma_f32_16x16x32_bf16 v[92:95], v[124:127], v[204:207], v[92:95]
	v_mfma_f32_16x16x32_bf16 v[88:91], v[140:143], v[204:207], v[88:91]
	v_mfma_f32_16x16x32_bf16 v[84:87], v[124:127], v[212:215], v[84:87]
	v_mfma_f32_16x16x32_bf16 v[80:83], v[140:143], v[212:215], v[80:83]
	v_mfma_f32_16x16x32_bf16 v[76:79], v[124:127], v[220:223], v[76:79]
	v_mfma_f32_16x16x32_bf16 v[72:75], v[140:143], v[220:223], v[72:75]
	v_mfma_f32_16x16x32_bf16 v[68:71], v[124:127], v[228:231], v[68:71]
	v_mfma_f32_16x16x32_bf16 v[64:67], v[140:143], v[228:231], v[64:67]
	v_mfma_f32_16x16x32_bf16 v[28:31], v[144:147], v[200:203], v[28:31]
	v_mfma_f32_16x16x32_bf16 v[24:27], v[192:195], v[200:203], v[24:27]
	v_mfma_f32_16x16x32_bf16 v[20:23], v[144:147], v[208:211], v[20:23]
	v_mfma_f32_16x16x32_bf16 v[16:19], v[192:195], v[208:211], v[16:19]
	v_mfma_f32_16x16x32_bf16 v[12:15], v[144:147], v[216:219], v[12:15]
	v_mfma_f32_16x16x32_bf16 v[8:11], v[192:195], v[216:219], v[8:11]
	v_mfma_f32_16x16x32_bf16 v[4:7], v[144:147], v[224:227], v[4:7]
	v_mfma_f32_16x16x32_bf16 v[0:3], v[192:195], v[224:227], v[0:3]
	v_mfma_f32_16x16x32_bf16 v[28:31], v[148:151], v[204:207], v[28:31]
	v_mfma_f32_16x16x32_bf16 v[24:27], v[196:199], v[204:207], v[24:27]
	v_mfma_f32_16x16x32_bf16 v[20:23], v[148:151], v[212:215], v[20:23]
	v_mfma_f32_16x16x32_bf16 v[16:19], v[196:199], v[212:215], v[16:19]
	v_mfma_f32_16x16x32_bf16 v[12:15], v[148:151], v[220:223], v[12:15]
	v_mfma_f32_16x16x32_bf16 v[8:11], v[196:199], v[220:223], v[8:11]
	v_mfma_f32_16x16x32_bf16 v[4:7], v[148:151], v[228:231], v[4:7]
	v_mfma_f32_16x16x32_bf16 v[0:3], v[196:199], v[228:231], v[0:3]
	s_setprio 0
	s_barrier
	s_add_i32 s68, 0, 0x18000
	s_add_i32 s69, 0, 0x1c000
	v_add_u32_e32 v140, s68, v179
	v_add_u32_e32 v170, s69, v179
	ds_read_b128 v[120:123], v140
	ds_read_b128 v[124:127], v140 offset:1024
	ds_read_b128 v[136:139], v140 offset:2048
	ds_read_b128 v[140:143], v140 offset:3072
	ds_read_b128 v[144:147], v170
	ds_read_b128 v[148:151], v170 offset:1024
	ds_read_b128 v[192:195], v170 offset:2048
	ds_read_b128 v[196:199], v170 offset:3072
	s_add_u32 s52, s52, 0x40000
	s_addc_u32 s53, s53, 0
	s_mov_b32 m0, s59
	v_lshl_add_u64 v[184:185], s[52:53], 0, v[152:153]
	ds_read_b128 v[200:203], v191 offset:32768
	ds_read_b128 v[204:207], v191 offset:33792
	ds_read_b128 v[208:211], v191 offset:34816
	ds_read_b128 v[212:215], v191 offset:35840
	ds_read_b128 v[216:219], v191 offset:36864
	ds_read_b128 v[220:223], v191 offset:37888
	ds_read_b128 v[224:227], v191 offset:38912
	ds_read_b128 v[228:231], v191 offset:39936
	global_load_lds_dwordx4 v[184:185], off
	v_lshl_add_u64 v[184:185], s[52:53], 0, v[156:157]
	s_mov_b32 m0, s60
	s_nop 0
	global_load_lds_dwordx4 v[184:185], off
	s_waitcnt vmcnt(8)
	s_waitcnt lgkmcnt(0)
	s_barrier
	s_setprio 1
	v_mfma_f32_16x16x32_bf16 v[132:135], v[120:123], v[200:203], v[132:135]
	v_mfma_f32_16x16x32_bf16 v[128:131], v[136:139], v[200:203], v[128:131]
	v_mfma_f32_16x16x32_bf16 v[116:119], v[120:123], v[208:211], v[116:119]
	v_mfma_f32_16x16x32_bf16 v[112:115], v[136:139], v[208:211], v[112:115]
	v_mfma_f32_16x16x32_bf16 v[108:111], v[120:123], v[216:219], v[108:111]
	v_mfma_f32_16x16x32_bf16 v[104:107], v[136:139], v[216:219], v[104:107]
	v_mfma_f32_16x16x32_bf16 v[100:103], v[120:123], v[224:227], v[100:103]
	v_mfma_f32_16x16x32_bf16 v[96:99], v[136:139], v[224:227], v[96:99]
	v_mfma_f32_16x16x32_bf16 v[132:135], v[124:127], v[204:207], v[132:135]
	v_mfma_f32_16x16x32_bf16 v[128:131], v[140:143], v[204:207], v[128:131]
	v_mfma_f32_16x16x32_bf16 v[116:119], v[124:127], v[212:215], v[116:119]
	v_mfma_f32_16x16x32_bf16 v[112:115], v[140:143], v[212:215], v[112:115]
	v_mfma_f32_16x16x32_bf16 v[108:111], v[124:127], v[220:223], v[108:111]
	v_mfma_f32_16x16x32_bf16 v[104:107], v[140:143], v[220:223], v[104:107]
	v_mfma_f32_16x16x32_bf16 v[100:103], v[124:127], v[228:231], v[100:103]
	v_mfma_f32_16x16x32_bf16 v[96:99], v[140:143], v[228:231], v[96:99]
	v_mfma_f32_16x16x32_bf16 v[60:63], v[144:147], v[200:203], v[60:63]
	v_mfma_f32_16x16x32_bf16 v[56:59], v[192:195], v[200:203], v[56:59]
	v_mfma_f32_16x16x32_bf16 v[52:55], v[144:147], v[208:211], v[52:55]
	v_mfma_f32_16x16x32_bf16 v[48:51], v[192:195], v[208:211], v[48:51]
	v_mfma_f32_16x16x32_bf16 v[44:47], v[144:147], v[216:219], v[44:47]
	v_mfma_f32_16x16x32_bf16 v[40:43], v[192:195], v[216:219], v[40:43]
	v_mfma_f32_16x16x32_bf16 v[36:39], v[144:147], v[224:227], v[36:39]
	v_mfma_f32_16x16x32_bf16 v[32:35], v[192:195], v[224:227], v[32:35]
	v_mfma_f32_16x16x32_bf16 v[60:63], v[148:151], v[204:207], v[60:63]
	v_mfma_f32_16x16x32_bf16 v[56:59], v[196:199], v[204:207], v[56:59]
	v_mfma_f32_16x16x32_bf16 v[52:55], v[148:151], v[212:215], v[52:55]
	v_mfma_f32_16x16x32_bf16 v[48:51], v[196:199], v[212:215], v[48:51]
	v_mfma_f32_16x16x32_bf16 v[44:47], v[148:151], v[220:223], v[44:47]
	v_mfma_f32_16x16x32_bf16 v[40:43], v[196:199], v[220:223], v[40:43]
	v_mfma_f32_16x16x32_bf16 v[36:39], v[148:151], v[228:231], v[36:39]
	v_mfma_f32_16x16x32_bf16 v[32:35], v[196:199], v[228:231], v[32:35]
	s_setprio 0
	s_barrier
; #define PG8_STAGE(bufoff, gbase, voff) do { _Pragma("unroll") for (int _i = 0; _i < 2; ++_i) \
;         __builtin_amdgcn_global_load_lds((const unsigned*)((const char*)(gbase) + (voff)[_i]), (PG8_LAS unsigned*)(lds + (bufoff) + ldsw + _i * 8192), 16, 0, 0); } while (0)
; #define PG8_LDA(dst, b, h) do { _Pragma("unroll") for (int m = 0; m < 4; ++m) _Pragma("unroll") for (int k = 0; k < 2; ++k) dst[m][k] = *(const PG8_LAS bf16x8*)(lds + PG8_SA(b, h) + aoff + m * 2048 + k * 1024); } while (0)
; #define PG8_MMA(ai, bj, At, Bt) do { __builtin_amdgcn_s_setprio(1); _Pragma("unroll") for (int m = 0; m < 4; ++m) _Pragma("unroll") for (int n = 0; n < 2; ++n) _Pragma("unroll") for (int k = 0; k < 2; ++k) \
;         acc[ai][bj][m][n] = __builtin_amdgcn_mfma_f32_16x16x32_bf16(Bt[n][k], At[m][k], acc[ai][bj][m][n], 0, 0, 0); __builtin_amdgcn_s_setprio(0); } while (0)
; #define PG8_WAIT_V(n) asm volatile("s_waitcnt vmcnt(" #n ")" ::: "memory")
; #define PG8_WAIT_L(n) asm volatile("s_waitcnt lgkmcnt(" #n ")" ::: "memory")
; #define PG8_BAR __builtin_amdgcn_s_barrier()
; #define PG8_SCHED __builtin_amdgcn_sched_barrier(0)
; template <class Epi, class Sched, bool ALIGN_EPI = false, bool SP2 = false>
; __device__ __forceinline__ void gemm_phase(PG8_LAS unsigned char* lds, const Gemm g, const Sched& S, const Epi& E) {
;     ...
;         for (int t = 0; t < nt; t += 2) {
;             const bool last = (t == nt - 2);
;             const char* a1 = cA + (long)(t + 1) * kstepA;
;             const char* a2 = last ? nA : cA + (long)(t + 2) * kstepA; const char* b2 = last ? nB : cB + (long)(t + 2) * kstep;
;     ...
;             PG8_LDA(At, 1, 1); PG8_STAGE(PG8_SB(1, 0), b3, voffB); PG8_STAGE(PG8_SB(1, 1), b3 + hstepB, voffB); PG8_STAGE(PG8_SA(1, 0), a3, voffA);
;             PG8_WAIT_V(8); PG8_WAIT_L(0); PG8_BAR; PG8_MMA(1, 0, At, B0); PG8_MMA(1, 1, At, B1); PG8_BAR; PG8_SCHED;
	s_add_i32 s52, s68, s57
	v_lshl_add_u64 v[168:169], v[168:169], 0, s[30:31]
	s_mov_b32 m0, s52
	ds_read_b128 v[200:203], v191 offset:49152
	ds_read_b128 v[204:207], v191 offset:50176
	ds_read_b128 v[208:211], v191 offset:51200
	ds_read_b128 v[212:215], v191 offset:52224
	ds_read_b128 v[216:219], v191 offset:53248
	ds_read_b128 v[220:223], v191 offset:54272
	ds_read_b128 v[224:227], v191 offset:55296
	ds_read_b128 v[228:231], v191 offset:56320
	global_load_lds_dwordx4 v[168:169], off
	s_add_i32 m0, s52, 0x2000
	s_add_u32 s36, s36, 0x40080
	v_lshl_add_u64 v[168:169], v[172:173], 0, s[30:31]
	s_addc_u32 s37, s37, 0
	s_add_i32 s52, s69, s57
	global_load_lds_dwordx4 v[168:169], off
	v_lshl_add_u64 v[168:169], s[36:37], 0, v[154:155]
	s_mov_b32 m0, s52
	s_nop 0
	global_load_lds_dwordx4 v[168:169], off
	v_lshl_add_u64 v[168:169], s[36:37], 0, v[158:159]
	s_add_i32 m0, s52, 0x2000
	s_nop 0
	global_load_lds_dwordx4 v[168:169], off
	v_lshl_add_u64 v[168:169], v[176:177], 0, s[30:31]
	s_mov_b32 m0, s17
	s_nop 0
	global_load_lds_dwordx4 v[168:169], off
	v_lshl_add_u64 v[168:169], v[180:181], 0, s[30:31]
	s_mov_b32 m0, s62
	s_nop 0
	global_load_lds_dwordx4 v[168:169], off
	s_waitcnt vmcnt(8)
	s_waitcnt lgkmcnt(0)
	s_barrier
	s_setprio 1
	v_mfma_f32_16x16x32_bf16 v[92:95], v[120:123], v[200:203], v[92:95]
	v_mfma_f32_16x16x32_bf16 v[88:91], v[136:139], v[200:203], v[88:91]
	v_mfma_f32_16x16x32_bf16 v[84:87], v[120:123], v[208:211], v[84:87]
	v_mfma_f32_16x16x32_bf16 v[80:83], v[136:139], v[208:211], v[80:83]
	v_mfma_f32_16x16x32_bf16 v[76:79], v[120:123], v[216:219], v[76:79]
	v_mfma_f32_16x16x32_bf16 v[72:75], v[136:139], v[216:219], v[72:75]
	v_mfma_f32_16x16x32_bf16 v[68:71], v[120:123], v[224:227], v[68:71]
	v_mfma_f32_16x16x32_bf16 v[64:67], v[136:139], v[224:227], v[64:67]
	v_mfma_f32_16x16x32_bf16 v[92:95], v[124:127], v[204:207], v[92:95]
	v_mfma_f32_16x16x32_bf16 v[88:91], v[140:143], v[204:207], v[88:91]
	v_mfma_f32_16x16x32_bf16 v[84:87], v[124:127], v[212:215], v[84:87]
	v_mfma_f32_16x16x32_bf16 v[80:83], v[140:143], v[212:215], v[80:83]
	v_mfma_f32_16x16x32_bf16 v[76:79], v[124:127], v[220:223], v[76:79]
	v_mfma_f32_16x16x32_bf16 v[72:75], v[140:143], v[220:223], v[72:75]
	v_mfma_f32_16x16x32_bf16 v[68:71], v[124:127], v[228:231], v[68:71]
	v_mfma_f32_16x16x32_bf16 v[64:67], v[140:143], v[228:231], v[64:67]
	v_mfma_f32_16x16x32_bf16 v[28:31], v[144:147], v[200:203], v[28:31]
	v_mfma_f32_16x16x32_bf16 v[24:27], v[192:195], v[200:203], v[24:27]
	v_mfma_f32_16x16x32_bf16 v[20:23], v[144:147], v[208:211], v[20:23]
	v_mfma_f32_16x16x32_bf16 v[16:19], v[192:195], v[208:211], v[16:19]
	v_mfma_f32_16x16x32_bf16 v[12:15], v[144:147], v[216:219], v[12:15]
	v_mfma_f32_16x16x32_bf16 v[8:11], v[192:195], v[216:219], v[8:11]
	v_mfma_f32_16x16x32_bf16 v[4:7], v[144:147], v[224:227], v[4:7]
	v_mfma_f32_16x16x32_bf16 v[0:3], v[192:195], v[224:227], v[0:3]
	v_mfma_f32_16x16x32_bf16 v[28:31], v[148:151], v[204:207], v[28:31]
	v_mfma_f32_16x16x32_bf16 v[24:27], v[196:199], v[204:207], v[24:27]
	v_mfma_f32_16x16x32_bf16 v[20:23], v[148:151], v[212:215], v[20:23]
	v_mfma_f32_16x16x32_bf16 v[16:19], v[196:199], v[212:215], v[16:19]
	v_mfma_f32_16x16x32_bf16 v[12:15], v[148:151], v[220:223], v[12:15]
	v_mfma_f32_16x16x32_bf16 v[8:11], v[196:199], v[220:223], v[8:11]
	v_mfma_f32_16x16x32_bf16 v[4:7], v[148:151], v[228:231], v[4:7]
	v_mfma_f32_16x16x32_bf16 v[0:3], v[196:199], v[228:231], v[0:3]
	s_setprio 0
	s_barrier
	s_add_u32 s12, s12, 0x100
	s_addc_u32 s13, s13, 0
	s_add_u32 s45, s45, 0x100
	s_addc_u32 s47, s47, 0
	s_cmp_ge_i32 s67, s14
	s_mov_b32 s36, s67
	s_cbranch_scc0 .LBB0_1695

; #define PG8_STAGE(bufoff, gbase, voff) do { _Pragma("unroll") for (int _i = 0; _i < 2; ++_i) \
;         __builtin_amdgcn_global_load_lds((const unsigned*)((const char*)(gbase) + (voff)[_i]), (PG8_LAS unsigned*)(lds + (bufoff) + ldsw + _i * 8192), 16, 0, 0); } while (0)
; #define PG8_LDA(dst, b, h) do { _Pragma("unroll") for (int m = 0; m < 4; ++m) _Pragma("unroll") for (int k = 0; k < 2; ++k) dst[m][k] = *(const PG8_LAS bf16x8*)(lds + PG8_SA(b, h) + aoff + m * 2048 + k * 1024); } while (0)
; #define PG8_LDB(dst, b, h) do { _Pragma("unroll") for (int n = 0; n < 2; ++n) _Pragma("unroll") for (int k = 0; k < 2; ++k) dst[n][k] = *(const PG8_LAS bf16x8*)(lds + PG8_SB(b, h) + boff + n * 2048 + k * 1024); } while (0)
; #define PG8_MMA(ai, bj, At, Bt) do { __builtin_amdgcn_s_setprio(1); _Pragma("unroll") for (int m = 0; m < 4; ++m) _Pragma("unroll") for (int n = 0; n < 2; ++n) _Pragma("unroll") for (int k = 0; k < 2; ++k) \
;         acc[ai][bj][m][n] = __builtin_amdgcn_mfma_f32_16x16x32_bf16(Bt[n][k], At[m][k], acc[ai][bj][m][n], 0, 0, 0); __builtin_amdgcn_s_setprio(0); } while (0)
; #define PG8_WAIT_V(n) asm volatile("s_waitcnt vmcnt(" #n ")" ::: "memory")
; #define PG8_WAIT_L(n) asm volatile("s_waitcnt lgkmcnt(" #n ")" ::: "memory")
; #define PG8_BAR __builtin_amdgcn_s_barrier()
; #define PG8_SCHED __builtin_amdgcn_sched_barrier(0)
; template <class Epi, class Sched, bool ALIGN_EPI = false, bool SP2 = false>
; __device__ __forceinline__ void gemm_phase(PG8_LAS unsigned char* lds, const Gemm g, const Sched& S, const Epi& E) {
;     ...
;             const char* a1 = cA + (long)(t + 1) * kstepA;
;             const char* a2 = last ? nA : cA + (long)(t + 2) * kstepA; const char* b2 = last ? nB : cB + (long)(t + 2) * kstep;
;             const char* a3 = a2 + kstepA; const char* b3 = b2 + kstep;
;             if (last && has_next) S.a_ready(nxt);
;             if constexpr (SP2) {
;             PG8_LDB(B0, 0, 0); PG8_LDB(B1, 0, 1); PG8_SCHED; PG8_LDA(At, 0, 0); PG8_STAGE(PG8_SA(1, 1), a1 + hstepA, voffA);
;             PG8_WAIT_V(8); PG8_WAIT_L(0); PG8_BAR; PG8_MMA(0, 0, At, B0); PG8_MMA(0, 1, At, B1); PG8_BAR; PG8_SCHED;
;             PG8_LDA(At, 0, 1); PG8_STAGE(PG8_SB(0, 0), b2, voffB); PG8_STAGE(PG8_SB(0, 1), b2 + hstepB, voffB); PG8_STAGE(PG8_SA(0, 0), a2, voffA);
.LBB0_2190:
	ds_read_b128 v[112:115], v195
	ds_read_b128 v[116:119], v195 offset:1024
	ds_read_b128 v[120:123], v195 offset:2048
	ds_read_b128 v[124:127], v195 offset:3072
	ds_read_b128 v[128:131], v199
	ds_read_b128 v[132:135], v199 offset:1024
	ds_read_b128 v[136:139], v199 offset:2048
	ds_read_b128 v[140:143], v199 offset:3072
	s_add_i32 s67, s36, 2
	s_add_u32 s37, s12, 0xfffc0080
	s_addc_u32 s56, s13, -1
	s_cmp_eq_u32 s63, s36
	s_cselect_b32 s36, s21, s49
	s_cselect_b32 s57, s18, s56
	s_cselect_b32 s56, s19, s37
	s_cselect_b32 s37, s20, s51
	v_lshl_add_u64 v[180:181], s[12:13], 0, v[172:173]
	s_add_i32 m0, s15, 0xc000
	ds_read_b128 v[160:163], v203
	ds_read_b128 v[204:207], v203 offset:1024
	ds_read_b128 v[208:211], v203 offset:2048
	ds_read_b128 v[212:215], v203 offset:3072
	ds_read_b128 v[216:219], v203 offset:4096
	ds_read_b128 v[220:223], v203 offset:5120
	ds_read_b128 v[224:227], v203 offset:6144
	ds_read_b128 v[228:231], v203 offset:7168
	global_load_lds_dwordx4 v[180:181], off
	v_lshl_add_u64 v[180:181], s[12:13], 0, v[174:175]
	s_add_i32 m0, s15, 0xe000
	s_nop 0
	global_load_lds_dwordx4 v[180:181], off
	s_waitcnt vmcnt(8)
	s_waitcnt lgkmcnt(0)
	s_barrier
	s_setprio 1
	v_mfma_f32_16x16x32_bf16 v[156:159], v[112:115], v[160:163], v[156:159]
	v_mfma_f32_16x16x32_bf16 v[152:155], v[120:123], v[160:163], v[152:155]
	v_mfma_f32_16x16x32_bf16 v[148:151], v[112:115], v[208:211], v[148:151]
	v_mfma_f32_16x16x32_bf16 v[144:147], v[120:123], v[208:211], v[144:147]
	v_mfma_f32_16x16x32_bf16 v[108:111], v[112:115], v[216:219], v[108:111]
	v_mfma_f32_16x16x32_bf16 v[104:107], v[120:123], v[216:219], v[104:107]
	v_mfma_f32_16x16x32_bf16 v[100:103], v[112:115], v[224:227], v[100:103]
	v_mfma_f32_16x16x32_bf16 v[96:99], v[120:123], v[224:227], v[96:99]
	v_mfma_f32_16x16x32_bf16 v[156:159], v[116:119], v[204:207], v[156:159]
	v_mfma_f32_16x16x32_bf16 v[152:155], v[124:127], v[204:207], v[152:155]
	v_mfma_f32_16x16x32_bf16 v[148:151], v[116:119], v[212:215], v[148:151]
	v_mfma_f32_16x16x32_bf16 v[144:147], v[124:127], v[212:215], v[144:147]
	v_mfma_f32_16x16x32_bf16 v[108:111], v[116:119], v[220:223], v[108:111]
	v_mfma_f32_16x16x32_bf16 v[104:107], v[124:127], v[220:223], v[104:107]
	v_mfma_f32_16x16x32_bf16 v[100:103], v[116:119], v[228:231], v[100:103]
	v_mfma_f32_16x16x32_bf16 v[96:99], v[124:127], v[228:231], v[96:99]
	v_mfma_f32_16x16x32_bf16 v[60:63], v[128:131], v[160:163], v[60:63]
	v_mfma_f32_16x16x32_bf16 v[56:59], v[136:139], v[160:163], v[56:59]
	v_mfma_f32_16x16x32_bf16 v[52:55], v[128:131], v[208:211], v[52:55]
	v_mfma_f32_16x16x32_bf16 v[48:51], v[136:139], v[208:211], v[48:51]
	v_mfma_f32_16x16x32_bf16 v[44:47], v[128:131], v[216:219], v[44:47]
	v_mfma_f32_16x16x32_bf16 v[40:43], v[136:139], v[216:219], v[40:43]
	v_mfma_f32_16x16x32_bf16 v[36:39], v[128:131], v[224:227], v[36:39]
	v_mfma_f32_16x16x32_bf16 v[32:35], v[136:139], v[224:227], v[32:35]
	v_mfma_f32_16x16x32_bf16 v[60:63], v[132:135], v[204:207], v[60:63]
	v_mfma_f32_16x16x32_bf16 v[56:59], v[140:143], v[204:207], v[56:59]
	v_mfma_f32_16x16x32_bf16 v[52:55], v[132:135], v[212:215], v[52:55]
	v_mfma_f32_16x16x32_bf16 v[48:51], v[140:143], v[212:215], v[48:51]
	v_mfma_f32_16x16x32_bf16 v[44:47], v[132:135], v[220:223], v[44:47]
	v_mfma_f32_16x16x32_bf16 v[40:43], v[140:143], v[220:223], v[40:43]
	v_mfma_f32_16x16x32_bf16 v[36:39], v[132:135], v[228:231], v[36:39]
	v_mfma_f32_16x16x32_bf16 v[32:35], v[140:143], v[228:231], v[32:35]
	s_setprio 0
	s_barrier
	s_add_i32 s68, s65, s14
	v_lshl_add_u64 v[180:181], s[36:37], 0, v[166:167]
	s_mov_b32 m0, s68
	ds_read_b128 v[160:163], v203 offset:16384
	ds_read_b128 v[204:207], v203 offset:17408
	ds_read_b128 v[208:211], v203 offset:18432
	ds_read_b128 v[212:215], v203 offset:19456
	ds_read_b128 v[216:219], v203 offset:20480
	ds_read_b128 v[220:223], v203 offset:21504
	ds_read_b128 v[224:227], v203 offset:22528
	ds_read_b128 v[228:231], v203 offset:23552
	global_load_lds_dwordx4 v[180:181], off
	s_add_i32 m0, s68, 0x2000
	s_add_u32 s68, s36, 0x40000
	v_lshl_add_u64 v[184:185], s[36:37], 0, v[170:171]
	s_addc_u32 s69, s37, 0
	s_add_i32 s70, s66, s14
	global_load_lds_dwordx4 v[184:185], off
	v_lshl_add_u64 v[188:189], s[68:69], 0, v[166:167]
	s_mov_b32 m0, s70
	v_lshl_add_u64 v[192:193], s[56:57], 0, v[168:169]
	global_load_lds_dwordx4 v[188:189], off
	v_lshl_add_u64 v[188:189], s[68:69], 0, v[170:171]
	s_add_i32 m0, s70, 0x2000
	s_nop 0
	global_load_lds_dwordx4 v[188:189], off
	v_lshl_add_u64 v[188:189], s[56:57], 0, v[164:165]
	s_mov_b32 m0, s15
	s_nop 0
	global_load_lds_dwordx4 v[188:189], off
	s_mov_b32 m0, s16
	s_nop 0
	global_load_lds_dwordx4 v[192:193], off
	s_waitcnt vmcnt(8)
	s_waitcnt lgkmcnt(0)
	s_barrier
; #define PG8_STAGE(bufoff, gbase, voff) do { _Pragma("unroll") for (int _i = 0; _i < 2; ++_i) \
;         __builtin_amdgcn_global_load_lds((const unsigned*)((const char*)(gbase) + (voff)[_i]), (PG8_LAS unsigned*)(lds + (bufoff) + ldsw + _i * 8192), 16, 0, 0); } while (0)
; #define PG8_LDA(dst, b, h) do { _Pragma("unroll") for (int m = 0; m < 4; ++m) _Pragma("unroll") for (int k = 0; k < 2; ++k) dst[m][k] = *(const PG8_LAS bf16x8*)(lds + PG8_SA(b, h) + aoff + m * 2048 + k * 1024); } while (0)
; #define PG8_LDB(dst, b, h) do { _Pragma("unroll") for (int n = 0; n < 2; ++n) _Pragma("unroll") for (int k = 0; k < 2; ++k) dst[n][k] = *(const PG8_LAS bf16x8*)(lds + PG8_SB(b, h) + boff + n * 2048 + k * 1024); } while (0)
; #define PG8_MMA(ai, bj, At, Bt) do { __builtin_amdgcn_s_setprio(1); _Pragma("unroll") for (int m = 0; m < 4; ++m) _Pragma("unroll") for (int n = 0; n < 2; ++n) _Pragma("unroll") for (int k = 0; k < 2; ++k) \
;         acc[ai][bj][m][n] = __builtin_amdgcn_mfma_f32_16x16x32_bf16(Bt[n][k], At[m][k], acc[ai][bj][m][n], 0, 0, 0); __builtin_amdgcn_s_setprio(0); } while (0)
; #define PG8_WAIT_V(n) asm volatile("s_waitcnt vmcnt(" #n ")" ::: "memory")
; #define PG8_WAIT_L(n) asm volatile("s_waitcnt lgkmcnt(" #n ")" ::: "memory")
; #define PG8_BAR __builtin_amdgcn_s_barrier()
; #define PG8_SCHED __builtin_amdgcn_sched_barrier(0)
; template <class Epi, class Sched, bool ALIGN_EPI = false, bool SP2 = false>
; __device__ __forceinline__ void gemm_phase(PG8_LAS unsigned char* lds, const Gemm g, const Sched& S, const Epi& E) {
;     ...
;             PG8_WAIT_V(8); PG8_WAIT_L(0); PG8_BAR; PG8_MMA(1, 0, At, B0); PG8_MMA(1, 1, At, B1); PG8_BAR; PG8_SCHED;
;             PG8_LDB(B0, 1, 0); PG8_LDB(B1, 1, 1); PG8_SCHED; PG8_LDA(At, 1, 0); PG8_STAGE(PG8_SA(0, 1), a2 + hstepA, voffA);
;             PG8_WAIT_V(8); PG8_WAIT_L(0); PG8_BAR; PG8_MMA(0, 0, At, B0); PG8_MMA(0, 1, At, B1); PG8_BAR; PG8_SCHED;
	s_setprio 1
	v_mfma_f32_16x16x32_bf16 v[92:95], v[112:115], v[160:163], v[92:95]
	v_mfma_f32_16x16x32_bf16 v[88:91], v[120:123], v[160:163], v[88:91]
	v_mfma_f32_16x16x32_bf16 v[84:87], v[112:115], v[208:211], v[84:87]
	v_mfma_f32_16x16x32_bf16 v[80:83], v[120:123], v[208:211], v[80:83]
	v_mfma_f32_16x16x32_bf16 v[76:79], v[112:115], v[216:219], v[76:79]
	v_mfma_f32_16x16x32_bf16 v[72:75], v[120:123], v[216:219], v[72:75]
	v_mfma_f32_16x16x32_bf16 v[68:71], v[112:115], v[224:227], v[68:71]
	v_mfma_f32_16x16x32_bf16 v[64:67], v[120:123], v[224:227], v[64:67]
	v_mfma_f32_16x16x32_bf16 v[92:95], v[116:119], v[204:207], v[92:95]
	v_mfma_f32_16x16x32_bf16 v[88:91], v[124:127], v[204:207], v[88:91]
	v_mfma_f32_16x16x32_bf16 v[84:87], v[116:119], v[212:215], v[84:87]
	v_mfma_f32_16x16x32_bf16 v[80:83], v[124:127], v[212:215], v[80:83]
	v_mfma_f32_16x16x32_bf16 v[76:79], v[116:119], v[220:223], v[76:79]
	v_mfma_f32_16x16x32_bf16 v[72:75], v[124:127], v[220:223], v[72:75]
	v_mfma_f32_16x16x32_bf16 v[68:71], v[116:119], v[228:231], v[68:71]
	v_mfma_f32_16x16x32_bf16 v[64:67], v[124:127], v[228:231], v[64:67]
	v_mfma_f32_16x16x32_bf16 v[28:31], v[128:131], v[160:163], v[28:31]
	v_mfma_f32_16x16x32_bf16 v[24:27], v[136:139], v[160:163], v[24:27]
	v_mfma_f32_16x16x32_bf16 v[20:23], v[128:131], v[208:211], v[20:23]
	v_mfma_f32_16x16x32_bf16 v[16:19], v[136:139], v[208:211], v[16:19]
	v_mfma_f32_16x16x32_bf16 v[12:15], v[128:131], v[216:219], v[12:15]
	v_mfma_f32_16x16x32_bf16 v[8:11], v[136:139], v[216:219], v[8:11]
	v_mfma_f32_16x16x32_bf16 v[4:7], v[128:131], v[224:227], v[4:7]
	v_mfma_f32_16x16x32_bf16 v[0:3], v[136:139], v[224:227], v[0:3]
	v_mfma_f32_16x16x32_bf16 v[28:31], v[132:135], v[204:207], v[28:31]
	v_mfma_f32_16x16x32_bf16 v[24:27], v[140:143], v[204:207], v[24:27]
	v_mfma_f32_16x16x32_bf16 v[20:23], v[132:135], v[212:215], v[20:23]
	v_mfma_f32_16x16x32_bf16 v[16:19], v[140:143], v[212:215], v[16:19]
	v_mfma_f32_16x16x32_bf16 v[12:15], v[132:135], v[220:223], v[12:15]
	v_mfma_f32_16x16x32_bf16 v[8:11], v[140:143], v[220:223], v[8:11]
	v_mfma_f32_16x16x32_bf16 v[4:7], v[132:135], v[228:231], v[4:7]
	v_mfma_f32_16x16x32_bf16 v[0:3], v[140:143], v[228:231], v[0:3]
	s_setprio 0
	s_barrier
	s_add_i32 s68, 0, 0x18000
	s_add_i32 s69, 0, 0x1c000
	v_add_u32_e32 v124, s68, v191
	v_add_u32_e32 v140, s69, v191
	ds_read_b128 v[112:115], v124
	ds_read_b128 v[116:119], v124 offset:1024
	ds_read_b128 v[120:123], v124 offset:2048
	ds_read_b128 v[124:127], v124 offset:3072
	ds_read_b128 v[128:131], v140
	ds_read_b128 v[132:135], v140 offset:1024
	ds_read_b128 v[136:139], v140 offset:2048
	ds_read_b128 v[140:143], v140 offset:3072
	s_add_u32 s56, s56, 0x40000
	s_addc_u32 s57, s57, 0
	s_mov_b32 m0, s17
	v_lshl_add_u64 v[196:197], s[56:57], 0, v[164:165]
	ds_read_b128 v[160:163], v203 offset:32768
	ds_read_b128 v[204:207], v203 offset:33792
	ds_read_b128 v[208:211], v203 offset:34816
	ds_read_b128 v[212:215], v203 offset:35840
	ds_read_b128 v[216:219], v203 offset:36864
	ds_read_b128 v[220:223], v203 offset:37888
	ds_read_b128 v[224:227], v203 offset:38912
	ds_read_b128 v[228:231], v203 offset:39936
	global_load_lds_dwordx4 v[196:197], off
	v_lshl_add_u64 v[196:197], s[56:57], 0, v[168:169]
	s_mov_b32 m0, s33
	s_nop 0
	global_load_lds_dwordx4 v[196:197], off
	s_waitcnt vmcnt(8)
	s_waitcnt lgkmcnt(0)
	s_barrier
	s_setprio 1
	v_mfma_f32_16x16x32_bf16 v[156:159], v[112:115], v[160:163], v[156:159]
	v_mfma_f32_16x16x32_bf16 v[152:155], v[120:123], v[160:163], v[152:155]
	v_mfma_f32_16x16x32_bf16 v[148:151], v[112:115], v[208:211], v[148:151]
	v_mfma_f32_16x16x32_bf16 v[144:147], v[120:123], v[208:211], v[144:147]
	v_mfma_f32_16x16x32_bf16 v[108:111], v[112:115], v[216:219], v[108:111]
	v_mfma_f32_16x16x32_bf16 v[104:107], v[120:123], v[216:219], v[104:107]
	v_mfma_f32_16x16x32_bf16 v[100:103], v[112:115], v[224:227], v[100:103]
	v_mfma_f32_16x16x32_bf16 v[96:99], v[120:123], v[224:227], v[96:99]
	v_mfma_f32_16x16x32_bf16 v[156:159], v[116:119], v[204:207], v[156:159]
	v_mfma_f32_16x16x32_bf16 v[152:155], v[124:127], v[204:207], v[152:155]
	v_mfma_f32_16x16x32_bf16 v[148:151], v[116:119], v[212:215], v[148:151]
	v_mfma_f32_16x16x32_bf16 v[144:147], v[124:127], v[212:215], v[144:147]
	v_mfma_f32_16x16x32_bf16 v[108:111], v[116:119], v[220:223], v[108:111]
	v_mfma_f32_16x16x32_bf16 v[104:107], v[124:127], v[220:223], v[104:107]
	v_mfma_f32_16x16x32_bf16 v[100:103], v[116:119], v[228:231], v[100:103]
	v_mfma_f32_16x16x32_bf16 v[96:99], v[124:127], v[228:231], v[96:99]
	v_mfma_f32_16x16x32_bf16 v[60:63], v[128:131], v[160:163], v[60:63]
	v_mfma_f32_16x16x32_bf16 v[56:59], v[136:139], v[160:163], v[56:59]
	v_mfma_f32_16x16x32_bf16 v[52:55], v[128:131], v[208:211], v[52:55]
	v_mfma_f32_16x16x32_bf16 v[48:51], v[136:139], v[208:211], v[48:51]
	v_mfma_f32_16x16x32_bf16 v[44:47], v[128:131], v[216:219], v[44:47]
	v_mfma_f32_16x16x32_bf16 v[40:43], v[136:139], v[216:219], v[40:43]
	v_mfma_f32_16x16x32_bf16 v[36:39], v[128:131], v[224:227], v[36:39]
	v_mfma_f32_16x16x32_bf16 v[32:35], v[136:139], v[224:227], v[32:35]
	v_mfma_f32_16x16x32_bf16 v[60:63], v[132:135], v[204:207], v[60:63]
	v_mfma_f32_16x16x32_bf16 v[56:59], v[140:143], v[204:207], v[56:59]
	v_mfma_f32_16x16x32_bf16 v[52:55], v[132:135], v[212:215], v[52:55]
	v_mfma_f32_16x16x32_bf16 v[48:51], v[140:143], v[212:215], v[48:51]
	v_mfma_f32_16x16x32_bf16 v[44:47], v[132:135], v[220:223], v[44:47]
	v_mfma_f32_16x16x32_bf16 v[40:43], v[140:143], v[220:223], v[40:43]
	v_mfma_f32_16x16x32_bf16 v[36:39], v[132:135], v[228:231], v[36:39]
	v_mfma_f32_16x16x32_bf16 v[32:35], v[140:143], v[228:231], v[32:35]
	s_setprio 0
	s_barrier
; #define PG8_STAGE(bufoff, gbase, voff) do { _Pragma("unroll") for (int _i = 0; _i < 2; ++_i) \
;         __builtin_amdgcn_global_load_lds((const unsigned*)((const char*)(gbase) + (voff)[_i]), (PG8_LAS unsigned*)(lds + (bufoff) + ldsw + _i * 8192), 16, 0, 0); } while (0)
; #define PG8_LDA(dst, b, h) do { _Pragma("unroll") for (int m = 0; m < 4; ++m) _Pragma("unroll") for (int k = 0; k < 2; ++k) dst[m][k] = *(const PG8_LAS bf16x8*)(lds + PG8_SA(b, h) + aoff + m * 2048 + k * 1024); } while (0)
; #define PG8_MMA(ai, bj, At, Bt) do { __builtin_amdgcn_s_setprio(1); _Pragma("unroll") for (int m = 0; m < 4; ++m) _Pragma("unroll") for (int n = 0; n < 2; ++n) _Pragma("unroll") for (int k = 0; k < 2; ++k) \
;         acc[ai][bj][m][n] = __builtin_amdgcn_mfma_f32_16x16x32_bf16(Bt[n][k], At[m][k], acc[ai][bj][m][n], 0, 0, 0); __builtin_amdgcn_s_setprio(0); } while (0)
; #define PG8_WAIT_V(n) asm volatile("s_waitcnt vmcnt(" #n ")" ::: "memory")
; #define PG8_WAIT_L(n) asm volatile("s_waitcnt lgkmcnt(" #n ")" ::: "memory")
; #define PG8_BAR __builtin_amdgcn_s_barrier()
; #define PG8_SCHED __builtin_amdgcn_sched_barrier(0)
; template <class Epi, class Sched, bool ALIGN_EPI = false, bool SP2 = false>
; __device__ __forceinline__ void gemm_phase(PG8_LAS unsigned char* lds, const Gemm g, const Sched& S, const Epi& E) {
;     ...
;         for (int t = 0; t < nt; t += 2) {
;             const bool last = (t == nt - 2);
;             const char* a1 = cA + (long)(t + 1) * kstepA;
;             const char* a2 = last ? nA : cA + (long)(t + 2) * kstepA; const char* b2 = last ? nB : cB + (long)(t + 2) * kstep;
;     ...
;             PG8_LDA(At, 1, 1); PG8_STAGE(PG8_SB(1, 0), b3, voffB); PG8_STAGE(PG8_SB(1, 1), b3 + hstepB, voffB); PG8_STAGE(PG8_SA(1, 0), a3, voffA);
;             PG8_WAIT_V(8); PG8_WAIT_L(0); PG8_BAR; PG8_MMA(1, 0, At, B0); PG8_MMA(1, 1, At, B1); PG8_BAR; PG8_SCHED;
	s_add_i32 s56, s68, s14
	v_lshl_add_u64 v[180:181], v[180:181], 0, s[40:41]
	s_mov_b32 m0, s56
	ds_read_b128 v[160:163], v203 offset:49152
	ds_read_b128 v[204:207], v203 offset:50176
	ds_read_b128 v[208:211], v203 offset:51200
	ds_read_b128 v[212:215], v203 offset:52224
	ds_read_b128 v[216:219], v203 offset:53248
	ds_read_b128 v[220:223], v203 offset:54272
	ds_read_b128 v[224:227], v203 offset:55296
	ds_read_b128 v[228:231], v203 offset:56320
	global_load_lds_dwordx4 v[180:181], off
	s_add_i32 m0, s56, 0x2000
	s_add_u32 s36, s36, 0x40080
	v_lshl_add_u64 v[180:181], v[184:185], 0, s[40:41]
	s_addc_u32 s37, s37, 0
	s_add_i32 s56, s69, s14
	global_load_lds_dwordx4 v[180:181], off
	v_lshl_add_u64 v[180:181], s[36:37], 0, v[166:167]
	s_mov_b32 m0, s56
	s_nop 0
	global_load_lds_dwordx4 v[180:181], off
	v_lshl_add_u64 v[180:181], s[36:37], 0, v[170:171]
	s_add_i32 m0, s56, 0x2000
	s_nop 0
	global_load_lds_dwordx4 v[180:181], off
	v_lshl_add_u64 v[180:181], v[188:189], 0, s[40:41]
	s_mov_b32 m0, s61
	s_nop 0
	global_load_lds_dwordx4 v[180:181], off
	v_lshl_add_u64 v[180:181], v[192:193], 0, s[40:41]
	s_mov_b32 m0, s62
	s_nop 0
	global_load_lds_dwordx4 v[180:181], off
	s_waitcnt vmcnt(8)
	s_waitcnt lgkmcnt(0)
	s_barrier
	s_setprio 1
	v_mfma_f32_16x16x32_bf16 v[92:95], v[112:115], v[160:163], v[92:95]
	v_mfma_f32_16x16x32_bf16 v[88:91], v[120:123], v[160:163], v[88:91]
	v_mfma_f32_16x16x32_bf16 v[84:87], v[112:115], v[208:211], v[84:87]
	v_mfma_f32_16x16x32_bf16 v[80:83], v[120:123], v[208:211], v[80:83]
	v_mfma_f32_16x16x32_bf16 v[76:79], v[112:115], v[216:219], v[76:79]
	v_mfma_f32_16x16x32_bf16 v[72:75], v[120:123], v[216:219], v[72:75]
	v_mfma_f32_16x16x32_bf16 v[68:71], v[112:115], v[224:227], v[68:71]
	v_mfma_f32_16x16x32_bf16 v[64:67], v[120:123], v[224:227], v[64:67]
	v_mfma_f32_16x16x32_bf16 v[92:95], v[116:119], v[204:207], v[92:95]
	v_mfma_f32_16x16x32_bf16 v[88:91], v[124:127], v[204:207], v[88:91]
	v_mfma_f32_16x16x32_bf16 v[84:87], v[116:119], v[212:215], v[84:87]
	v_mfma_f32_16x16x32_bf16 v[80:83], v[124:127], v[212:215], v[80:83]
	v_mfma_f32_16x16x32_bf16 v[76:79], v[116:119], v[220:223], v[76:79]
	v_mfma_f32_16x16x32_bf16 v[72:75], v[124:127], v[220:223], v[72:75]
	v_mfma_f32_16x16x32_bf16 v[68:71], v[116:119], v[228:231], v[68:71]
	v_mfma_f32_16x16x32_bf16 v[64:67], v[124:127], v[228:231], v[64:67]
	v_mfma_f32_16x16x32_bf16 v[28:31], v[128:131], v[160:163], v[28:31]
	v_mfma_f32_16x16x32_bf16 v[24:27], v[136:139], v[160:163], v[24:27]
	v_mfma_f32_16x16x32_bf16 v[20:23], v[128:131], v[208:211], v[20:23]
	v_mfma_f32_16x16x32_bf16 v[16:19], v[136:139], v[208:211], v[16:19]
	v_mfma_f32_16x16x32_bf16 v[12:15], v[128:131], v[216:219], v[12:15]
	v_mfma_f32_16x16x32_bf16 v[8:11], v[136:139], v[216:219], v[8:11]
	v_mfma_f32_16x16x32_bf16 v[4:7], v[128:131], v[224:227], v[4:7]
	v_mfma_f32_16x16x32_bf16 v[0:3], v[136:139], v[224:227], v[0:3]
	v_mfma_f32_16x16x32_bf16 v[28:31], v[132:135], v[204:207], v[28:31]
	v_mfma_f32_16x16x32_bf16 v[24:27], v[140:143], v[204:207], v[24:27]
	v_mfma_f32_16x16x32_bf16 v[20:23], v[132:135], v[212:215], v[20:23]
	v_mfma_f32_16x16x32_bf16 v[16:19], v[140:143], v[212:215], v[16:19]
	v_mfma_f32_16x16x32_bf16 v[12:15], v[132:135], v[220:223], v[12:15]
	v_mfma_f32_16x16x32_bf16 v[8:11], v[140:143], v[220:223], v[8:11]
	v_mfma_f32_16x16x32_bf16 v[4:7], v[132:135], v[228:231], v[4:7]
	v_mfma_f32_16x16x32_bf16 v[0:3], v[140:143], v[228:231], v[0:3]
	s_setprio 0
	s_barrier
	s_add_u32 s12, s12, 0x100
	s_addc_u32 s13, s13, 0
	s_add_u32 s49, s49, 0x100
	s_addc_u32 s51, s51, 0
	s_cmp_ge_i32 s67, s58
	s_mov_b32 s36, s67
	s_cbranch_scc0 .LBB0_2190
